# best + EpiRes second-batch prefetch + EpiUp dead zero-inits before full-mask row_ror DPP replaced by s_nop
# baseline (speedup 1.0000x reference)
.LBB0_980:
	s_or_b64 exec, exec, s[4:5]
	v_mad_i64_i32 v[228:229], s[4:5], v136, s70, 0
	v_mad_i64_i32 v[226:227], s[4:5], v138, s70, 0
	s_waitcnt lgkmcnt(2)
	v_pk_add_f32 v[136:137], v[146:147], v[148:149]
	v_mov_b64_e32 v[138:139], s[62:63]
	v_pk_fma_f32 v[136:137], v[136:137], s[60:61], v[138:139] op_sel_hi:[1,0,0]
	v_mad_i64_i32 v[224:225], s[4:5], v140, s70, 0
	v_mul_f32_e32 v140, 0x4b800000, v137
	v_cmp_gt_f32_e64 s[6:7], s77, v137
	v_mad_i64_i32 v[230:231], s[4:5], v204, s70, 0
	s_nop 0
	v_cndmask_b32_e64 v137, v137, v140, s[6:7]
	v_rsq_f32_e32 v137, v137
	v_cmp_gt_f32_e64 s[4:5], s77, v136
	s_nop 0
	s_nop 0
	v_mul_f32_e32 v140, 0x45800000, v137
	v_cndmask_b32_e64 v218, v137, v140, s[6:7]
	v_mul_f32_e32 v137, 0x4b800000, v136
	v_cndmask_b32_e64 v136, v136, v137, s[4:5]
	v_rsq_f32_e32 v136, v136
	s_waitcnt vmcnt(0)
	v_mov_b32_dpp v217, v176 row_ror:2 row_mask:0xf bank_mask:0xf
	v_mov_b32_dpp v215, v176 row_ror:1 row_mask:0xf bank_mask:0xf
	s_nop 0
	v_mul_f32_e32 v137, 0x45800000, v136
	v_cndmask_b32_e64 v216, v136, v137, s[4:5]
	s_waitcnt lgkmcnt(0)
	v_pk_add_f32 v[136:137], v[142:143], v[144:145]
	v_mov_b32_dpp v217, v172 row_shr:2 row_mask:0xf bank_mask:0xf
	v_pk_fma_f32 v[136:137], v[136:137], s[60:61], v[138:139] op_sel_hi:[1,0,0]
	v_mov_b32_dpp v215, v172 row_shr:1 row_mask:0xf bank_mask:0xf
	v_mul_f32_e32 v138, 0x4b800000, v137
	v_cmp_gt_f32_e64 s[6:7], s77, v137
	v_cmp_gt_f32_e64 s[4:5], s77, v136
	s_nop 0
	v_cndmask_b32_e64 v137, v137, v138, s[6:7]
	v_rsq_f32_e32 v137, v137
	v_lshlrev_b32_e32 v232, 16, v217
	v_and_b32_e32 v233, 0xffff0000, v217
	v_mov_b32_dpp v219, v177 row_ror:1 row_mask:0xf bank_mask:0xf
	v_mul_f32_e32 v138, 0x45800000, v137
	v_cndmask_b32_e64 v214, v137, v138, s[6:7]
	v_mul_f32_e32 v137, 0x4b800000, v136
	v_cndmask_b32_e64 v136, v136, v137, s[4:5]
	v_rsq_f32_e32 v136, v136
	v_mov_b32_dpp v243, v177 row_ror:2 row_mask:0xf bank_mask:0xf
	v_lshlrev_b32_e32 v176, 16, v215
	v_and_b32_e32 v177, 0xffff0000, v215
	v_mul_f32_e32 v137, 0x45800000, v136
	v_cndmask_b32_e64 v212, v136, v137, s[4:5]
	v_lshlrev_b64 v[136:137], 2, v[198:199]
	v_lshl_add_u64 v[200:201], s[20:21], 0, v[136:137]
	v_lshl_add_u64 v[210:211], s[38:39], 0, v[136:137]
	v_lshl_add_u64 v[208:209], s[44:45], 0, v[136:137]
	v_lshl_add_u64 v[202:203], s[22:23], 0, v[136:137]
	global_load_dwordx4 v[136:139], v[200:201], off offset:16
	global_load_dwordx4 v[164:167], v[200:201], off
	global_load_dwordx4 v[140:143], v[210:211], off offset:16
	global_load_dwordx4 v[160:163], v[210:211], off
	global_load_dwordx4 v[144:147], v[208:209], off offset:16
	global_load_dwordx4 v[156:159], v[208:209], off
	global_load_dwordx4 v[148:151], v[202:203], off offset:16
	global_load_dwordx4 v[168:171], v[202:203], off
	v_lshlrev_b32_e32 v244, 16, v172
	v_and_b32_e32 v245, 0xffff0000, v172
	v_mov_b32_dpp v219, v173 row_shr:1 row_mask:0xf bank_mask:0xf
	v_mov_b32_dpp v243, v173 row_shr:2 row_mask:0xf bank_mask:0xf
	v_pk_mul_f32 v[132:133], v[132:133], v[218:219] op_sel_hi:[1,0]
	v_pk_mul_f32 v[134:135], v[134:135], v[218:219] op_sel_hi:[1,0]
	s_nop 0
	v_pk_mul_f32 v[124:125], v[124:125], v[218:219] op_sel_hi:[1,0]
	v_pk_mul_f32 v[126:127], v[126:127], v[218:219] op_sel_hi:[1,0]
	v_mov_b32_dpp v217, v179 row_ror:2 row_mask:0xf bank_mask:0xf
	v_pk_mul_f32 v[100:101], v[100:101], v[212:213] op_sel_hi:[1,0]
	v_pk_mul_f32 v[102:103], v[102:103], v[212:213] op_sel_hi:[1,0]
	v_mov_b32_dpp v217, v175 row_shr:2 row_mask:0xf bank_mask:0xf
	v_pk_mul_f32 v[116:117], v[116:117], v[216:217] op_sel_hi:[1,0]
	v_pk_mul_f32 v[118:119], v[118:119], v[216:217] op_sel_hi:[1,0]
	v_pk_mul_f32 v[112:113], v[112:113], v[216:217] op_sel_hi:[1,0]
	v_pk_mul_f32 v[114:115], v[114:115], v[216:217] op_sel_hi:[1,0]
	v_pk_mul_f32 v[96:97], v[96:97], v[212:213] op_sel_hi:[1,0]
	v_pk_mul_f32 v[98:99], v[98:99], v[212:213] op_sel_hi:[1,0]
	s_waitcnt vmcnt(0)
	v_pk_fma_f32 v[232:233], v[164:165], v[232:233], v[168:169]
	s_nop 0
	v_pk_fma_f32 v[176:177], v[160:161], v[176:177], v[232:233]
	s_nop 0
	v_pk_fma_f32 v[176:177], v[156:157], v[244:245], v[176:177]
	v_lshlrev_b32_e32 v244, 16, v173
	v_mul_f32_e32 v215, 0xbfb8aa3b, v176
	v_exp_f32_e32 v215, v215
	v_and_b32_e32 v245, 0xffff0000, v173
	v_add_f32_e32 v215, 1.0, v215
	v_rcp_f32_e32 v232, v215
	v_mul_f32_e32 v215, 0xbfb8aa3b, v177
	v_exp_f32_e32 v215, v215
	s_nop 0
	v_add_f32_e32 v215, 1.0, v215
	v_rcp_f32_e32 v233, v215
	s_nop 0
	v_pk_mul_f32 v[176:177], v[176:177], v[232:233]
	v_lshlrev_b32_e32 v232, 16, v243
	v_and_b32_e32 v233, 0xffff0000, v243
	v_pk_mul_f32 v[132:133], v[132:133], v[176:177]
	v_lshlrev_b32_e32 v176, 16, v219
	v_and_b32_e32 v177, 0xffff0000, v219
	v_pk_fma_f32 v[232:233], v[166:167], v[232:233], v[170:171]
	v_cvt_pk_bf16_f32 v132, v132, v133
	v_pk_fma_f32 v[176:177], v[162:163], v[176:177], v[232:233]
	s_nop 0
	v_pk_fma_f32 v[176:177], v[158:159], v[244:245], v[176:177]
	s_nop 0
	v_mul_f32_e32 v215, 0xbfb8aa3b, v176
	v_exp_f32_e32 v215, v215
	s_nop 0
	v_add_f32_e32 v215, 1.0, v215
	v_rcp_f32_e32 v232, v215
	v_mul_f32_e32 v215, 0xbfb8aa3b, v177
	v_exp_f32_e32 v215, v215
	s_nop 0
	v_add_f32_e32 v215, 1.0, v215
	v_rcp_f32_e32 v233, v215
	s_nop 0
	v_pk_mul_f32 v[176:177], v[176:177], v[232:233]
	s_nop 0
	v_pk_mul_f32 v[134:135], v[134:135], v[176:177]
	s_nop 0
	v_cvt_pk_bf16_f32 v133, v134, v135
	s_nop 0
	v_mov_b32_dpp v177, v178 row_ror:2 row_mask:0xf bank_mask:0xf
	v_mov_b32_dpp v215, v179 row_ror:1 row_mask:0xf bank_mask:0xf
	v_mov_b32_dpp v135, v178 row_ror:1 row_mask:0xf bank_mask:0xf
	v_mov_b32_dpp v177, v174 row_shr:2 row_mask:0xf bank_mask:0xf
	v_lshlrev_b32_e32 v176, 16, v177
	v_mov_b32_dpp v135, v174 row_shr:1 row_mask:0xf bank_mask:0xf
	v_and_b32_e32 v177, 0xffff0000, v177
	v_lshlrev_b32_e32 v134, 16, v135
	v_and_b32_e32 v135, 0xffff0000, v135
	v_pk_fma_f32 v[176:177], v[136:137], v[176:177], v[148:149]
	v_lshlrev_b32_e32 v178, 16, v174
	v_and_b32_e32 v179, 0xffff0000, v174
	v_pk_fma_f32 v[134:135], v[140:141], v[134:135], v[176:177]
	v_mov_b32_dpp v215, v175 row_shr:1 row_mask:0xf bank_mask:0xf
	v_pk_fma_f32 v[134:135], v[144:145], v[178:179], v[134:135]
	v_lshlrev_b32_e32 v178, 16, v175
	v_mul_f32_e32 v176, 0xbfb8aa3b, v134
	v_mul_f32_e32 v177, 0xbfb8aa3b, v135
	v_exp_f32_e32 v176, v176
	v_exp_f32_e32 v177, v177
	v_and_b32_e32 v179, 0xffff0000, v175
	v_pk_mul_f32 v[108:109], v[108:109], v[214:215] op_sel_hi:[1,0]
	v_add_f32_e32 v176, 1.0, v176
	v_add_f32_e32 v177, 1.0, v177
	v_rcp_f32_e32 v176, v176
	v_rcp_f32_e32 v177, v177
	v_pk_mul_f32 v[110:111], v[110:111], v[214:215] op_sel_hi:[1,0]
	v_pk_mul_f32 v[104:105], v[104:105], v[214:215] op_sel_hi:[1,0]
	v_pk_mul_f32 v[106:107], v[106:107], v[214:215] op_sel_hi:[1,0]
	v_pk_mul_f32 v[134:135], v[134:135], v[176:177]
	v_lshlrev_b32_e32 v176, 16, v217
	v_and_b32_e32 v177, 0xffff0000, v217
	v_pk_mul_f32 v[124:125], v[124:125], v[134:135]
	v_lshlrev_b32_e32 v134, 16, v215
	v_and_b32_e32 v135, 0xffff0000, v215
	v_pk_fma_f32 v[176:177], v[138:139], v[176:177], v[150:151]
	s_nop 0
	v_pk_fma_f32 v[134:135], v[142:143], v[134:135], v[176:177]
	s_nop 0
	v_pk_fma_f32 v[134:135], v[146:147], v[178:179], v[134:135]
	s_nop 0
	v_mul_f32_e32 v176, 0xbfb8aa3b, v134
	v_mul_f32_e32 v177, 0xbfb8aa3b, v135
	v_exp_f32_e32 v176, v176
	v_exp_f32_e32 v177, v177
	v_add_f32_e32 v176, 1.0, v176
	v_add_f32_e32 v177, 1.0, v177
	v_rcp_f32_e32 v176, v176
	v_rcp_f32_e32 v177, v177
	s_nop 0
	v_pk_mul_f32 v[134:135], v[134:135], v[176:177]
	s_nop 0
	v_pk_mul_f32 v[126:127], v[126:127], v[134:135]
	v_cvt_pk_bf16_f32 v134, v124, v125
	v_cvt_pk_bf16_f32 v135, v126, v127
	v_lshl_add_u64 v[124:125], s[14:15], 0, v[230:231]
	v_lshlrev_b64 v[176:177], 1, v[198:199]
	s_nop 0
	v_lshl_add_u64 v[178:179], v[124:125], 0, v[176:177]
	s_nop 0
	v_mov_b32_dpp v127, v172 row_ror:2 row_mask:0xf bank_mask:0xf
	global_store_dwordx4 v[178:179], v[132:135], off
	v_mov_b32_dpp v125, v172 row_ror:1 row_mask:0xf bank_mask:0xf
	v_mov_b32_dpp v127, v152 row_shr:2 row_mask:0xf bank_mask:0xf
	v_lshlrev_b32_e32 v126, 16, v127
	v_mov_b32_dpp v125, v152 row_shr:1 row_mask:0xf bank_mask:0xf
	v_and_b32_e32 v127, 0xffff0000, v127
	v_lshlrev_b32_e32 v124, 16, v125
	v_and_b32_e32 v125, 0xffff0000, v125
	v_pk_fma_f32 v[126:127], v[164:165], v[126:127], v[168:169]
	v_lshlrev_b32_e32 v132, 16, v152
	v_and_b32_e32 v133, 0xffff0000, v152
	v_pk_fma_f32 v[124:125], v[160:161], v[124:125], v[126:127]
	s_nop 0
	v_pk_fma_f32 v[124:125], v[156:157], v[132:133], v[124:125]
	s_nop 0
	v_mul_f32_e32 v126, 0xbfb8aa3b, v124
	v_mul_f32_e32 v127, 0xbfb8aa3b, v125
	v_exp_f32_e32 v126, v126
	v_exp_f32_e32 v127, v127
	v_mov_b32_dpp v135, v173 row_ror:2 row_mask:0xf bank_mask:0xf
	v_mov_b32_dpp v134, v173 row_ror:1 row_mask:0xf bank_mask:0xf
	v_add_f32_e32 v126, 1.0, v126
	v_add_f32_e32 v127, 1.0, v127
	v_rcp_f32_e32 v126, v126
	v_rcp_f32_e32 v127, v127
	v_mov_b32_dpp v135, v153 row_shr:2 row_mask:0xf bank_mask:0xf
	v_mov_b32_dpp v134, v153 row_shr:1 row_mask:0xf bank_mask:0xf
	v_lshlrev_b32_e32 v132, 16, v153
	v_pk_mul_f32 v[124:125], v[124:125], v[126:127]
	v_lshlrev_b32_e32 v126, 16, v135
	v_and_b32_e32 v127, 0xffff0000, v135
	v_pk_mul_f32 v[116:117], v[116:117], v[124:125]
	v_lshlrev_b32_e32 v124, 16, v134
	v_and_b32_e32 v125, 0xffff0000, v134
	v_pk_fma_f32 v[126:127], v[166:167], v[126:127], v[170:171]
	v_and_b32_e32 v133, 0xffff0000, v153
	v_pk_fma_f32 v[124:125], v[162:163], v[124:125], v[126:127]
	v_cvt_pk_bf16_f32 v116, v116, v117
	v_pk_fma_f32 v[124:125], v[158:159], v[132:133], v[124:125]
	s_nop 0
	v_mul_f32_e32 v126, 0xbfb8aa3b, v124
	v_mul_f32_e32 v127, 0xbfb8aa3b, v125
	v_exp_f32_e32 v126, v126
	v_exp_f32_e32 v127, v127
	s_nop 0
	v_mov_b32_dpp v133, v175 row_ror:2 row_mask:0xf bank_mask:0xf
	v_add_f32_e32 v126, 1.0, v126
	v_add_f32_e32 v127, 1.0, v127
	v_rcp_f32_e32 v126, v126
	v_rcp_f32_e32 v127, v127
	v_mov_b32_dpp v132, v175 row_ror:1 row_mask:0xf bank_mask:0xf
	v_mov_b32_dpp v133, v155 row_shr:2 row_mask:0xf bank_mask:0xf
	v_pk_mul_f32 v[124:125], v[124:125], v[126:127]
	s_nop 0
	v_pk_mul_f32 v[118:119], v[118:119], v[124:125]
	s_nop 0
	v_cvt_pk_bf16_f32 v117, v118, v119
	s_nop 0
	v_mov_b32_dpp v125, v174 row_ror:2 row_mask:0xf bank_mask:0xf
	v_lshlrev_b32_e32 v126, 16, v154
	v_mov_b32_dpp v119, v174 row_ror:1 row_mask:0xf bank_mask:0xf
	v_mov_b32_dpp v125, v154 row_shr:2 row_mask:0xf bank_mask:0xf
	v_lshlrev_b32_e32 v124, 16, v125
	v_mov_b32_dpp v119, v154 row_shr:1 row_mask:0xf bank_mask:0xf
	v_and_b32_e32 v125, 0xffff0000, v125
	v_lshlrev_b32_e32 v118, 16, v119
	v_and_b32_e32 v119, 0xffff0000, v119
	v_pk_fma_f32 v[124:125], v[136:137], v[124:125], v[148:149]
	v_and_b32_e32 v127, 0xffff0000, v154
	v_pk_fma_f32 v[118:119], v[140:141], v[118:119], v[124:125]
	v_mov_b32_dpp v132, v155 row_shr:1 row_mask:0xf bank_mask:0xf
	v_pk_fma_f32 v[118:119], v[144:145], v[126:127], v[118:119]
	v_lshlrev_b32_e32 v126, 16, v155
	v_mul_f32_e32 v124, 0xbfb8aa3b, v118
	v_mul_f32_e32 v125, 0xbfb8aa3b, v119
	v_exp_f32_e32 v124, v124
	v_exp_f32_e32 v125, v125
	v_and_b32_e32 v127, 0xffff0000, v155
	v_add_f32_e32 v124, 1.0, v124
	v_add_f32_e32 v125, 1.0, v125
	v_rcp_f32_e32 v124, v124
	v_rcp_f32_e32 v125, v125
	s_nop 0
	v_pk_mul_f32 v[118:119], v[118:119], v[124:125]
	v_lshlrev_b32_e32 v124, 16, v133
	v_and_b32_e32 v125, 0xffff0000, v133
	v_pk_mul_f32 v[112:113], v[112:113], v[118:119]
	v_lshlrev_b32_e32 v118, 16, v132
	v_and_b32_e32 v119, 0xffff0000, v132
	v_pk_fma_f32 v[124:125], v[138:139], v[124:125], v[150:151]
	s_nop 0
	v_pk_fma_f32 v[118:119], v[142:143], v[118:119], v[124:125]
	s_nop 0
	v_pk_fma_f32 v[118:119], v[146:147], v[126:127], v[118:119]
	s_nop 0
	v_mul_f32_e32 v124, 0xbfb8aa3b, v118
	v_mul_f32_e32 v125, 0xbfb8aa3b, v119
	v_exp_f32_e32 v124, v124
	v_exp_f32_e32 v125, v125
	v_add_f32_e32 v124, 1.0, v124
	v_add_f32_e32 v125, 1.0, v125
	v_rcp_f32_e32 v124, v124
	v_rcp_f32_e32 v125, v125
	s_nop 0
	v_pk_mul_f32 v[118:119], v[118:119], v[124:125]
	s_nop 0
	v_pk_mul_f32 v[114:115], v[114:115], v[118:119]
	v_cvt_pk_bf16_f32 v118, v112, v113
	v_cvt_pk_bf16_f32 v119, v114, v115
	v_lshl_add_u64 v[112:113], s[14:15], 0, v[228:229]
	s_nop 0
	v_lshl_add_u64 v[172:173], v[112:113], 0, v[176:177]
	s_nop 0
	v_mov_b32_dpp v115, v152 row_ror:2 row_mask:0xf bank_mask:0xf
	global_store_dwordx4 v[172:173], v[116:119], off
	v_mov_b32_dpp v113, v152 row_ror:1 row_mask:0xf bank_mask:0xf
	v_mov_b32_dpp v115, v128 row_shr:2 row_mask:0xf bank_mask:0xf
	v_lshlrev_b32_e32 v114, 16, v115
	v_mov_b32_dpp v113, v128 row_shr:1 row_mask:0xf bank_mask:0xf
	v_and_b32_e32 v115, 0xffff0000, v115
	v_lshlrev_b32_e32 v112, 16, v113
	v_and_b32_e32 v113, 0xffff0000, v113
	v_pk_fma_f32 v[114:115], v[164:165], v[114:115], v[168:169]
	v_lshlrev_b32_e32 v116, 16, v128
	v_and_b32_e32 v117, 0xffff0000, v128
	v_pk_fma_f32 v[112:113], v[160:161], v[112:113], v[114:115]
	s_nop 0
	v_pk_fma_f32 v[112:113], v[156:157], v[116:117], v[112:113]
	s_nop 0
	v_mul_f32_e32 v114, 0xbfb8aa3b, v112
	v_mul_f32_e32 v115, 0xbfb8aa3b, v113
	v_exp_f32_e32 v114, v114
	v_exp_f32_e32 v115, v115
	v_mov_b32_dpp v119, v153 row_ror:2 row_mask:0xf bank_mask:0xf
	v_mov_b32_dpp v118, v153 row_ror:1 row_mask:0xf bank_mask:0xf
	v_add_f32_e32 v114, 1.0, v114
	v_add_f32_e32 v115, 1.0, v115
	v_rcp_f32_e32 v114, v114
	v_rcp_f32_e32 v115, v115
	v_mov_b32_dpp v119, v129 row_shr:2 row_mask:0xf bank_mask:0xf
	v_mov_b32_dpp v118, v129 row_shr:1 row_mask:0xf bank_mask:0xf
	v_lshlrev_b32_e32 v116, 16, v129
	v_pk_mul_f32 v[112:113], v[112:113], v[114:115]
	v_lshlrev_b32_e32 v114, 16, v119
	v_and_b32_e32 v115, 0xffff0000, v119
	v_pk_mul_f32 v[108:109], v[108:109], v[112:113]
	v_lshlrev_b32_e32 v112, 16, v118
	v_and_b32_e32 v113, 0xffff0000, v118
	v_pk_fma_f32 v[114:115], v[166:167], v[114:115], v[170:171]
	v_and_b32_e32 v117, 0xffff0000, v129
	v_pk_fma_f32 v[112:113], v[162:163], v[112:113], v[114:115]
	v_cvt_pk_bf16_f32 v108, v108, v109
	v_pk_fma_f32 v[112:113], v[158:159], v[116:117], v[112:113]
	s_nop 0
	v_mul_f32_e32 v114, 0xbfb8aa3b, v112
	v_mul_f32_e32 v115, 0xbfb8aa3b, v113
	v_exp_f32_e32 v114, v114
	v_exp_f32_e32 v115, v115
	s_nop 0
	v_mov_b32_dpp v117, v155 row_ror:2 row_mask:0xf bank_mask:0xf
	v_add_f32_e32 v114, 1.0, v114
	v_add_f32_e32 v115, 1.0, v115
	v_rcp_f32_e32 v114, v114
	v_rcp_f32_e32 v115, v115
	v_mov_b32_dpp v116, v155 row_ror:1 row_mask:0xf bank_mask:0xf
	v_mov_b32_dpp v117, v131 row_shr:2 row_mask:0xf bank_mask:0xf
	v_pk_mul_f32 v[112:113], v[112:113], v[114:115]
	s_nop 0
	v_pk_mul_f32 v[110:111], v[110:111], v[112:113]
	s_nop 0
	v_cvt_pk_bf16_f32 v109, v110, v111
	s_nop 0
	v_mov_b32_dpp v113, v154 row_ror:2 row_mask:0xf bank_mask:0xf
	v_lshlrev_b32_e32 v114, 16, v130
	v_mov_b32_dpp v111, v154 row_ror:1 row_mask:0xf bank_mask:0xf
	v_mov_b32_dpp v113, v130 row_shr:2 row_mask:0xf bank_mask:0xf
	v_lshlrev_b32_e32 v112, 16, v113
	v_mov_b32_dpp v111, v130 row_shr:1 row_mask:0xf bank_mask:0xf
	v_and_b32_e32 v113, 0xffff0000, v113
	v_lshlrev_b32_e32 v110, 16, v111
	v_and_b32_e32 v111, 0xffff0000, v111
	v_pk_fma_f32 v[112:113], v[136:137], v[112:113], v[148:149]
	v_and_b32_e32 v115, 0xffff0000, v130
	v_pk_fma_f32 v[110:111], v[140:141], v[110:111], v[112:113]
	v_mov_b32_dpp v116, v131 row_shr:1 row_mask:0xf bank_mask:0xf
	v_pk_fma_f32 v[110:111], v[144:145], v[114:115], v[110:111]
	v_lshlrev_b32_e32 v114, 16, v131
	v_mul_f32_e32 v112, 0xbfb8aa3b, v110
	v_mul_f32_e32 v113, 0xbfb8aa3b, v111
	v_exp_f32_e32 v112, v112
	v_exp_f32_e32 v113, v113
	v_and_b32_e32 v115, 0xffff0000, v131
	v_add_f32_e32 v112, 1.0, v112
	v_add_f32_e32 v113, 1.0, v113
	v_rcp_f32_e32 v112, v112
	v_rcp_f32_e32 v113, v113
	s_nop 0
	v_pk_mul_f32 v[110:111], v[110:111], v[112:113]
	v_lshlrev_b32_e32 v112, 16, v117
	v_and_b32_e32 v113, 0xffff0000, v117
	v_pk_mul_f32 v[104:105], v[104:105], v[110:111]
	v_lshlrev_b32_e32 v110, 16, v116
	v_and_b32_e32 v111, 0xffff0000, v116
	v_pk_fma_f32 v[112:113], v[138:139], v[112:113], v[150:151]
	s_nop 0
	v_pk_fma_f32 v[110:111], v[142:143], v[110:111], v[112:113]
	s_nop 0
	v_pk_fma_f32 v[110:111], v[146:147], v[114:115], v[110:111]
	s_nop 0
	v_mul_f32_e32 v112, 0xbfb8aa3b, v110
	v_mul_f32_e32 v113, 0xbfb8aa3b, v111
	v_exp_f32_e32 v112, v112
	v_exp_f32_e32 v113, v113
	s_nop 0
	v_mov_b32_dpp v115, v130 row_ror:2 row_mask:0xf bank_mask:0xf
	v_add_f32_e32 v112, 1.0, v112
	v_add_f32_e32 v113, 1.0, v113
	v_rcp_f32_e32 v112, v112
	v_rcp_f32_e32 v113, v113
	v_mov_b32_dpp v114, v130 row_ror:1 row_mask:0xf bank_mask:0xf
	v_mov_b32_dpp v115, v122 row_shr:2 row_mask:0xf bank_mask:0xf
	v_mov_b32_dpp v117, v131 row_ror:2 row_mask:0xf bank_mask:0xf
	v_pk_mul_f32 v[110:111], v[110:111], v[112:113]
	s_nop 0
	v_pk_mul_f32 v[106:107], v[106:107], v[110:111]
	v_cvt_pk_bf16_f32 v110, v104, v105
	v_cvt_pk_bf16_f32 v111, v106, v107
	v_lshl_add_u64 v[104:105], s[14:15], 0, v[226:227]
	s_nop 0
	v_lshl_add_u64 v[154:155], v[104:105], 0, v[176:177]
	s_nop 0
	v_mov_b32_dpp v106, v128 row_ror:2 row_mask:0xf bank_mask:0xf
	global_store_dwordx4 v[154:155], v[108:111], off
	v_mov_b32_dpp v104, v128 row_ror:1 row_mask:0xf bank_mask:0xf
	v_mov_b32_dpp v106, v120 row_shr:2 row_mask:0xf bank_mask:0xf
	v_lshlrev_b32_e32 v108, 16, v106
	v_mov_b32_dpp v104, v120 row_shr:1 row_mask:0xf bank_mask:0xf
	v_and_b32_e32 v109, 0xffff0000, v106
	v_lshlrev_b32_e32 v110, 16, v104
	v_and_b32_e32 v111, 0xffff0000, v104
	v_pk_fma_f32 v[108:109], v[164:165], v[108:109], v[168:169]
	s_nop 0
	v_pk_fma_f32 v[108:109], v[160:161], v[110:111], v[108:109]
	v_lshlrev_b32_e32 v110, 16, v120
	v_and_b32_e32 v111, 0xffff0000, v120
	v_pk_fma_f32 v[108:109], v[156:157], v[110:111], v[108:109]
	v_mov_b32_dpp v113, v129 row_ror:2 row_mask:0xf bank_mask:0xf
	v_mul_f32_e32 v104, 0xbfb8aa3b, v108
	v_exp_f32_e32 v104, v104
	v_mov_b32_dpp v112, v129 row_ror:1 row_mask:0xf bank_mask:0xf
	v_mov_b32_dpp v113, v121 row_shr:2 row_mask:0xf bank_mask:0xf
	v_mov_b32_dpp v114, v122 row_shr:1 row_mask:0xf bank_mask:0xf
	v_add_f32_e32 v104, 1.0, v104
	v_rcp_f32_e32 v110, v104
	v_mul_f32_e32 v104, 0xbfb8aa3b, v109
	v_exp_f32_e32 v104, v104
	v_mov_b32_dpp v112, v121 row_shr:1 row_mask:0xf bank_mask:0xf
	v_mov_b32_dpp v116, v131 row_ror:1 row_mask:0xf bank_mask:0xf
	v_mov_b32_dpp v117, v123 row_shr:2 row_mask:0xf bank_mask:0xf
	v_add_f32_e32 v104, 1.0, v104
	v_rcp_f32_e32 v111, v104
	v_mov_b32_dpp v116, v123 row_shr:1 row_mask:0xf bank_mask:0xf
	v_and_b32_e32 v105, 0xffff0000, v117
	v_and_b32_e32 v107, 0xffff0000, v116
	v_pk_mul_f32 v[108:109], v[108:109], v[110:111]
	v_lshlrev_b32_e32 v110, 16, v112
	v_pk_mul_f32 v[100:101], v[100:101], v[108:109]
	v_lshlrev_b32_e32 v108, 16, v113
	v_and_b32_e32 v109, 0xffff0000, v113
	v_and_b32_e32 v111, 0xffff0000, v112
	v_pk_fma_f32 v[108:109], v[166:167], v[108:109], v[170:171]
	v_lshlrev_b32_e32 v106, 16, v116
	v_pk_fma_f32 v[108:109], v[162:163], v[110:111], v[108:109]
	v_lshlrev_b32_e32 v110, 16, v121
	v_and_b32_e32 v111, 0xffff0000, v121
	v_pk_fma_f32 v[108:109], v[158:159], v[110:111], v[108:109]
	v_or_b32_e32 v112, 0x80, v198
	v_mul_f32_e32 v104, 0xbfb8aa3b, v108
	v_exp_f32_e32 v104, v104
	v_ashrrev_i32_e32 v113, 31, v112
	v_add_f32_e32 v104, 1.0, v104
	v_rcp_f32_e32 v110, v104
	v_mul_f32_e32 v104, 0xbfb8aa3b, v109
	v_exp_f32_e32 v104, v104
	s_nop 0
	v_add_f32_e32 v104, 1.0, v104
	v_rcp_f32_e32 v111, v104
	s_nop 0
	v_pk_mul_f32 v[108:109], v[108:109], v[110:111]
	s_nop 0
	v_pk_mul_f32 v[102:103], v[102:103], v[108:109]
	v_lshlrev_b32_e32 v108, 16, v115
	v_and_b32_e32 v109, 0xffff0000, v115
	v_lshlrev_b32_e32 v110, 16, v114
	v_and_b32_e32 v111, 0xffff0000, v114
	v_pk_fma_f32 v[108:109], v[136:137], v[108:109], v[148:149]
	v_lshlrev_b64 v[148:149], 1, v[112:113]
	v_pk_fma_f32 v[108:109], v[140:141], v[110:111], v[108:109]
	v_lshlrev_b32_e32 v110, 16, v122
	v_and_b32_e32 v111, 0xffff0000, v122
	v_pk_fma_f32 v[108:109], v[144:145], v[110:111], v[108:109]
	s_nop 0
	v_mul_f32_e32 v104, 0xbfb8aa3b, v108
	v_exp_f32_e32 v104, v104
	s_nop 0
	v_add_f32_e32 v104, 1.0, v104
	v_rcp_f32_e32 v110, v104
	v_mul_f32_e32 v104, 0xbfb8aa3b, v109
	v_exp_f32_e32 v104, v104
	s_nop 0
	v_add_f32_e32 v104, 1.0, v104
	v_rcp_f32_e32 v111, v104
	v_lshlrev_b32_e32 v104, 16, v117
	v_pk_mul_f32 v[108:109], v[108:109], v[110:111]
	s_nop 0
	v_pk_mul_f32 v[108:109], v[96:97], v[108:109]
	v_cvt_pk_bf16_f32 v97, v102, v103
	v_pk_fma_f32 v[102:103], v[138:139], v[104:105], v[150:151]
	v_cvt_pk_bf16_f32 v96, v100, v101
	v_lshlrev_b32_e32 v100, 16, v123
	v_and_b32_e32 v101, 0xffff0000, v123
	v_pk_fma_f32 v[102:103], v[142:143], v[106:107], v[102:103]
	s_nop 0
	v_pk_fma_f32 v[100:101], v[146:147], v[100:101], v[102:103]
	s_nop 0
	v_mul_f32_e32 v102, 0xbfb8aa3b, v100
	v_mul_f32_e32 v103, 0xbfb8aa3b, v101
	v_exp_f32_e32 v102, v102
	v_exp_f32_e32 v103, v103
	v_add_f32_e32 v102, 1.0, v102
	v_add_f32_e32 v103, 1.0, v103
	v_rcp_f32_e32 v102, v102
	v_rcp_f32_e32 v103, v103
	s_nop 0
	v_pk_mul_f32 v[100:101], v[100:101], v[102:103]
	s_nop 0
	v_pk_mul_f32 v[100:101], v[98:99], v[100:101]
	v_cvt_pk_bf16_f32 v98, v108, v109
	v_cvt_pk_bf16_f32 v99, v100, v101
	v_lshl_add_u64 v[100:101], s[14:15], 0, v[224:225]
	v_lshl_add_u64 v[156:157], v[100:101], 0, v[176:177]
	global_store_dwordx4 v[156:157], v[96:99], off
	s_nop 1
	v_lshl_add_u64 v[96:97], s[12:13], 0, v[230:231]
	v_lshl_add_u64 v[96:97], v[96:97], 0, v[148:149]
	global_load_dwordx4 v[140:143], v[96:97], off
	v_lshl_add_u64 v[96:97], s[12:13], 0, v[228:229]
	v_lshl_add_u64 v[96:97], v[96:97], 0, v[148:149]
	global_load_dwordx4 v[136:139], v[96:97], off
	v_lshl_add_u64 v[96:97], s[12:13], 0, v[226:227]
	v_lshl_add_u64 v[96:97], v[96:97], 0, v[148:149]
	global_load_dwordx4 v[100:103], v[96:97], off
	v_lshl_add_u64 v[96:97], s[12:13], 0, v[224:225]
	v_lshl_add_u64 v[96:97], v[96:97], 0, v[148:149]
	global_load_dwordx4 v[96:99], v[96:97], off
	s_and_saveexec_b64 s[4:5], vcc
	s_xor_b64 s[4:5], exec, s[4:5]
	s_cbranch_execz .LBB0_984
	v_mov_b32_e32 v147, 0
	v_mov_b32_e32 v146, 0
	v_mov_b32_e32 v145, 0
	v_mov_b32_e32 v144, 0
	s_and_saveexec_b64 s[6:7], s[0:1]
	s_cbranch_execz .LBB0_983
	v_readlane_b32 s72, v254, 11
	v_lshlrev_b32_e32 v104, 2, v213
	v_readlane_b32 s73, v254, 12
	s_nop 4
	global_load_dword v114, v104, s[72:73]
	v_readlane_b32 s72, v254, 19
	v_readlane_b32 s73, v254, 20
	s_waitcnt vmcnt(0)
	v_fmamk_f32 v114, v114, 0x3a800000, v241
	v_lshl_add_u64 v[104:105], s[72:73], 0, v[220:221]
	v_lshl_add_u64 v[108:109], v[198:199], 2, v[104:105]
	global_load_dwordx4 v[104:107], v[108:109], off offset:512
	s_nop 0
	global_load_dwordx4 v[108:111], v[108:109], off offset:528
	v_mul_f32_e32 v115, 0x4b800000, v114
	v_cmp_gt_f32_e32 vcc, s77, v114
	s_nop 1
	v_cndmask_b32_e32 v114, v114, v115, vcc
	v_rsq_f32_e32 v114, v114
	s_nop 0
	v_mul_f32_e32 v115, 0x45800000, v114
	v_cndmask_b32_e32 v114, v114, v115, vcc
	s_waitcnt vmcnt(1)
	v_pk_mul_f32 v[104:105], v[104:105], v[114:115] op_sel_hi:[1,0]
	v_pk_mul_f32 v[106:107], v[106:107], v[114:115] op_sel_hi:[1,0]
	s_waitcnt vmcnt(0)
	v_pk_mul_f32 v[108:109], v[108:109], v[114:115] op_sel_hi:[1,0]
	v_pk_mul_f32 v[110:111], v[114:115], v[110:111] op_sel_hi:[0,1]
	v_cvt_pk_bf16_f32 v144, v104, v105
	v_cvt_pk_bf16_f32 v145, v106, v107
	v_cvt_pk_bf16_f32 v146, v108, v109
	v_cvt_pk_bf16_f32 v147, v110, v111

.LBB0_986:
	s_or_b64 exec, exec, s[4:5]
	global_load_dwordx4 v[104:107], v[200:201], off offset:528
	global_load_dwordx4 v[120:123], v[200:201], off offset:512
	global_load_dwordx4 v[108:111], v[202:203], off offset:528
	global_load_dwordx4 v[132:135], v[202:203], off offset:512
	v_lshlrev_b64 v[116:117], 2, v[112:113]
	v_lshl_add_u64 v[150:151], s[38:39], 0, v[116:117]
	global_load_dwordx4 v[128:131], v[150:151], off
	global_load_dwordx4 v[112:115], v[150:151], off offset:16
	v_lshl_add_u64 v[152:153], s[44:45], 0, v[116:117]
	global_load_dwordx4 v[124:127], v[152:153], off
	global_load_dwordx4 v[116:119], v[152:153], off offset:16
	s_nop 0
	s_nop 0
	s_nop 0
	s_nop 0
	s_nop 0
	s_waitcnt vmcnt(8)
	v_mov_b32_dpp v164, v144 row_ror:1 row_mask:0xf bank_mask:0xf
	v_mov_b32_dpp v165, v144 row_ror:2 row_mask:0xf bank_mask:0xf
	v_mov_b32_dpp v167, v145 row_ror:1 row_mask:0xf bank_mask:0xf
	v_mov_b32_dpp v168, v145 row_ror:2 row_mask:0xf bank_mask:0xf
	v_mov_b32_e32 v219, v218
	s_nop 0
	s_nop 0
	s_nop 0
	v_mov_b32_dpp v171, v146 row_ror:2 row_mask:0xf bank_mask:0xf
	v_mov_b32_dpp v164, v140 row_shr:1 row_mask:0xf bank_mask:0xf
	v_mov_b32_dpp v165, v140 row_shr:2 row_mask:0xf bank_mask:0xf
	v_mov_b32_dpp v167, v141 row_shr:1 row_mask:0xf bank_mask:0xf
	v_mov_b32_dpp v168, v141 row_shr:2 row_mask:0xf bank_mask:0xf
	v_mov_b32_dpp v169, v146 row_ror:1 row_mask:0xf bank_mask:0xf
	v_mov_b32_dpp v174, v147 row_ror:1 row_mask:0xf bank_mask:0xf
	v_mov_b32_dpp v175, v147 row_ror:2 row_mask:0xf bank_mask:0xf
	v_pk_mul_f32 v[144:145], v[88:89], v[218:219]
	v_mov_b32_dpp v171, v142 row_shr:2 row_mask:0xf bank_mask:0xf
	v_lshlrev_b32_e32 v88, 16, v164
	v_lshlrev_b32_e32 v146, 16, v165
	v_and_b32_e32 v89, 0xffff0000, v164
	v_and_b32_e32 v147, 0xffff0000, v165
	v_lshlrev_b32_e32 v164, 16, v167
	v_lshlrev_b32_e32 v166, 16, v168
	v_and_b32_e32 v165, 0xffff0000, v167
	v_and_b32_e32 v167, 0xffff0000, v168
	v_mov_b32_dpp v169, v142 row_shr:1 row_mask:0xf bank_mask:0xf
	v_lshlrev_b32_e32 v170, 16, v171
	v_and_b32_e32 v171, 0xffff0000, v171
	v_lshlrev_b32_e32 v158, 16, v140
	v_and_b32_e32 v159, 0xffff0000, v140
	v_lshlrev_b32_e32 v160, 16, v141
	v_and_b32_e32 v161, 0xffff0000, v141
	v_lshlrev_b32_e32 v168, 16, v169
	v_and_b32_e32 v169, 0xffff0000, v169
	v_lshlrev_b32_e32 v162, 16, v142
	v_and_b32_e32 v163, 0xffff0000, v142
	v_pk_mul_f32 v[92:93], v[92:93], v[218:219]
	v_pk_mul_f32 v[94:95], v[94:95], v[218:219]
	v_mov_b32_dpp v175, v143 row_shr:2 row_mask:0xf bank_mask:0xf
	v_mov_b32_dpp v174, v143 row_shr:1 row_mask:0xf bank_mask:0xf
	v_pk_mul_f32 v[90:91], v[90:91], v[218:219]
	v_mov_b32_e32 v217, v216
	v_pk_mul_f32 v[84:85], v[84:85], v[216:217]
	v_pk_mul_f32 v[86:87], v[86:87], v[216:217]
	v_pk_mul_f32 v[80:81], v[80:81], v[216:217]
	v_pk_mul_f32 v[82:83], v[82:83], v[216:217]
	v_mov_b32_e32 v215, v214
	v_pk_mul_f32 v[76:77], v[76:77], v[214:215]
	v_pk_mul_f32 v[78:79], v[78:79], v[214:215]
	v_pk_mul_f32 v[72:73], v[72:73], v[214:215]
	v_pk_mul_f32 v[74:75], v[74:75], v[214:215]
	v_mov_b32_e32 v213, v212
	v_pk_mul_f32 v[68:69], v[68:69], v[212:213]
	v_pk_mul_f32 v[70:71], v[70:71], v[212:213]
	v_pk_mul_f32 v[64:65], v[64:65], v[212:213]
	v_pk_mul_f32 v[66:67], v[66:67], v[212:213]
	s_waitcnt vmcnt(5)
	v_pk_fma_f32 v[170:171], v[104:105], v[170:171], v[108:109]
	s_waitcnt vmcnt(4)
	v_pk_fma_f32 v[146:147], v[120:121], v[146:147], v[132:133]
	v_pk_fma_f32 v[166:167], v[122:123], v[166:167], v[134:135]
	s_waitcnt vmcnt(3)
	v_pk_fma_f32 v[88:89], v[128:129], v[88:89], v[146:147]
	v_pk_fma_f32 v[146:147], v[130:131], v[164:165], v[166:167]
	s_waitcnt vmcnt(2)
	v_pk_fma_f32 v[164:165], v[112:113], v[168:169], v[170:171]
	s_waitcnt vmcnt(1)
	v_pk_fma_f32 v[88:89], v[124:125], v[158:159], v[88:89]
	v_pk_fma_f32 v[146:147], v[126:127], v[160:161], v[146:147]
	s_waitcnt vmcnt(0)
	v_pk_fma_f32 v[158:159], v[116:117], v[162:163], v[164:165]
	v_mul_f32_e32 v160, 0xbfb8aa3b, v88
	v_mul_f32_e32 v161, 0xbfb8aa3b, v89
	v_mul_f32_e32 v162, 0xbfb8aa3b, v146
	v_mul_f32_e32 v163, 0xbfb8aa3b, v147
	v_exp_f32_e32 v160, v160
	v_exp_f32_e32 v161, v161
	v_exp_f32_e32 v162, v162
	v_exp_f32_e32 v163, v163
	v_add_f32_e32 v160, 1.0, v160
	v_add_f32_e32 v161, 1.0, v161
	v_add_f32_e32 v162, 1.0, v162
	v_add_f32_e32 v163, 1.0, v163
	v_rcp_f32_e32 v160, v160
	v_rcp_f32_e32 v161, v161
	v_rcp_f32_e32 v162, v162
	v_rcp_f32_e32 v163, v163
	v_mul_f32_e32 v164, 0xbfb8aa3b, v158
	v_pk_mul_f32 v[88:89], v[88:89], v[160:161]
	v_mul_f32_e32 v165, 0xbfb8aa3b, v159
	v_pk_mul_f32 v[146:147], v[146:147], v[162:163]
	v_pk_mul_f32 v[88:89], v[92:93], v[88:89]
	v_pk_mul_f32 v[92:93], v[94:95], v[146:147]
	v_lshlrev_b32_e32 v94, 16, v175
	v_and_b32_e32 v95, 0xffff0000, v175
	v_cvt_pk_bf16_f32 v88, v88, v89
	v_cvt_pk_bf16_f32 v89, v92, v93
	v_lshlrev_b32_e32 v92, 16, v174
	v_and_b32_e32 v93, 0xffff0000, v174
	v_pk_fma_f32 v[94:95], v[106:107], v[94:95], v[110:111]
	v_lshlrev_b32_e32 v146, 16, v143
	v_and_b32_e32 v147, 0xffff0000, v143
	v_pk_fma_f32 v[92:93], v[114:115], v[92:93], v[94:95]
	v_exp_f32_e32 v164, v164
	v_pk_fma_f32 v[92:93], v[118:119], v[146:147], v[92:93]
	v_exp_f32_e32 v165, v165
	v_mul_f32_e32 v94, 0xbfb8aa3b, v92
	v_mul_f32_e32 v95, 0xbfb8aa3b, v93
	v_exp_f32_e32 v94, v94
	v_exp_f32_e32 v95, v95
	v_add_f32_e32 v164, 1.0, v164
	v_add_f32_e32 v160, 1.0, v165
	v_add_f32_e32 v94, 1.0, v94
	v_add_f32_e32 v95, 1.0, v95
	v_rcp_f32_e32 v164, v164
	v_rcp_f32_e32 v165, v160
	v_rcp_f32_e32 v94, v94
	v_rcp_f32_e32 v95, v95
	v_pk_mul_f32 v[146:147], v[158:159], v[164:165]
	s_nop 0
	v_pk_mul_f32 v[144:145], v[144:145], v[146:147]
	v_pk_mul_f32 v[92:93], v[92:93], v[94:95]
	s_nop 0
	v_pk_mul_f32 v[92:93], v[90:91], v[92:93]
	v_cvt_pk_bf16_f32 v90, v144, v145
	v_cvt_pk_bf16_f32 v91, v92, v93
	global_store_dwordx4 v[178:179], v[88:91], off offset:256
	v_mov_b32_dpp v95, v141 row_ror:1 row_mask:0xf bank_mask:0xf
	v_lshlrev_b32_e32 v92, 16, v136
	s_nop 0
	s_nop 0
	v_mov_b32_dpp v95, v137 row_shr:1 row_mask:0xf bank_mask:0xf
	v_mov_b32_dpp v91, v140 row_ror:2 row_mask:0xf bank_mask:0xf
	v_mov_b32_dpp v89, v140 row_ror:1 row_mask:0xf bank_mask:0xf
	s_nop 0
	v_mov_b32_dpp v91, v136 row_shr:2 row_mask:0xf bank_mask:0xf
	v_mov_b32_dpp v89, v136 row_shr:1 row_mask:0xf bank_mask:0xf
	v_lshlrev_b32_e32 v90, 16, v91
	v_and_b32_e32 v91, 0xffff0000, v91
	v_mov_b32_dpp v140, v141 row_ror:2 row_mask:0xf bank_mask:0xf
	v_lshlrev_b32_e32 v88, 16, v89
	v_and_b32_e32 v89, 0xffff0000, v89
	v_pk_fma_f32 v[90:91], v[120:121], v[90:91], v[132:133]
	v_and_b32_e32 v93, 0xffff0000, v136
	v_pk_fma_f32 v[88:89], v[128:129], v[88:89], v[90:91]
	v_mov_b32_dpp v140, v137 row_shr:2 row_mask:0xf bank_mask:0xf
	v_pk_fma_f32 v[88:89], v[124:125], v[92:93], v[88:89]
	v_lshlrev_b32_e32 v92, 16, v95
	v_lshlrev_b32_e32 v94, 16, v140
	v_and_b32_e32 v93, 0xffff0000, v95
	v_and_b32_e32 v95, 0xffff0000, v140
	v_pk_fma_f32 v[94:95], v[122:123], v[94:95], v[134:135]
	v_lshlrev_b32_e32 v140, 16, v137
	v_and_b32_e32 v141, 0xffff0000, v137
	v_pk_fma_f32 v[92:93], v[130:131], v[92:93], v[94:95]
	v_mul_f32_e32 v90, 0xbfb8aa3b, v88
	v_mul_f32_e32 v91, 0xbfb8aa3b, v89
	v_pk_fma_f32 v[92:93], v[126:127], v[140:141], v[92:93]
	v_exp_f32_e32 v90, v90
	v_exp_f32_e32 v91, v91
	v_mul_f32_e32 v94, 0xbfb8aa3b, v92
	v_mul_f32_e32 v95, 0xbfb8aa3b, v93
	v_exp_f32_e32 v94, v94
	v_exp_f32_e32 v95, v95
	v_add_f32_e32 v90, 1.0, v90
	v_add_f32_e32 v91, 1.0, v91
	v_rcp_f32_e32 v90, v90
	v_rcp_f32_e32 v91, v91
	v_add_f32_e32 v94, 1.0, v94
	v_add_f32_e32 v95, 1.0, v95
	v_rcp_f32_e32 v94, v94
	v_rcp_f32_e32 v95, v95
	v_pk_mul_f32 v[88:89], v[88:89], v[90:91]
	v_lshlrev_b32_e32 v90, 16, v138
	v_pk_mul_f32 v[84:85], v[84:85], v[88:89]
	v_pk_mul_f32 v[88:89], v[92:93], v[94:95]
	v_cvt_pk_bf16_f32 v84, v84, v85
	v_pk_mul_f32 v[86:87], v[86:87], v[88:89]
	s_nop 0
	v_cvt_pk_bf16_f32 v85, v86, v87
	s_nop 0
	v_mov_b32_dpp v89, v142 row_ror:2 row_mask:0xf bank_mask:0xf
	s_nop 0
	v_mov_b32_dpp v87, v142 row_ror:1 row_mask:0xf bank_mask:0xf
	v_mov_b32_dpp v89, v138 row_shr:2 row_mask:0xf bank_mask:0xf
	s_nop 0
	v_mov_b32_dpp v87, v138 row_shr:1 row_mask:0xf bank_mask:0xf
	v_lshlrev_b32_e32 v88, 16, v89
	v_and_b32_e32 v89, 0xffff0000, v89
	v_mov_b32_dpp v93, v143 row_ror:1 row_mask:0xf bank_mask:0xf
	v_mov_b32_dpp v94, v143 row_ror:2 row_mask:0xf bank_mask:0xf
	v_lshlrev_b32_e32 v86, 16, v87
	v_and_b32_e32 v87, 0xffff0000, v87
	v_pk_fma_f32 v[88:89], v[104:105], v[88:89], v[108:109]
	v_mov_b32_dpp v93, v139 row_shr:1 row_mask:0xf bank_mask:0xf
	v_and_b32_e32 v91, 0xffff0000, v138
	v_pk_fma_f32 v[86:87], v[112:113], v[86:87], v[88:89]
	v_mov_b32_dpp v94, v139 row_shr:2 row_mask:0xf bank_mask:0xf
	v_pk_fma_f32 v[86:87], v[116:117], v[90:91], v[86:87]
	v_lshlrev_b32_e32 v90, 16, v93
	v_lshlrev_b32_e32 v92, 16, v94
	v_and_b32_e32 v91, 0xffff0000, v93
	v_and_b32_e32 v93, 0xffff0000, v94
	v_pk_fma_f32 v[92:93], v[106:107], v[92:93], v[110:111]
	v_lshlrev_b32_e32 v94, 16, v139
	v_and_b32_e32 v95, 0xffff0000, v139
	v_pk_fma_f32 v[90:91], v[114:115], v[90:91], v[92:93]
	v_mul_f32_e32 v88, 0xbfb8aa3b, v86
	v_mul_f32_e32 v89, 0xbfb8aa3b, v87
	v_pk_fma_f32 v[90:91], v[118:119], v[94:95], v[90:91]
	v_exp_f32_e32 v88, v88
	v_exp_f32_e32 v89, v89
	v_mul_f32_e32 v92, 0xbfb8aa3b, v90
	v_mul_f32_e32 v93, 0xbfb8aa3b, v91
	v_exp_f32_e32 v92, v92
	v_exp_f32_e32 v93, v93
	v_add_f32_e32 v88, 1.0, v88
	v_add_f32_e32 v89, 1.0, v89
	v_rcp_f32_e32 v88, v88
	v_rcp_f32_e32 v89, v89
	v_add_f32_e32 v92, 1.0, v92
	v_add_f32_e32 v93, 1.0, v93
	v_rcp_f32_e32 v92, v92
	v_rcp_f32_e32 v93, v93
	v_pk_mul_f32 v[86:87], v[86:87], v[88:89]
	s_nop 0
	v_pk_mul_f32 v[80:81], v[80:81], v[86:87]
	v_pk_mul_f32 v[86:87], v[90:91], v[92:93]
	v_mov_b32_dpp v88, v137 row_ror:2 row_mask:0xf bank_mask:0xf
	v_pk_mul_f32 v[82:83], v[82:83], v[86:87]
	v_cvt_pk_bf16_f32 v86, v80, v81
	v_cvt_pk_bf16_f32 v87, v82, v83
	s_nop 0
	s_nop 0
	global_store_dwordx4 v[172:173], v[84:87], off offset:256
	v_mov_b32_dpp v83, v136 row_ror:2 row_mask:0xf bank_mask:0xf
	v_mov_b32_dpp v81, v136 row_ror:1 row_mask:0xf bank_mask:0xf
	s_nop 0
	v_mov_b32_dpp v83, v100 row_shr:2 row_mask:0xf bank_mask:0xf
	v_mov_b32_dpp v81, v100 row_shr:1 row_mask:0xf bank_mask:0xf
	v_lshlrev_b32_e32 v82, 16, v83
	v_and_b32_e32 v83, 0xffff0000, v83
	v_mov_b32_dpp v87, v137 row_ror:1 row_mask:0xf bank_mask:0xf
	v_lshlrev_b32_e32 v80, 16, v81
	v_and_b32_e32 v81, 0xffff0000, v81
	v_pk_fma_f32 v[82:83], v[120:121], v[82:83], v[132:133]
	v_mov_b32_dpp v87, v101 row_shr:1 row_mask:0xf bank_mask:0xf
	v_lshlrev_b32_e32 v84, 16, v100
	v_and_b32_e32 v85, 0xffff0000, v100
	v_pk_fma_f32 v[80:81], v[128:129], v[80:81], v[82:83]
	v_mov_b32_dpp v88, v101 row_shr:2 row_mask:0xf bank_mask:0xf
	v_pk_fma_f32 v[80:81], v[124:125], v[84:85], v[80:81]
	v_lshlrev_b32_e32 v84, 16, v87
	v_lshlrev_b32_e32 v86, 16, v88
	v_and_b32_e32 v85, 0xffff0000, v87
	v_and_b32_e32 v87, 0xffff0000, v88
	v_pk_fma_f32 v[86:87], v[122:123], v[86:87], v[134:135]
	v_lshlrev_b32_e32 v88, 16, v101
	v_and_b32_e32 v89, 0xffff0000, v101
	v_pk_fma_f32 v[84:85], v[130:131], v[84:85], v[86:87]
	v_mul_f32_e32 v82, 0xbfb8aa3b, v80
	v_mul_f32_e32 v83, 0xbfb8aa3b, v81
	v_pk_fma_f32 v[84:85], v[126:127], v[88:89], v[84:85]
	v_exp_f32_e32 v82, v82
	v_exp_f32_e32 v83, v83
	v_mul_f32_e32 v86, 0xbfb8aa3b, v84
	v_mul_f32_e32 v87, 0xbfb8aa3b, v85
	v_exp_f32_e32 v86, v86
	v_exp_f32_e32 v87, v87
	v_add_f32_e32 v82, 1.0, v82
	v_add_f32_e32 v83, 1.0, v83
	v_rcp_f32_e32 v82, v82
	v_rcp_f32_e32 v83, v83
	v_add_f32_e32 v86, 1.0, v86
	v_add_f32_e32 v87, 1.0, v87
	v_rcp_f32_e32 v86, v86
	v_rcp_f32_e32 v87, v87
	v_pk_mul_f32 v[80:81], v[80:81], v[82:83]
	v_lshlrev_b32_e32 v82, 16, v102
	v_pk_mul_f32 v[76:77], v[76:77], v[80:81]
	v_pk_mul_f32 v[80:81], v[84:85], v[86:87]
	v_cvt_pk_bf16_f32 v76, v76, v77
	v_pk_mul_f32 v[78:79], v[78:79], v[80:81]
	s_nop 0
	v_cvt_pk_bf16_f32 v77, v78, v79
	s_nop 0
	v_mov_b32_dpp v81, v138 row_ror:2 row_mask:0xf bank_mask:0xf
	s_nop 0
	v_mov_b32_dpp v79, v138 row_ror:1 row_mask:0xf bank_mask:0xf
	v_mov_b32_dpp v81, v102 row_shr:2 row_mask:0xf bank_mask:0xf
	s_nop 0
	v_mov_b32_dpp v79, v102 row_shr:1 row_mask:0xf bank_mask:0xf
	v_lshlrev_b32_e32 v80, 16, v81
	v_and_b32_e32 v81, 0xffff0000, v81
	v_mov_b32_dpp v85, v139 row_ror:1 row_mask:0xf bank_mask:0xf
	v_mov_b32_dpp v86, v139 row_ror:2 row_mask:0xf bank_mask:0xf
	v_lshlrev_b32_e32 v78, 16, v79
	v_and_b32_e32 v79, 0xffff0000, v79
	v_pk_fma_f32 v[80:81], v[104:105], v[80:81], v[108:109]
	v_mov_b32_dpp v85, v103 row_shr:1 row_mask:0xf bank_mask:0xf
	v_and_b32_e32 v83, 0xffff0000, v102
	v_pk_fma_f32 v[78:79], v[112:113], v[78:79], v[80:81]
	v_mov_b32_dpp v86, v103 row_shr:2 row_mask:0xf bank_mask:0xf
	v_pk_fma_f32 v[78:79], v[116:117], v[82:83], v[78:79]
	v_lshlrev_b32_e32 v82, 16, v85
	v_lshlrev_b32_e32 v84, 16, v86
	v_and_b32_e32 v83, 0xffff0000, v85
	v_and_b32_e32 v85, 0xffff0000, v86
	v_pk_fma_f32 v[84:85], v[106:107], v[84:85], v[110:111]
	v_lshlrev_b32_e32 v86, 16, v103
	v_and_b32_e32 v87, 0xffff0000, v103
	v_pk_fma_f32 v[82:83], v[114:115], v[82:83], v[84:85]
	v_mul_f32_e32 v80, 0xbfb8aa3b, v78
	v_mul_f32_e32 v81, 0xbfb8aa3b, v79
	v_pk_fma_f32 v[82:83], v[118:119], v[86:87], v[82:83]
	v_exp_f32_e32 v80, v80
	v_exp_f32_e32 v81, v81
	v_mul_f32_e32 v84, 0xbfb8aa3b, v82
	v_mul_f32_e32 v85, 0xbfb8aa3b, v83
	v_exp_f32_e32 v84, v84
	v_exp_f32_e32 v85, v85
	v_add_f32_e32 v80, 1.0, v80
	v_add_f32_e32 v81, 1.0, v81
	v_rcp_f32_e32 v80, v80
	v_rcp_f32_e32 v81, v81
	v_add_f32_e32 v84, 1.0, v84
	v_add_f32_e32 v85, 1.0, v85
	v_rcp_f32_e32 v84, v84
	v_rcp_f32_e32 v85, v85
	v_pk_mul_f32 v[78:79], v[78:79], v[80:81]
	s_nop 0
	v_pk_mul_f32 v[72:73], v[72:73], v[78:79]
	v_pk_mul_f32 v[78:79], v[82:83], v[84:85]
	s_nop 0
	v_pk_mul_f32 v[74:75], v[74:75], v[78:79]
	v_cvt_pk_bf16_f32 v78, v72, v73
	s_nop 0
	v_cvt_pk_bf16_f32 v79, v74, v75
	s_nop 0
	v_mov_b32_dpp v73, v100 row_ror:2 row_mask:0xf bank_mask:0xf
	global_store_dwordx4 v[154:155], v[76:79], off offset:256
	v_mov_b32_dpp v75, v100 row_ror:1 row_mask:0xf bank_mask:0xf
	v_mov_b32_dpp v73, v96 row_shr:2 row_mask:0xf bank_mask:0xf
	v_lshlrev_b32_e32 v72, 16, v73
	v_mov_b32_dpp v75, v96 row_shr:1 row_mask:0xf bank_mask:0xf
	v_and_b32_e32 v73, 0xffff0000, v73
	v_lshlrev_b32_e32 v74, 16, v75
	v_and_b32_e32 v75, 0xffff0000, v75
	v_pk_fma_f32 v[72:73], v[120:121], v[72:73], v[132:133]
	s_nop 0
	v_pk_fma_f32 v[72:73], v[128:129], v[74:75], v[72:73]
	v_lshlrev_b32_e32 v74, 16, v96
	v_and_b32_e32 v75, 0xffff0000, v96
	v_pk_fma_f32 v[72:73], v[124:125], v[74:75], v[72:73]
	s_nop 0
	v_mul_f32_e32 v74, 0xbfb8aa3b, v72
	v_mul_f32_e32 v75, 0xbfb8aa3b, v73
	v_exp_f32_e32 v74, v74
	v_exp_f32_e32 v75, v75
	v_mov_b32_dpp v78, v101 row_ror:2 row_mask:0xf bank_mask:0xf
	v_mov_b32_dpp v76, v101 row_ror:1 row_mask:0xf bank_mask:0xf
	v_add_f32_e32 v74, 1.0, v74
	v_add_f32_e32 v75, 1.0, v75
	v_rcp_f32_e32 v74, v74
	v_rcp_f32_e32 v75, v75
	v_mov_b32_dpp v78, v97 row_shr:2 row_mask:0xf bank_mask:0xf
	v_mov_b32_dpp v76, v97 row_shr:1 row_mask:0xf bank_mask:0xf
	v_lshlrev_b32_e32 v80, 16, v76
	v_pk_mul_f32 v[72:73], v[72:73], v[74:75]
	v_lshlrev_b32_e32 v74, 16, v78
	v_and_b32_e32 v75, 0xffff0000, v78
	v_and_b32_e32 v81, 0xffff0000, v76
	v_pk_fma_f32 v[74:75], v[122:123], v[74:75], v[134:135]
	s_nop 0
	v_pk_fma_f32 v[74:75], v[130:131], v[80:81], v[74:75]
	v_lshlrev_b32_e32 v80, 16, v97
	v_and_b32_e32 v81, 0xffff0000, v97
	v_mov_b32_dpp v84, v102 row_ror:2 row_mask:0xf bank_mask:0xf
	v_pk_fma_f32 v[74:75], v[126:127], v[80:81], v[74:75]
	v_mov_b32_dpp v83, v102 row_ror:1 row_mask:0xf bank_mask:0xf
	v_mov_b32_dpp v84, v98 row_shr:2 row_mask:0xf bank_mask:0xf
	v_mul_f32_e32 v76, 0xbfb8aa3b, v74
	v_mov_b32_dpp v83, v98 row_shr:1 row_mask:0xf bank_mask:0xf
	v_exp_f32_e32 v76, v76
	v_lshlrev_b32_e32 v80, 16, v84
	v_and_b32_e32 v81, 0xffff0000, v84
	v_lshlrev_b32_e32 v82, 16, v83
	v_and_b32_e32 v83, 0xffff0000, v83
	v_pk_fma_f32 v[80:81], v[104:105], v[80:81], v[108:109]
	v_pk_mul_f32 v[68:69], v[68:69], v[72:73]
	v_pk_fma_f32 v[80:81], v[112:113], v[82:83], v[80:81]
	v_lshlrev_b32_e32 v82, 16, v98
	v_and_b32_e32 v83, 0xffff0000, v98
	v_mul_f32_e32 v72, 0xbfb8aa3b, v75
	v_pk_fma_f32 v[80:81], v[116:117], v[82:83], v[80:81]
	v_exp_f32_e32 v73, v72
	v_add_f32_e32 v72, 1.0, v76
	v_mul_f32_e32 v76, 0xbfb8aa3b, v80
	v_exp_f32_e32 v76, v76
	v_mul_f32_e32 v78, 0xbfb8aa3b, v81
	v_exp_f32_e32 v78, v78
	v_add_f32_e32 v73, 1.0, v73
	s_nop 0
	v_mov_b32_dpp v86, v103 row_ror:2 row_mask:0xf bank_mask:0xf
	v_rcp_f32_e32 v72, v72
	v_rcp_f32_e32 v73, v73
	v_add_f32_e32 v76, 1.0, v76
	v_mov_b32_dpp v85, v103 row_ror:1 row_mask:0xf bank_mask:0xf
	v_mov_b32_dpp v86, v99 row_shr:2 row_mask:0xf bank_mask:0xf
	v_rcp_f32_e32 v82, v76
	v_add_f32_e32 v76, 1.0, v78
	v_mov_b32_dpp v85, v99 row_shr:1 row_mask:0xf bank_mask:0xf
	v_and_b32_e32 v77, 0xffff0000, v86
	v_rcp_f32_e32 v83, v76
	v_lshlrev_b32_e32 v76, 16, v86
	v_and_b32_e32 v79, 0xffff0000, v85
	v_lshlrev_b32_e32 v78, 16, v85
	v_pk_fma_f32 v[76:77], v[106:107], v[76:77], v[110:111]
	v_pk_mul_f32 v[72:73], v[74:75], v[72:73]
	v_lshlrev_b32_e32 v74, 16, v99
	v_and_b32_e32 v75, 0xffff0000, v99
	v_pk_fma_f32 v[76:77], v[114:115], v[78:79], v[76:77]
	v_pk_mul_f32 v[70:71], v[70:71], v[72:73]
	v_pk_fma_f32 v[74:75], v[118:119], v[74:75], v[76:77]
	v_pk_mul_f32 v[72:73], v[80:81], v[82:83]
	v_mul_f32_e32 v76, 0xbfb8aa3b, v74
	v_exp_f32_e32 v76, v76
	v_mul_f32_e32 v77, 0xbfb8aa3b, v75
	v_exp_f32_e32 v77, v77
	v_pk_mul_f32 v[72:73], v[64:65], v[72:73]
	v_add_f32_e32 v64, 1.0, v76
	v_rcp_f32_e32 v76, v64
	v_add_f32_e32 v64, 1.0, v77
	v_rcp_f32_e32 v77, v64
	v_cvt_pk_bf16_f32 v64, v68, v69
	v_cvt_pk_bf16_f32 v65, v70, v71
	v_add_u32_e32 v70, 0x90, v204
	v_pk_mul_f32 v[68:69], v[74:75], v[76:77]
	v_ashrrev_i32_e32 v71, 31, v70
	v_pk_mul_f32 v[68:69], v[66:67], v[68:69]
	v_cvt_pk_bf16_f32 v66, v72, v73
	v_cvt_pk_bf16_f32 v67, v68, v69
	v_add_u32_e32 v68, 0x80, v204
	v_ashrrev_i32_e32 v69, 31, v68
	global_store_dwordx4 v[156:157], v[64:67], off offset:256
	v_add_u32_e32 v76, 0xa0, v204
	v_ashrrev_i32_e32 v77, 31, v76
	v_lshlrev_b64 v[64:65], 6, v[68:69]
	v_lshl_add_u64 v[64:65], v[188:189], 0, v[64:65]
	global_load_dwordx4 v[80:83], v[64:65], off
	v_lshlrev_b64 v[64:65], 6, v[70:71]
	v_lshl_add_u64 v[64:65], v[188:189], 0, v[64:65]
	global_load_dwordx4 v[84:87], v[64:65], off
	v_lshlrev_b64 v[64:65], 6, v[76:77]
	v_add_u32_e32 v78, 0xb0, v204
	v_lshl_add_u64 v[64:65], v[188:189], 0, v[64:65]
	v_ashrrev_i32_e32 v79, 31, v78
	global_load_dwordx4 v[92:95], v[64:65], off
	v_lshlrev_b64 v[64:65], 6, v[78:79]
	v_lshl_add_u64 v[64:65], v[188:189], 0, v[64:65]
	global_load_dwordx4 v[96:99], v[64:65], off
	v_mad_i64_i32 v[64:65], s[4:5], v68, s70, v[206:207]
	v_mad_i64_i32 v[66:67], s[4:5], v70, s70, v[206:207]
	global_load_dwordx4 v[108:111], v[64:65], off
	global_load_dwordx4 v[88:91], v[66:67], off
	v_mad_i64_i32 v[64:65], s[4:5], v76, s70, v[206:207]
	v_mad_i64_i32 v[66:67], s[4:5], v78, s70, v[206:207]
	global_load_dwordx4 v[72:75], v[64:65], off
	s_nop 0
	global_load_dwordx4 v[64:67], v[66:67], off
	v_and_b32_e32 v117, 0x1fcf, v68
	v_cmp_gt_u32_e32 vcc, 16, v117
	v_mul_hi_u32_u24_e32 v125, 0x2c00, v117
	v_mul_u32_u24_e32 v124, 0x2c00, v117
	s_waitcnt vmcnt(7)
	v_mov_b32_e32 v100, v81
	v_mov_b32_e32 v101, v82
	v_mov_b32_e32 v81, v83
	s_waitcnt vmcnt(6)
	v_mov_b32_e32 v82, v85
	v_mov_b32_e32 v83, v86
	v_mov_b32_e32 v85, v87
	v_pk_add_f32 v[80:81], v[100:101], v[80:81]
	v_pk_add_f32 v[82:83], v[82:83], v[84:85]
	v_mov_b32_e32 v85, v80
	v_mov_b32_e32 v84, v82
	v_mov_b32_e32 v80, v83
	v_pk_add_f32 v[80:81], v[84:85], v[80:81]
	s_waitcnt vmcnt(5)
	v_mov_b32_e32 v84, v93
	v_mov_b32_e32 v85, v94
	v_mov_b32_e32 v93, v95
	s_waitcnt vmcnt(4)
	v_mov_b32_e32 v86, v97
	v_mov_b32_e32 v87, v98
	v_mov_b32_e32 v97, v99
	v_pk_add_f32 v[84:85], v[84:85], v[92:93]
	v_pk_add_f32 v[86:87], v[86:87], v[96:97]
	v_mov_b32_e32 v93, v84
	v_mov_b32_e32 v92, v86
	v_mov_b32_e32 v84, v87
	v_pk_add_f32 v[92:93], v[92:93], v[84:85]
	ds_bpermute_b32 v83, v205, v81
	ds_bpermute_b32 v82, v205, v80
	ds_bpermute_b32 v95, v205, v93
	ds_bpermute_b32 v94, v205, v92
	s_waitcnt lgkmcnt(2)
	v_pk_add_f32 v[84:85], v[80:81], v[82:83]
	ds_bpermute_b32 v87, v242, v85
	s_waitcnt lgkmcnt(1)
	v_pk_add_f32 v[80:81], v[92:93], v[94:95]
	ds_bpermute_b32 v86, v242, v84
	ds_bpermute_b32 v83, v242, v81
	ds_bpermute_b32 v82, v242, v80
	s_and_saveexec_b64 s[4:5], vcc
	s_xor_b64 s[6:7], exec, s[4:5]
	s_cbranch_execz .LBB0_990
	v_mov_b32_e32 v115, 0
	v_mov_b32_e32 v114, 0
	v_mov_b32_e32 v113, 0
	v_mov_b32_e32 v112, 0
	s_and_saveexec_b64 s[82:83], s[0:1]
	s_cbranch_execz .LBB0_989
	v_readlane_b32 s4, v254, 11
	v_lshlrev_b32_e32 v69, 2, v117
	v_readlane_b32 s5, v254, 12
	s_nop 4
	global_load_dword v69, v69, s[4:5]
	v_readlane_b32 s4, v254, 19
	v_readlane_b32 s5, v254, 20
	s_waitcnt vmcnt(0)
	v_fmamk_f32 v69, v69, 0x3a800000, v241
	v_lshl_add_u64 v[92:93], s[4:5], 0, v[124:125]
	v_lshl_add_u64 v[96:97], v[198:199], 2, v[92:93]
	global_load_dwordx4 v[92:95], v[96:97], off
	s_nop 0
	global_load_dwordx4 v[96:99], v[96:97], off offset:16
	v_mul_f32_e32 v71, 0x4b800000, v69
	v_cmp_gt_f32_e64 s[4:5], s77, v69
	s_nop 1
	v_cndmask_b32_e64 v69, v69, v71, s[4:5]
	v_rsq_f32_e32 v69, v69
	s_nop 0
	v_mul_f32_e32 v71, 0x45800000, v69
	v_cndmask_b32_e64 v100, v69, v71, s[4:5]
	s_waitcnt vmcnt(1)
	v_pk_mul_f32 v[92:93], v[92:93], v[100:101] op_sel_hi:[1,0]
	v_pk_mul_f32 v[94:95], v[94:95], v[100:101] op_sel_hi:[1,0]
	s_waitcnt vmcnt(0)
	v_pk_mul_f32 v[96:97], v[96:97], v[100:101] op_sel_hi:[1,0]
	v_pk_mul_f32 v[98:99], v[100:101], v[98:99] op_sel_hi:[0,1]
	v_cvt_pk_bf16_f32 v112, v92, v93
	v_cvt_pk_bf16_f32 v113, v94, v95
	v_cvt_pk_bf16_f32 v114, v96, v97
	v_cvt_pk_bf16_f32 v115, v98, v99

.LBB0_992:
	s_or_b64 exec, exec, s[4:5]
	v_mad_i64_i32 v[134:135], s[4:5], v68, s70, 0
	v_mad_i64_i32 v[132:133], s[4:5], v70, s70, 0
	s_waitcnt lgkmcnt(2)
	v_pk_add_f32 v[68:69], v[84:85], v[86:87]
	v_mov_b64_e32 v[70:71], s[62:63]
	v_pk_fma_f32 v[68:69], v[68:69], s[60:61], v[70:71] op_sel_hi:[1,0,0]
	v_mad_i64_i32 v[130:131], s[4:5], v76, s70, 0
	v_mul_f32_e32 v76, 0x4b800000, v69
	v_cmp_gt_f32_e64 s[6:7], s77, v69
	v_mad_i64_i32 v[128:129], s[4:5], v78, s70, 0
	s_nop 0
	v_cndmask_b32_e64 v69, v69, v76, s[6:7]
	v_rsq_f32_e32 v69, v69
	v_cmp_gt_f32_e64 s[4:5], s77, v68
	s_nop 0
	s_nop 0
	v_mul_f32_e32 v76, 0x45800000, v69
	v_cndmask_b32_e64 v122, v69, v76, s[6:7]
	v_mul_f32_e32 v69, 0x4b800000, v68
	v_cndmask_b32_e64 v68, v68, v69, s[4:5]
	v_rsq_f32_e32 v68, v68
	s_waitcnt vmcnt(0)
	v_mov_b32_dpp v121, v112 row_ror:2 row_mask:0xf bank_mask:0xf
	v_mov_b32_dpp v119, v112 row_ror:1 row_mask:0xf bank_mask:0xf
	s_nop 0
	v_mul_f32_e32 v69, 0x45800000, v68
	v_cndmask_b32_e64 v120, v68, v69, s[4:5]
	s_waitcnt lgkmcnt(0)
	v_pk_add_f32 v[68:69], v[80:81], v[82:83]
	v_mov_b32_dpp v121, v108 row_shr:2 row_mask:0xf bank_mask:0xf
	v_pk_fma_f32 v[68:69], v[68:69], s[60:61], v[70:71] op_sel_hi:[1,0,0]
	v_mov_b32_dpp v119, v108 row_shr:1 row_mask:0xf bank_mask:0xf
	v_mul_f32_e32 v70, 0x4b800000, v69
	v_cmp_gt_f32_e64 s[6:7], s77, v69
	v_cmp_gt_f32_e64 s[4:5], s77, v68
	s_nop 0
	v_cndmask_b32_e64 v69, v69, v70, s[6:7]
	v_rsq_f32_e32 v69, v69
	v_lshlrev_b32_e32 v136, 16, v121
	v_and_b32_e32 v137, 0xffff0000, v121
	v_mov_b32_dpp v123, v113 row_ror:1 row_mask:0xf bank_mask:0xf
	v_mul_f32_e32 v70, 0x45800000, v69
	v_cndmask_b32_e64 v118, v69, v70, s[6:7]
	v_mul_f32_e32 v69, 0x4b800000, v68
	v_cndmask_b32_e64 v68, v68, v69, s[4:5]
	v_rsq_f32_e32 v68, v68
	v_mov_b32_dpp v140, v113 row_ror:2 row_mask:0xf bank_mask:0xf
	v_lshlrev_b32_e32 v112, 16, v119
	v_and_b32_e32 v113, 0xffff0000, v119
	v_mul_f32_e32 v69, 0x45800000, v68
	v_cndmask_b32_e64 v116, v68, v69, s[4:5]
	global_load_dwordx4 v[68:71], v[200:201], off offset:16
	global_load_dwordx4 v[100:103], v[200:201], off
	global_load_dwordx4 v[76:79], v[210:211], off offset:16
	global_load_dwordx4 v[96:99], v[210:211], off
	global_load_dwordx4 v[80:83], v[208:209], off offset:16
	global_load_dwordx4 v[92:95], v[208:209], off
	global_load_dwordx4 v[84:87], v[202:203], off offset:16
	global_load_dwordx4 v[104:107], v[202:203], off
	v_lshlrev_b32_e32 v138, 16, v108
	v_and_b32_e32 v139, 0xffff0000, v108
	v_mov_b32_dpp v123, v109 row_shr:1 row_mask:0xf bank_mask:0xf
	v_mov_b32_dpp v140, v109 row_shr:2 row_mask:0xf bank_mask:0xf
	v_pk_mul_f32 v[60:61], v[60:61], v[122:123] op_sel_hi:[1,0]
	v_pk_mul_f32 v[62:63], v[62:63], v[122:123] op_sel_hi:[1,0]
	s_nop 0
	v_pk_mul_f32 v[56:57], v[56:57], v[122:123] op_sel_hi:[1,0]
	v_pk_mul_f32 v[58:59], v[58:59], v[122:123] op_sel_hi:[1,0]
	v_mov_b32_dpp v121, v115 row_ror:2 row_mask:0xf bank_mask:0xf
	v_pk_mul_f32 v[36:37], v[36:37], v[116:117] op_sel_hi:[1,0]
	v_pk_mul_f32 v[38:39], v[38:39], v[116:117] op_sel_hi:[1,0]
	v_mov_b32_dpp v121, v111 row_shr:2 row_mask:0xf bank_mask:0xf
	v_pk_mul_f32 v[52:53], v[52:53], v[120:121] op_sel_hi:[1,0]
	v_pk_mul_f32 v[54:55], v[54:55], v[120:121] op_sel_hi:[1,0]
	v_pk_mul_f32 v[48:49], v[48:49], v[120:121] op_sel_hi:[1,0]
	v_pk_mul_f32 v[50:51], v[50:51], v[120:121] op_sel_hi:[1,0]
	v_pk_mul_f32 v[32:33], v[32:33], v[116:117] op_sel_hi:[1,0]
	v_pk_mul_f32 v[34:35], v[34:35], v[116:117] op_sel_hi:[1,0]
	s_waitcnt vmcnt(0)
	v_pk_fma_f32 v[136:137], v[100:101], v[136:137], v[104:105]
	s_nop 0
	v_pk_fma_f32 v[112:113], v[96:97], v[112:113], v[136:137]
	s_nop 0
	v_pk_fma_f32 v[112:113], v[92:93], v[138:139], v[112:113]
	v_lshlrev_b32_e32 v138, 16, v109
	v_mul_f32_e32 v119, 0xbfb8aa3b, v112
	v_exp_f32_e32 v119, v119
	v_and_b32_e32 v139, 0xffff0000, v109
	v_add_f32_e32 v119, 1.0, v119
	v_rcp_f32_e32 v136, v119
	v_mul_f32_e32 v119, 0xbfb8aa3b, v113
	v_exp_f32_e32 v119, v119
	s_nop 0
	v_add_f32_e32 v119, 1.0, v119
	v_rcp_f32_e32 v137, v119
	s_nop 0
	v_pk_mul_f32 v[112:113], v[112:113], v[136:137]
	v_lshlrev_b32_e32 v136, 16, v140
	v_and_b32_e32 v137, 0xffff0000, v140
	v_pk_mul_f32 v[60:61], v[60:61], v[112:113]
	v_lshlrev_b32_e32 v112, 16, v123
	v_and_b32_e32 v113, 0xffff0000, v123
	v_pk_fma_f32 v[136:137], v[102:103], v[136:137], v[106:107]
	v_cvt_pk_bf16_f32 v60, v60, v61
	v_pk_fma_f32 v[112:113], v[98:99], v[112:113], v[136:137]
	s_nop 0
	v_pk_fma_f32 v[112:113], v[94:95], v[138:139], v[112:113]
	s_nop 0
	v_mul_f32_e32 v119, 0xbfb8aa3b, v112
	v_exp_f32_e32 v119, v119
	s_nop 0
	v_add_f32_e32 v119, 1.0, v119
	v_rcp_f32_e32 v136, v119
	v_mul_f32_e32 v119, 0xbfb8aa3b, v113
	v_exp_f32_e32 v119, v119
	s_nop 0
	v_add_f32_e32 v119, 1.0, v119
	v_rcp_f32_e32 v137, v119
	s_nop 0
	v_pk_mul_f32 v[112:113], v[112:113], v[136:137]
	s_nop 0
	v_pk_mul_f32 v[62:63], v[62:63], v[112:113]
	s_nop 0
	v_cvt_pk_bf16_f32 v61, v62, v63
	s_nop 0
	v_mov_b32_dpp v113, v114 row_ror:2 row_mask:0xf bank_mask:0xf
	v_mov_b32_dpp v119, v115 row_ror:1 row_mask:0xf bank_mask:0xf
	v_mov_b32_dpp v63, v114 row_ror:1 row_mask:0xf bank_mask:0xf
	v_mov_b32_dpp v113, v110 row_shr:2 row_mask:0xf bank_mask:0xf
	v_lshlrev_b32_e32 v112, 16, v113
	v_mov_b32_dpp v63, v110 row_shr:1 row_mask:0xf bank_mask:0xf
	v_and_b32_e32 v113, 0xffff0000, v113
	v_lshlrev_b32_e32 v62, 16, v63
	v_and_b32_e32 v63, 0xffff0000, v63
	v_pk_fma_f32 v[112:113], v[68:69], v[112:113], v[84:85]
	v_lshlrev_b32_e32 v114, 16, v110
	v_and_b32_e32 v115, 0xffff0000, v110
	v_pk_fma_f32 v[62:63], v[76:77], v[62:63], v[112:113]
	v_mov_b32_dpp v119, v111 row_shr:1 row_mask:0xf bank_mask:0xf
	v_pk_fma_f32 v[62:63], v[80:81], v[114:115], v[62:63]
	v_lshlrev_b32_e32 v114, 16, v111
	v_mul_f32_e32 v112, 0xbfb8aa3b, v62
	v_mul_f32_e32 v113, 0xbfb8aa3b, v63
	v_exp_f32_e32 v112, v112
	v_exp_f32_e32 v113, v113
	v_and_b32_e32 v115, 0xffff0000, v111
	v_pk_mul_f32 v[44:45], v[44:45], v[118:119] op_sel_hi:[1,0]
	v_add_f32_e32 v112, 1.0, v112
	v_add_f32_e32 v113, 1.0, v113
	v_rcp_f32_e32 v112, v112
	v_rcp_f32_e32 v113, v113
	v_pk_mul_f32 v[46:47], v[46:47], v[118:119] op_sel_hi:[1,0]
	v_pk_mul_f32 v[40:41], v[40:41], v[118:119] op_sel_hi:[1,0]
	v_pk_mul_f32 v[42:43], v[42:43], v[118:119] op_sel_hi:[1,0]
	v_pk_mul_f32 v[62:63], v[62:63], v[112:113]
	v_lshlrev_b32_e32 v112, 16, v121
	v_and_b32_e32 v113, 0xffff0000, v121
	v_pk_mul_f32 v[56:57], v[56:57], v[62:63]
	v_lshlrev_b32_e32 v62, 16, v119
	v_and_b32_e32 v63, 0xffff0000, v119
	v_pk_fma_f32 v[112:113], v[70:71], v[112:113], v[86:87]
	s_nop 0
	v_pk_fma_f32 v[62:63], v[78:79], v[62:63], v[112:113]
	s_nop 0
	v_pk_fma_f32 v[62:63], v[82:83], v[114:115], v[62:63]
	s_nop 0
	v_mul_f32_e32 v112, 0xbfb8aa3b, v62
	v_mul_f32_e32 v113, 0xbfb8aa3b, v63
	v_exp_f32_e32 v112, v112
	v_exp_f32_e32 v113, v113
	v_add_f32_e32 v112, 1.0, v112
	v_add_f32_e32 v113, 1.0, v113
	v_rcp_f32_e32 v112, v112
	v_rcp_f32_e32 v113, v113
	s_nop 0
	v_pk_mul_f32 v[62:63], v[62:63], v[112:113]
	s_nop 0
	v_pk_mul_f32 v[58:59], v[58:59], v[62:63]
	v_cvt_pk_bf16_f32 v62, v56, v57
	v_cvt_pk_bf16_f32 v63, v58, v59
	v_lshl_add_u64 v[56:57], s[14:15], 0, v[134:135]
	s_nop 0
	v_lshl_add_u64 v[112:113], v[56:57], 0, v[176:177]
	s_nop 0
	v_mov_b32_dpp v59, v108 row_ror:2 row_mask:0xf bank_mask:0xf
	global_store_dwordx4 v[112:113], v[60:63], off
	v_mov_b32_dpp v57, v108 row_ror:1 row_mask:0xf bank_mask:0xf
	v_mov_b32_dpp v59, v88 row_shr:2 row_mask:0xf bank_mask:0xf
	v_lshlrev_b32_e32 v58, 16, v59
	v_mov_b32_dpp v57, v88 row_shr:1 row_mask:0xf bank_mask:0xf
	v_and_b32_e32 v59, 0xffff0000, v59
	v_lshlrev_b32_e32 v56, 16, v57
	v_and_b32_e32 v57, 0xffff0000, v57
	v_pk_fma_f32 v[58:59], v[100:101], v[58:59], v[104:105]
	v_lshlrev_b32_e32 v60, 16, v88
	v_and_b32_e32 v61, 0xffff0000, v88
	v_pk_fma_f32 v[56:57], v[96:97], v[56:57], v[58:59]
	s_nop 0
	v_pk_fma_f32 v[56:57], v[92:93], v[60:61], v[56:57]
	s_nop 0
	v_mul_f32_e32 v58, 0xbfb8aa3b, v56
	v_mul_f32_e32 v59, 0xbfb8aa3b, v57
	v_exp_f32_e32 v58, v58
	v_exp_f32_e32 v59, v59
	v_mov_b32_dpp v63, v109 row_ror:2 row_mask:0xf bank_mask:0xf
	v_mov_b32_dpp v62, v109 row_ror:1 row_mask:0xf bank_mask:0xf
	v_add_f32_e32 v58, 1.0, v58
	v_add_f32_e32 v59, 1.0, v59
	v_rcp_f32_e32 v58, v58
	v_rcp_f32_e32 v59, v59
	v_mov_b32_dpp v63, v89 row_shr:2 row_mask:0xf bank_mask:0xf
	v_mov_b32_dpp v62, v89 row_shr:1 row_mask:0xf bank_mask:0xf
	v_lshlrev_b32_e32 v60, 16, v89
	v_pk_mul_f32 v[56:57], v[56:57], v[58:59]
	v_lshlrev_b32_e32 v58, 16, v63
	v_and_b32_e32 v59, 0xffff0000, v63
	v_pk_mul_f32 v[52:53], v[52:53], v[56:57]
	v_lshlrev_b32_e32 v56, 16, v62
	v_and_b32_e32 v57, 0xffff0000, v62
	v_pk_fma_f32 v[58:59], v[102:103], v[58:59], v[106:107]
	v_and_b32_e32 v61, 0xffff0000, v89
	v_pk_fma_f32 v[56:57], v[98:99], v[56:57], v[58:59]
	v_cvt_pk_bf16_f32 v52, v52, v53
	v_pk_fma_f32 v[56:57], v[94:95], v[60:61], v[56:57]
	s_nop 0
	v_mul_f32_e32 v58, 0xbfb8aa3b, v56
	v_mul_f32_e32 v59, 0xbfb8aa3b, v57
	v_exp_f32_e32 v58, v58
	v_exp_f32_e32 v59, v59
	s_nop 0
	v_mov_b32_dpp v61, v111 row_ror:2 row_mask:0xf bank_mask:0xf
	v_add_f32_e32 v58, 1.0, v58
	v_add_f32_e32 v59, 1.0, v59
	v_rcp_f32_e32 v58, v58
	v_rcp_f32_e32 v59, v59
	v_mov_b32_dpp v60, v111 row_ror:1 row_mask:0xf bank_mask:0xf
	v_mov_b32_dpp v61, v91 row_shr:2 row_mask:0xf bank_mask:0xf
	v_pk_mul_f32 v[56:57], v[56:57], v[58:59]
	s_nop 0
	v_pk_mul_f32 v[54:55], v[54:55], v[56:57]
	s_nop 0
	v_cvt_pk_bf16_f32 v53, v54, v55
	s_nop 0
	v_mov_b32_dpp v57, v110 row_ror:2 row_mask:0xf bank_mask:0xf
	v_lshlrev_b32_e32 v58, 16, v90
	v_mov_b32_dpp v55, v110 row_ror:1 row_mask:0xf bank_mask:0xf
	v_mov_b32_dpp v57, v90 row_shr:2 row_mask:0xf bank_mask:0xf
	v_lshlrev_b32_e32 v56, 16, v57
	v_mov_b32_dpp v55, v90 row_shr:1 row_mask:0xf bank_mask:0xf
	v_and_b32_e32 v57, 0xffff0000, v57
	v_lshlrev_b32_e32 v54, 16, v55
	v_and_b32_e32 v55, 0xffff0000, v55
	v_pk_fma_f32 v[56:57], v[68:69], v[56:57], v[84:85]
	v_and_b32_e32 v59, 0xffff0000, v90
	v_pk_fma_f32 v[54:55], v[76:77], v[54:55], v[56:57]
	v_mov_b32_dpp v60, v91 row_shr:1 row_mask:0xf bank_mask:0xf
	v_pk_fma_f32 v[54:55], v[80:81], v[58:59], v[54:55]
	v_lshlrev_b32_e32 v58, 16, v91
	v_mul_f32_e32 v56, 0xbfb8aa3b, v54
	v_mul_f32_e32 v57, 0xbfb8aa3b, v55
	v_exp_f32_e32 v56, v56
	v_exp_f32_e32 v57, v57
	v_and_b32_e32 v59, 0xffff0000, v91
	v_add_f32_e32 v56, 1.0, v56
	v_add_f32_e32 v57, 1.0, v57
	v_rcp_f32_e32 v56, v56
	v_rcp_f32_e32 v57, v57
	s_nop 0
	v_pk_mul_f32 v[54:55], v[54:55], v[56:57]
	v_lshlrev_b32_e32 v56, 16, v61
	v_and_b32_e32 v57, 0xffff0000, v61
	v_pk_mul_f32 v[48:49], v[48:49], v[54:55]
	v_lshlrev_b32_e32 v54, 16, v60
	v_and_b32_e32 v55, 0xffff0000, v60
	v_pk_fma_f32 v[56:57], v[70:71], v[56:57], v[86:87]
	s_nop 0
	v_pk_fma_f32 v[54:55], v[78:79], v[54:55], v[56:57]
	s_nop 0
	v_pk_fma_f32 v[54:55], v[82:83], v[58:59], v[54:55]
	s_nop 0
	v_mul_f32_e32 v56, 0xbfb8aa3b, v54
	v_mul_f32_e32 v57, 0xbfb8aa3b, v55
	v_exp_f32_e32 v56, v56
	v_exp_f32_e32 v57, v57
	v_add_f32_e32 v56, 1.0, v56
	v_add_f32_e32 v57, 1.0, v57
	v_rcp_f32_e32 v56, v56
	v_rcp_f32_e32 v57, v57
	s_nop 0
	v_pk_mul_f32 v[54:55], v[54:55], v[56:57]
	s_nop 0
	v_pk_mul_f32 v[50:51], v[50:51], v[54:55]
	v_cvt_pk_bf16_f32 v54, v48, v49
	v_cvt_pk_bf16_f32 v55, v50, v51
	v_lshl_add_u64 v[48:49], s[14:15], 0, v[132:133]
	s_nop 0
	v_lshl_add_u64 v[108:109], v[48:49], 0, v[176:177]
	s_nop 0
	v_mov_b32_dpp v51, v88 row_ror:2 row_mask:0xf bank_mask:0xf
	global_store_dwordx4 v[108:109], v[52:55], off
	v_mov_b32_dpp v49, v88 row_ror:1 row_mask:0xf bank_mask:0xf
	v_mov_b32_dpp v51, v72 row_shr:2 row_mask:0xf bank_mask:0xf
	v_lshlrev_b32_e32 v50, 16, v51
	v_mov_b32_dpp v49, v72 row_shr:1 row_mask:0xf bank_mask:0xf
	v_and_b32_e32 v51, 0xffff0000, v51
	v_lshlrev_b32_e32 v48, 16, v49
	v_and_b32_e32 v49, 0xffff0000, v49
	v_pk_fma_f32 v[50:51], v[100:101], v[50:51], v[104:105]
	v_lshlrev_b32_e32 v52, 16, v72
	v_and_b32_e32 v53, 0xffff0000, v72
	v_pk_fma_f32 v[48:49], v[96:97], v[48:49], v[50:51]
	s_nop 0
	v_pk_fma_f32 v[48:49], v[92:93], v[52:53], v[48:49]
	s_nop 0
	v_mul_f32_e32 v50, 0xbfb8aa3b, v48
	v_mul_f32_e32 v51, 0xbfb8aa3b, v49
	v_exp_f32_e32 v50, v50
	v_exp_f32_e32 v51, v51
	v_mov_b32_dpp v55, v89 row_ror:2 row_mask:0xf bank_mask:0xf
	v_mov_b32_dpp v54, v89 row_ror:1 row_mask:0xf bank_mask:0xf
	v_add_f32_e32 v50, 1.0, v50
	v_add_f32_e32 v51, 1.0, v51
	v_rcp_f32_e32 v50, v50
	v_rcp_f32_e32 v51, v51
	v_mov_b32_dpp v55, v73 row_shr:2 row_mask:0xf bank_mask:0xf
	v_mov_b32_dpp v54, v73 row_shr:1 row_mask:0xf bank_mask:0xf
	v_lshlrev_b32_e32 v52, 16, v73
	v_pk_mul_f32 v[48:49], v[48:49], v[50:51]
	v_lshlrev_b32_e32 v50, 16, v55
	v_and_b32_e32 v51, 0xffff0000, v55
	v_pk_mul_f32 v[44:45], v[44:45], v[48:49]
	v_lshlrev_b32_e32 v48, 16, v54
	v_and_b32_e32 v49, 0xffff0000, v54
	v_pk_fma_f32 v[50:51], v[102:103], v[50:51], v[106:107]
	v_and_b32_e32 v53, 0xffff0000, v73
	v_pk_fma_f32 v[48:49], v[98:99], v[48:49], v[50:51]
	v_cvt_pk_bf16_f32 v44, v44, v45
	v_pk_fma_f32 v[48:49], v[94:95], v[52:53], v[48:49]
	s_nop 0
	v_mul_f32_e32 v50, 0xbfb8aa3b, v48
	v_mul_f32_e32 v51, 0xbfb8aa3b, v49
	v_exp_f32_e32 v50, v50
	v_exp_f32_e32 v51, v51
	s_nop 0
	v_mov_b32_dpp v53, v91 row_ror:2 row_mask:0xf bank_mask:0xf
	v_add_f32_e32 v50, 1.0, v50
	v_add_f32_e32 v51, 1.0, v51
	v_rcp_f32_e32 v50, v50
	v_rcp_f32_e32 v51, v51
	v_mov_b32_dpp v52, v91 row_ror:1 row_mask:0xf bank_mask:0xf
	v_mov_b32_dpp v53, v75 row_shr:2 row_mask:0xf bank_mask:0xf
	v_pk_mul_f32 v[48:49], v[48:49], v[50:51]
	s_nop 0
	v_pk_mul_f32 v[46:47], v[46:47], v[48:49]
	s_nop 0
	v_cvt_pk_bf16_f32 v45, v46, v47
	s_nop 0
	v_mov_b32_dpp v49, v90 row_ror:2 row_mask:0xf bank_mask:0xf
	v_lshlrev_b32_e32 v50, 16, v74
	v_mov_b32_dpp v47, v90 row_ror:1 row_mask:0xf bank_mask:0xf
	v_mov_b32_dpp v49, v74 row_shr:2 row_mask:0xf bank_mask:0xf
	v_lshlrev_b32_e32 v48, 16, v49
	v_mov_b32_dpp v47, v74 row_shr:1 row_mask:0xf bank_mask:0xf
	v_and_b32_e32 v49, 0xffff0000, v49
	v_lshlrev_b32_e32 v46, 16, v47
	v_and_b32_e32 v47, 0xffff0000, v47
	v_pk_fma_f32 v[48:49], v[68:69], v[48:49], v[84:85]
	v_and_b32_e32 v51, 0xffff0000, v74
	v_pk_fma_f32 v[46:47], v[76:77], v[46:47], v[48:49]
	v_mov_b32_dpp v52, v75 row_shr:1 row_mask:0xf bank_mask:0xf
	v_pk_fma_f32 v[46:47], v[80:81], v[50:51], v[46:47]
	v_lshlrev_b32_e32 v50, 16, v75
	v_mul_f32_e32 v48, 0xbfb8aa3b, v46
	v_mul_f32_e32 v49, 0xbfb8aa3b, v47
	v_exp_f32_e32 v48, v48
	v_exp_f32_e32 v49, v49
	v_and_b32_e32 v51, 0xffff0000, v75
	v_add_f32_e32 v48, 1.0, v48
	v_add_f32_e32 v49, 1.0, v49
	v_rcp_f32_e32 v48, v48
	v_rcp_f32_e32 v49, v49
	s_nop 0
	v_pk_mul_f32 v[46:47], v[46:47], v[48:49]
	v_lshlrev_b32_e32 v48, 16, v53
	v_and_b32_e32 v49, 0xffff0000, v53
	v_pk_mul_f32 v[40:41], v[40:41], v[46:47]
	v_lshlrev_b32_e32 v46, 16, v52
	v_and_b32_e32 v47, 0xffff0000, v52
	v_pk_fma_f32 v[48:49], v[70:71], v[48:49], v[86:87]
	s_nop 0
	v_pk_fma_f32 v[46:47], v[78:79], v[46:47], v[48:49]
	s_nop 0
	v_pk_fma_f32 v[46:47], v[82:83], v[50:51], v[46:47]
	s_nop 0
	v_mul_f32_e32 v48, 0xbfb8aa3b, v46
	v_mul_f32_e32 v49, 0xbfb8aa3b, v47
	v_exp_f32_e32 v48, v48
	v_exp_f32_e32 v49, v49
	s_nop 0
	v_mov_b32_dpp v51, v74 row_ror:2 row_mask:0xf bank_mask:0xf
	v_add_f32_e32 v48, 1.0, v48
	v_add_f32_e32 v49, 1.0, v49
	v_rcp_f32_e32 v48, v48
	v_rcp_f32_e32 v49, v49
	v_mov_b32_dpp v50, v74 row_ror:1 row_mask:0xf bank_mask:0xf
	v_mov_b32_dpp v51, v66 row_shr:2 row_mask:0xf bank_mask:0xf
	v_mov_b32_dpp v53, v75 row_ror:2 row_mask:0xf bank_mask:0xf
	v_pk_mul_f32 v[46:47], v[46:47], v[48:49]
	s_nop 0
	v_pk_mul_f32 v[42:43], v[42:43], v[46:47]
	v_cvt_pk_bf16_f32 v46, v40, v41
	v_cvt_pk_bf16_f32 v47, v42, v43
	v_lshl_add_u64 v[40:41], s[14:15], 0, v[130:131]
	s_nop 0
	v_lshl_add_u64 v[88:89], v[40:41], 0, v[176:177]
	s_nop 0
	v_mov_b32_dpp v42, v72 row_ror:2 row_mask:0xf bank_mask:0xf
	global_store_dwordx4 v[88:89], v[44:47], off
	v_mov_b32_dpp v40, v72 row_ror:1 row_mask:0xf bank_mask:0xf
	v_mov_b32_dpp v42, v64 row_shr:2 row_mask:0xf bank_mask:0xf
	v_lshlrev_b32_e32 v44, 16, v42
	v_mov_b32_dpp v40, v64 row_shr:1 row_mask:0xf bank_mask:0xf
	v_and_b32_e32 v45, 0xffff0000, v42
	v_lshlrev_b32_e32 v46, 16, v40
	v_and_b32_e32 v47, 0xffff0000, v40
	v_pk_fma_f32 v[44:45], v[100:101], v[44:45], v[104:105]
	s_nop 0
	v_pk_fma_f32 v[44:45], v[96:97], v[46:47], v[44:45]
	v_lshlrev_b32_e32 v46, 16, v64
	v_and_b32_e32 v47, 0xffff0000, v64
	v_pk_fma_f32 v[44:45], v[92:93], v[46:47], v[44:45]
	v_mov_b32_dpp v49, v73 row_ror:2 row_mask:0xf bank_mask:0xf
	v_mul_f32_e32 v40, 0xbfb8aa3b, v44
	v_exp_f32_e32 v40, v40
	v_mov_b32_dpp v48, v73 row_ror:1 row_mask:0xf bank_mask:0xf
	v_mov_b32_dpp v49, v65 row_shr:2 row_mask:0xf bank_mask:0xf
	v_mov_b32_dpp v50, v66 row_shr:1 row_mask:0xf bank_mask:0xf
	v_add_f32_e32 v40, 1.0, v40
	v_rcp_f32_e32 v46, v40
	v_mul_f32_e32 v40, 0xbfb8aa3b, v45
	v_exp_f32_e32 v40, v40
	v_mov_b32_dpp v48, v65 row_shr:1 row_mask:0xf bank_mask:0xf
	v_mov_b32_dpp v52, v75 row_ror:1 row_mask:0xf bank_mask:0xf
	v_mov_b32_dpp v53, v67 row_shr:2 row_mask:0xf bank_mask:0xf
	v_add_f32_e32 v40, 1.0, v40
	v_rcp_f32_e32 v47, v40
	v_mov_b32_dpp v52, v67 row_shr:1 row_mask:0xf bank_mask:0xf
	v_and_b32_e32 v41, 0xffff0000, v53
	v_and_b32_e32 v43, 0xffff0000, v52
	v_pk_mul_f32 v[44:45], v[44:45], v[46:47]
	v_lshlrev_b32_e32 v46, 16, v48
	v_pk_mul_f32 v[36:37], v[36:37], v[44:45]
	v_lshlrev_b32_e32 v44, 16, v49
	v_and_b32_e32 v45, 0xffff0000, v49
	v_and_b32_e32 v47, 0xffff0000, v48
	v_pk_fma_f32 v[44:45], v[102:103], v[44:45], v[106:107]
	v_lshlrev_b32_e32 v42, 16, v52
	v_pk_fma_f32 v[44:45], v[98:99], v[46:47], v[44:45]
	v_lshlrev_b32_e32 v46, 16, v65
	v_and_b32_e32 v47, 0xffff0000, v65
	v_pk_fma_f32 v[44:45], v[94:95], v[46:47], v[44:45]
	s_nop 0
	v_mul_f32_e32 v40, 0xbfb8aa3b, v44
	v_exp_f32_e32 v40, v40
	s_nop 0
	v_add_f32_e32 v40, 1.0, v40
	v_rcp_f32_e32 v46, v40
	v_mul_f32_e32 v40, 0xbfb8aa3b, v45
	v_exp_f32_e32 v40, v40
	s_nop 0
	v_add_f32_e32 v40, 1.0, v40
	v_rcp_f32_e32 v47, v40
	s_nop 0
	v_pk_mul_f32 v[44:45], v[44:45], v[46:47]
	s_nop 0
	v_pk_mul_f32 v[38:39], v[38:39], v[44:45]
	v_lshlrev_b32_e32 v44, 16, v51
	v_and_b32_e32 v45, 0xffff0000, v51
	v_lshlrev_b32_e32 v46, 16, v50
	v_and_b32_e32 v47, 0xffff0000, v50
	v_pk_fma_f32 v[44:45], v[68:69], v[44:45], v[84:85]
	s_nop 0
	v_pk_fma_f32 v[44:45], v[76:77], v[46:47], v[44:45]
	v_lshlrev_b32_e32 v46, 16, v66
	v_and_b32_e32 v47, 0xffff0000, v66
	v_pk_fma_f32 v[44:45], v[80:81], v[46:47], v[44:45]
	s_nop 0
	v_mul_f32_e32 v40, 0xbfb8aa3b, v44
	v_exp_f32_e32 v40, v40
	s_nop 0
	v_add_f32_e32 v40, 1.0, v40
	v_rcp_f32_e32 v46, v40
	v_mul_f32_e32 v40, 0xbfb8aa3b, v45
	v_exp_f32_e32 v40, v40
	s_nop 0
	v_add_f32_e32 v40, 1.0, v40
	v_rcp_f32_e32 v47, v40
	v_lshlrev_b32_e32 v40, 16, v53
	v_pk_mul_f32 v[44:45], v[44:45], v[46:47]
	s_nop 0
	v_pk_mul_f32 v[44:45], v[32:33], v[44:45]
	v_cvt_pk_bf16_f32 v33, v38, v39
	v_pk_fma_f32 v[38:39], v[70:71], v[40:41], v[86:87]
	v_cvt_pk_bf16_f32 v32, v36, v37
	v_lshlrev_b32_e32 v36, 16, v67
	v_and_b32_e32 v37, 0xffff0000, v67
	v_pk_fma_f32 v[38:39], v[78:79], v[42:43], v[38:39]
	s_nop 0
	v_pk_fma_f32 v[36:37], v[82:83], v[36:37], v[38:39]
	s_nop 0
	v_mul_f32_e32 v38, 0xbfb8aa3b, v36
	v_mul_f32_e32 v39, 0xbfb8aa3b, v37
	v_exp_f32_e32 v38, v38
	v_exp_f32_e32 v39, v39
	v_add_f32_e32 v38, 1.0, v38
	v_add_f32_e32 v39, 1.0, v39
	v_rcp_f32_e32 v38, v38
	v_rcp_f32_e32 v39, v39
	s_nop 0
	v_pk_mul_f32 v[36:37], v[36:37], v[38:39]
	s_nop 0
	v_pk_mul_f32 v[36:37], v[34:35], v[36:37]
	v_cvt_pk_bf16_f32 v34, v44, v45
	v_cvt_pk_bf16_f32 v35, v36, v37
	v_lshl_add_u64 v[36:37], s[14:15], 0, v[128:129]
	v_lshl_add_u64 v[84:85], v[36:37], 0, v[176:177]
	global_store_dwordx4 v[84:85], v[32:35], off
	s_nop 1
	v_lshl_add_u64 v[32:33], s[12:13], 0, v[134:135]
	v_lshl_add_u64 v[32:33], v[32:33], 0, v[148:149]
	global_load_dwordx4 v[76:79], v[32:33], off
	v_lshl_add_u64 v[32:33], s[12:13], 0, v[132:133]
	v_lshl_add_u64 v[32:33], v[32:33], 0, v[148:149]
	global_load_dwordx4 v[72:75], v[32:33], off
	v_lshl_add_u64 v[32:33], s[12:13], 0, v[130:131]
	v_lshl_add_u64 v[32:33], v[32:33], 0, v[148:149]
	global_load_dwordx4 v[36:39], v[32:33], off
	v_lshl_add_u64 v[32:33], s[12:13], 0, v[128:129]
	v_lshl_add_u64 v[32:33], v[32:33], 0, v[148:149]
	global_load_dwordx4 v[32:35], v[32:33], off
	s_and_saveexec_b64 s[4:5], vcc
	s_xor_b64 s[4:5], exec, s[4:5]
	s_cbranch_execz .LBB0_996
	v_mov_b32_e32 v83, 0
	v_mov_b32_e32 v82, 0
	v_mov_b32_e32 v81, 0
	v_mov_b32_e32 v80, 0
	s_and_saveexec_b64 s[6:7], s[0:1]
	s_cbranch_execz .LBB0_995
	v_readlane_b32 s72, v254, 11
	v_lshlrev_b32_e32 v40, 2, v117
	v_readlane_b32 s73, v254, 12
	s_nop 4
	global_load_dword v48, v40, s[72:73]
	v_readlane_b32 s72, v254, 19
	v_readlane_b32 s73, v254, 20
	s_waitcnt vmcnt(0)
	v_fmamk_f32 v48, v48, 0x3a800000, v241
	v_lshl_add_u64 v[40:41], s[72:73], 0, v[124:125]
	v_lshl_add_u64 v[44:45], v[198:199], 2, v[40:41]
	global_load_dwordx4 v[40:43], v[44:45], off offset:512
	s_nop 0
	global_load_dwordx4 v[44:47], v[44:45], off offset:528
	v_mul_f32_e32 v49, 0x4b800000, v48
	v_cmp_gt_f32_e32 vcc, s77, v48
	s_nop 1
	v_cndmask_b32_e32 v48, v48, v49, vcc
	v_rsq_f32_e32 v48, v48
	s_nop 0
	v_mul_f32_e32 v49, 0x45800000, v48
	v_cndmask_b32_e32 v48, v48, v49, vcc
	s_waitcnt vmcnt(1)
	v_pk_mul_f32 v[40:41], v[40:41], v[48:49] op_sel_hi:[1,0]
	v_pk_mul_f32 v[42:43], v[42:43], v[48:49] op_sel_hi:[1,0]
	s_waitcnt vmcnt(0)
	v_pk_mul_f32 v[44:45], v[44:45], v[48:49] op_sel_hi:[1,0]
	v_pk_mul_f32 v[46:47], v[48:49], v[46:47] op_sel_hi:[0,1]
	v_cvt_pk_bf16_f32 v80, v40, v41
	v_cvt_pk_bf16_f32 v81, v42, v43
	v_cvt_pk_bf16_f32 v82, v44, v45
	v_cvt_pk_bf16_f32 v83, v46, v47

.LBB0_998:
	s_or_b64 exec, exec, s[4:5]
	global_load_dwordx4 v[60:63], v[202:203], off offset:512
	global_load_dwordx4 v[64:67], v[200:201], off offset:512
	global_load_dwordx4 v[40:43], v[200:201], off offset:528
	global_load_dwordx4 v[44:47], v[202:203], off offset:528
	global_load_dwordx4 v[68:71], v[150:151], off
	global_load_dwordx4 v[48:51], v[150:151], off offset:16
	global_load_dwordx4 v[56:59], v[152:153], off
	global_load_dwordx4 v[52:55], v[152:153], off offset:16
	s_nop 0
	s_nop 0
	s_nop 0
	s_nop 0
	s_nop 0
	s_waitcnt vmcnt(8)
	v_mov_b32_dpp v94, v80 row_ror:1 row_mask:0xf bank_mask:0xf
	v_mov_b32_dpp v95, v80 row_ror:2 row_mask:0xf bank_mask:0xf
	v_mov_b32_dpp v97, v81 row_ror:1 row_mask:0xf bank_mask:0xf
	v_mov_b32_dpp v98, v81 row_ror:2 row_mask:0xf bank_mask:0xf
	v_mov_b32_e32 v123, v122
	s_nop 0
	s_nop 0
	s_nop 0
	v_mov_b32_dpp v101, v82 row_ror:2 row_mask:0xf bank_mask:0xf
	v_mov_b32_dpp v94, v76 row_shr:1 row_mask:0xf bank_mask:0xf
	v_mov_b32_dpp v95, v76 row_shr:2 row_mask:0xf bank_mask:0xf
	v_mov_b32_dpp v97, v77 row_shr:1 row_mask:0xf bank_mask:0xf
	v_mov_b32_dpp v98, v77 row_shr:2 row_mask:0xf bank_mask:0xf
	v_mov_b32_dpp v99, v82 row_ror:1 row_mask:0xf bank_mask:0xf
	v_mov_b32_dpp v103, v83 row_ror:1 row_mask:0xf bank_mask:0xf
	v_mov_b32_dpp v104, v83 row_ror:2 row_mask:0xf bank_mask:0xf
	v_pk_mul_f32 v[80:81], v[24:25], v[122:123]
	v_mov_b32_dpp v101, v78 row_shr:2 row_mask:0xf bank_mask:0xf
	v_lshlrev_b32_e32 v24, 16, v94
	v_lshlrev_b32_e32 v82, 16, v95
	v_and_b32_e32 v25, 0xffff0000, v94
	v_and_b32_e32 v83, 0xffff0000, v95
	v_lshlrev_b32_e32 v94, 16, v97
	v_lshlrev_b32_e32 v96, 16, v98
	v_and_b32_e32 v95, 0xffff0000, v97
	v_and_b32_e32 v97, 0xffff0000, v98
	v_mov_b32_dpp v99, v78 row_shr:1 row_mask:0xf bank_mask:0xf
	v_lshlrev_b32_e32 v100, 16, v101
	v_and_b32_e32 v101, 0xffff0000, v101
	v_lshlrev_b32_e32 v86, 16, v76
	v_and_b32_e32 v87, 0xffff0000, v76
	v_lshlrev_b32_e32 v90, 16, v77
	v_and_b32_e32 v91, 0xffff0000, v77
	v_lshlrev_b32_e32 v98, 16, v99
	v_and_b32_e32 v99, 0xffff0000, v99
	v_lshlrev_b32_e32 v92, 16, v78
	v_and_b32_e32 v93, 0xffff0000, v78
	v_pk_mul_f32 v[28:29], v[28:29], v[122:123]
	v_pk_mul_f32 v[30:31], v[30:31], v[122:123]
	v_mov_b32_dpp v104, v79 row_shr:2 row_mask:0xf bank_mask:0xf
	v_mov_b32_dpp v103, v79 row_shr:1 row_mask:0xf bank_mask:0xf
	v_lshlrev_b32_e32 v102, 16, v103
	v_and_b32_e32 v103, 0xffff0000, v103
	v_pk_mul_f32 v[26:27], v[26:27], v[122:123]
	v_mov_b32_e32 v121, v120
	v_pk_mul_f32 v[20:21], v[20:21], v[120:121]
	v_pk_mul_f32 v[22:23], v[22:23], v[120:121]
	v_pk_mul_f32 v[16:17], v[16:17], v[120:121]
	v_pk_mul_f32 v[18:19], v[18:19], v[120:121]
	v_mov_b32_e32 v119, v118
	v_pk_mul_f32 v[12:13], v[12:13], v[118:119]
	v_pk_mul_f32 v[14:15], v[14:15], v[118:119]
	v_pk_mul_f32 v[8:9], v[8:9], v[118:119]
	v_pk_mul_f32 v[10:11], v[10:11], v[118:119]
	v_mov_b32_e32 v117, v116
	v_pk_mul_f32 v[4:5], v[4:5], v[116:117]
	v_pk_mul_f32 v[6:7], v[6:7], v[116:117]
	v_pk_mul_f32 v[0:1], v[0:1], v[116:117]
	v_pk_mul_f32 v[2:3], v[2:3], v[116:117]
	s_andn2_b64 vcc, exec, s[2:3]
	s_mov_b64 s[2:3], -1
	s_waitcnt vmcnt(6)
	v_pk_fma_f32 v[82:83], v[64:65], v[82:83], v[60:61]
	v_pk_fma_f32 v[96:97], v[66:67], v[96:97], v[62:63]
	s_waitcnt vmcnt(4)
	v_pk_fma_f32 v[100:101], v[40:41], v[100:101], v[44:45]
	s_waitcnt vmcnt(3)
	v_pk_fma_f32 v[24:25], v[68:69], v[24:25], v[82:83]
	v_pk_fma_f32 v[82:83], v[70:71], v[94:95], v[96:97]
	s_waitcnt vmcnt(2)
	v_pk_fma_f32 v[94:95], v[48:49], v[98:99], v[100:101]
	s_waitcnt vmcnt(1)
	v_pk_fma_f32 v[24:25], v[56:57], v[86:87], v[24:25]
	v_pk_fma_f32 v[82:83], v[58:59], v[90:91], v[82:83]
	s_waitcnt vmcnt(0)
	v_pk_fma_f32 v[86:87], v[52:53], v[92:93], v[94:95]
	v_mul_f32_e32 v90, 0xbfb8aa3b, v24
	v_mul_f32_e32 v91, 0xbfb8aa3b, v25
	v_mul_f32_e32 v92, 0xbfb8aa3b, v82
	v_mul_f32_e32 v93, 0xbfb8aa3b, v83
	v_exp_f32_e32 v90, v90
	v_exp_f32_e32 v91, v91
	v_exp_f32_e32 v92, v92
	v_exp_f32_e32 v93, v93
	v_add_f32_e32 v90, 1.0, v90
	v_add_f32_e32 v91, 1.0, v91
	v_add_f32_e32 v92, 1.0, v92
	v_add_f32_e32 v93, 1.0, v93
	v_rcp_f32_e32 v90, v90
	v_rcp_f32_e32 v91, v91
	v_rcp_f32_e32 v92, v92
	v_rcp_f32_e32 v93, v93
	v_mul_f32_e32 v94, 0xbfb8aa3b, v86
	v_pk_mul_f32 v[24:25], v[24:25], v[90:91]
	v_mul_f32_e32 v95, 0xbfb8aa3b, v87
	v_pk_mul_f32 v[82:83], v[82:83], v[92:93]
	v_pk_mul_f32 v[24:25], v[28:29], v[24:25]
	v_pk_mul_f32 v[28:29], v[30:31], v[82:83]
	v_cvt_pk_bf16_f32 v24, v24, v25
	v_cvt_pk_bf16_f32 v25, v28, v29
	v_lshlrev_b32_e32 v28, 16, v104
	v_and_b32_e32 v29, 0xffff0000, v104
	v_pk_fma_f32 v[28:29], v[42:43], v[28:29], v[46:47]
	v_lshlrev_b32_e32 v30, 16, v79
	v_and_b32_e32 v31, 0xffff0000, v79
	v_pk_fma_f32 v[28:29], v[50:51], v[102:103], v[28:29]
	v_exp_f32_e32 v94, v94
	v_pk_fma_f32 v[28:29], v[54:55], v[30:31], v[28:29]
	v_exp_f32_e32 v95, v95
	v_mul_f32_e32 v30, 0xbfb8aa3b, v28
	v_mul_f32_e32 v31, 0xbfb8aa3b, v29
	v_exp_f32_e32 v30, v30
	v_exp_f32_e32 v31, v31
	v_add_f32_e32 v94, 1.0, v94
	v_add_f32_e32 v95, 1.0, v95
	v_add_f32_e32 v30, 1.0, v30
	v_add_f32_e32 v31, 1.0, v31
	v_rcp_f32_e32 v94, v94
	v_rcp_f32_e32 v95, v95
	v_rcp_f32_e32 v30, v30
	v_rcp_f32_e32 v31, v31
	v_pk_mul_f32 v[82:83], v[86:87], v[94:95]
	s_nop 0
	v_pk_mul_f32 v[80:81], v[80:81], v[82:83]
	v_pk_mul_f32 v[28:29], v[28:29], v[30:31]
	s_nop 0
	v_pk_mul_f32 v[28:29], v[26:27], v[28:29]
	v_cvt_pk_bf16_f32 v26, v80, v81
	v_cvt_pk_bf16_f32 v27, v28, v29
	global_store_dwordx4 v[112:113], v[24:27], off offset:256
	v_mov_b32_dpp v31, v77 row_ror:1 row_mask:0xf bank_mask:0xf
	v_lshlrev_b32_e32 v28, 16, v72
	s_nop 0
	s_nop 0
	v_mov_b32_dpp v31, v73 row_shr:1 row_mask:0xf bank_mask:0xf
	v_mov_b32_dpp v27, v76 row_ror:2 row_mask:0xf bank_mask:0xf
	v_mov_b32_dpp v25, v76 row_ror:1 row_mask:0xf bank_mask:0xf
	s_nop 0
	v_mov_b32_dpp v27, v72 row_shr:2 row_mask:0xf bank_mask:0xf
	v_mov_b32_dpp v25, v72 row_shr:1 row_mask:0xf bank_mask:0xf
	v_lshlrev_b32_e32 v26, 16, v27
	v_and_b32_e32 v27, 0xffff0000, v27
	v_mov_b32_dpp v76, v77 row_ror:2 row_mask:0xf bank_mask:0xf
	v_lshlrev_b32_e32 v24, 16, v25
	v_and_b32_e32 v25, 0xffff0000, v25
	v_pk_fma_f32 v[26:27], v[64:65], v[26:27], v[60:61]
	v_and_b32_e32 v29, 0xffff0000, v72
	v_pk_fma_f32 v[24:25], v[68:69], v[24:25], v[26:27]
	v_mov_b32_dpp v76, v73 row_shr:2 row_mask:0xf bank_mask:0xf
	v_pk_fma_f32 v[24:25], v[56:57], v[28:29], v[24:25]
	v_lshlrev_b32_e32 v28, 16, v31
	v_lshlrev_b32_e32 v30, 16, v76
	v_and_b32_e32 v29, 0xffff0000, v31
	v_and_b32_e32 v31, 0xffff0000, v76
	v_pk_fma_f32 v[30:31], v[66:67], v[30:31], v[62:63]
	v_lshlrev_b32_e32 v76, 16, v73
	v_and_b32_e32 v77, 0xffff0000, v73
	v_pk_fma_f32 v[28:29], v[70:71], v[28:29], v[30:31]
	v_mul_f32_e32 v26, 0xbfb8aa3b, v24
	v_mul_f32_e32 v27, 0xbfb8aa3b, v25
	v_pk_fma_f32 v[28:29], v[58:59], v[76:77], v[28:29]
	v_exp_f32_e32 v26, v26
	v_exp_f32_e32 v27, v27
	v_mul_f32_e32 v30, 0xbfb8aa3b, v28
	v_mul_f32_e32 v31, 0xbfb8aa3b, v29
	v_exp_f32_e32 v30, v30
	v_exp_f32_e32 v31, v31
	v_add_f32_e32 v26, 1.0, v26
	v_add_f32_e32 v27, 1.0, v27
	v_rcp_f32_e32 v26, v26
	v_rcp_f32_e32 v27, v27
	v_add_f32_e32 v30, 1.0, v30
	v_add_f32_e32 v31, 1.0, v31
	v_rcp_f32_e32 v30, v30
	v_rcp_f32_e32 v31, v31
	v_pk_mul_f32 v[24:25], v[24:25], v[26:27]
	v_lshlrev_b32_e32 v26, 16, v74
	v_pk_mul_f32 v[20:21], v[20:21], v[24:25]
	v_pk_mul_f32 v[24:25], v[28:29], v[30:31]
	v_cvt_pk_bf16_f32 v20, v20, v21
	v_pk_mul_f32 v[22:23], v[22:23], v[24:25]
	s_nop 0
	v_cvt_pk_bf16_f32 v21, v22, v23
	s_nop 0
	v_mov_b32_dpp v25, v78 row_ror:2 row_mask:0xf bank_mask:0xf
	s_nop 0
	v_mov_b32_dpp v23, v78 row_ror:1 row_mask:0xf bank_mask:0xf
	v_mov_b32_dpp v25, v74 row_shr:2 row_mask:0xf bank_mask:0xf
	s_nop 0
	v_mov_b32_dpp v23, v74 row_shr:1 row_mask:0xf bank_mask:0xf
	v_lshlrev_b32_e32 v24, 16, v25
	v_and_b32_e32 v25, 0xffff0000, v25
	v_mov_b32_dpp v29, v79 row_ror:1 row_mask:0xf bank_mask:0xf
	v_mov_b32_dpp v30, v79 row_ror:2 row_mask:0xf bank_mask:0xf
	v_lshlrev_b32_e32 v22, 16, v23
	v_and_b32_e32 v23, 0xffff0000, v23
	v_pk_fma_f32 v[24:25], v[40:41], v[24:25], v[44:45]
	v_mov_b32_dpp v29, v75 row_shr:1 row_mask:0xf bank_mask:0xf
	v_and_b32_e32 v27, 0xffff0000, v74
	v_pk_fma_f32 v[22:23], v[48:49], v[22:23], v[24:25]
	v_mov_b32_dpp v30, v75 row_shr:2 row_mask:0xf bank_mask:0xf
	v_pk_fma_f32 v[22:23], v[52:53], v[26:27], v[22:23]
	v_lshlrev_b32_e32 v26, 16, v29
	v_lshlrev_b32_e32 v28, 16, v30
	v_and_b32_e32 v27, 0xffff0000, v29
	v_and_b32_e32 v29, 0xffff0000, v30
	v_pk_fma_f32 v[28:29], v[42:43], v[28:29], v[46:47]
	v_lshlrev_b32_e32 v30, 16, v75
	v_and_b32_e32 v31, 0xffff0000, v75
	v_pk_fma_f32 v[26:27], v[50:51], v[26:27], v[28:29]
	v_mul_f32_e32 v24, 0xbfb8aa3b, v22
	v_mul_f32_e32 v25, 0xbfb8aa3b, v23
	v_pk_fma_f32 v[26:27], v[54:55], v[30:31], v[26:27]
	v_exp_f32_e32 v24, v24
	v_exp_f32_e32 v25, v25
	v_mul_f32_e32 v28, 0xbfb8aa3b, v26
	v_mul_f32_e32 v29, 0xbfb8aa3b, v27
	v_exp_f32_e32 v28, v28
	v_exp_f32_e32 v29, v29
	v_add_f32_e32 v24, 1.0, v24
	v_add_f32_e32 v25, 1.0, v25
	v_rcp_f32_e32 v24, v24
	v_rcp_f32_e32 v25, v25
	v_add_f32_e32 v28, 1.0, v28
	v_add_f32_e32 v29, 1.0, v29
	v_rcp_f32_e32 v28, v28
	v_rcp_f32_e32 v29, v29
	v_pk_mul_f32 v[22:23], v[22:23], v[24:25]
	s_nop 0
	v_pk_mul_f32 v[16:17], v[16:17], v[22:23]
	v_pk_mul_f32 v[22:23], v[26:27], v[28:29]
	v_mov_b32_dpp v24, v73 row_ror:2 row_mask:0xf bank_mask:0xf
	v_pk_mul_f32 v[18:19], v[18:19], v[22:23]
	v_cvt_pk_bf16_f32 v22, v16, v17
	v_cvt_pk_bf16_f32 v23, v18, v19
	s_nop 0
	s_nop 0
	global_store_dwordx4 v[108:109], v[20:23], off offset:256
	v_mov_b32_dpp v19, v72 row_ror:2 row_mask:0xf bank_mask:0xf
	v_mov_b32_dpp v17, v72 row_ror:1 row_mask:0xf bank_mask:0xf
	s_nop 0
	v_mov_b32_dpp v19, v36 row_shr:2 row_mask:0xf bank_mask:0xf
	v_mov_b32_dpp v17, v36 row_shr:1 row_mask:0xf bank_mask:0xf
	v_lshlrev_b32_e32 v18, 16, v19
	v_and_b32_e32 v19, 0xffff0000, v19
	v_mov_b32_dpp v23, v73 row_ror:1 row_mask:0xf bank_mask:0xf
	v_lshlrev_b32_e32 v16, 16, v17
	v_and_b32_e32 v17, 0xffff0000, v17
	v_pk_fma_f32 v[18:19], v[64:65], v[18:19], v[60:61]
	v_mov_b32_dpp v23, v37 row_shr:1 row_mask:0xf bank_mask:0xf
	v_lshlrev_b32_e32 v20, 16, v36
	v_and_b32_e32 v21, 0xffff0000, v36
	v_pk_fma_f32 v[16:17], v[68:69], v[16:17], v[18:19]
	v_mov_b32_dpp v24, v37 row_shr:2 row_mask:0xf bank_mask:0xf
	v_pk_fma_f32 v[16:17], v[56:57], v[20:21], v[16:17]
	v_lshlrev_b32_e32 v20, 16, v23
	v_lshlrev_b32_e32 v22, 16, v24
	v_and_b32_e32 v21, 0xffff0000, v23
	v_and_b32_e32 v23, 0xffff0000, v24
	v_pk_fma_f32 v[22:23], v[66:67], v[22:23], v[62:63]
	v_lshlrev_b32_e32 v24, 16, v37
	v_and_b32_e32 v25, 0xffff0000, v37
	v_pk_fma_f32 v[20:21], v[70:71], v[20:21], v[22:23]
	v_mul_f32_e32 v18, 0xbfb8aa3b, v16
	v_mul_f32_e32 v19, 0xbfb8aa3b, v17
	v_pk_fma_f32 v[20:21], v[58:59], v[24:25], v[20:21]
	v_exp_f32_e32 v18, v18
	v_exp_f32_e32 v19, v19
	v_mul_f32_e32 v22, 0xbfb8aa3b, v20
	v_mul_f32_e32 v23, 0xbfb8aa3b, v21
	v_exp_f32_e32 v22, v22
	v_exp_f32_e32 v23, v23
	v_add_f32_e32 v18, 1.0, v18
	v_add_f32_e32 v19, 1.0, v19
	v_rcp_f32_e32 v18, v18
	v_rcp_f32_e32 v19, v19
	v_add_f32_e32 v22, 1.0, v22
	v_add_f32_e32 v23, 1.0, v23
	v_rcp_f32_e32 v22, v22
	v_rcp_f32_e32 v23, v23
	v_pk_mul_f32 v[16:17], v[16:17], v[18:19]
	v_lshlrev_b32_e32 v18, 16, v38
	v_pk_mul_f32 v[12:13], v[12:13], v[16:17]
	v_pk_mul_f32 v[16:17], v[20:21], v[22:23]
	v_cvt_pk_bf16_f32 v12, v12, v13
	v_pk_mul_f32 v[14:15], v[14:15], v[16:17]
	s_nop 0
	v_cvt_pk_bf16_f32 v13, v14, v15
	s_nop 0
	v_mov_b32_dpp v17, v74 row_ror:2 row_mask:0xf bank_mask:0xf
	s_nop 0
	v_mov_b32_dpp v15, v74 row_ror:1 row_mask:0xf bank_mask:0xf
	v_mov_b32_dpp v17, v38 row_shr:2 row_mask:0xf bank_mask:0xf
	s_nop 0
	v_mov_b32_dpp v15, v38 row_shr:1 row_mask:0xf bank_mask:0xf
	v_lshlrev_b32_e32 v16, 16, v17
	v_and_b32_e32 v17, 0xffff0000, v17
	v_mov_b32_dpp v21, v75 row_ror:1 row_mask:0xf bank_mask:0xf
	v_mov_b32_dpp v22, v75 row_ror:2 row_mask:0xf bank_mask:0xf
	v_lshlrev_b32_e32 v14, 16, v15
	v_and_b32_e32 v15, 0xffff0000, v15
	v_pk_fma_f32 v[16:17], v[40:41], v[16:17], v[44:45]
	v_mov_b32_dpp v21, v39 row_shr:1 row_mask:0xf bank_mask:0xf
	v_and_b32_e32 v19, 0xffff0000, v38
	v_pk_fma_f32 v[14:15], v[48:49], v[14:15], v[16:17]
	v_mov_b32_dpp v22, v39 row_shr:2 row_mask:0xf bank_mask:0xf
	v_pk_fma_f32 v[14:15], v[52:53], v[18:19], v[14:15]
	v_lshlrev_b32_e32 v18, 16, v21
	v_lshlrev_b32_e32 v20, 16, v22
	v_and_b32_e32 v19, 0xffff0000, v21
	v_and_b32_e32 v21, 0xffff0000, v22
	v_pk_fma_f32 v[20:21], v[42:43], v[20:21], v[46:47]
	v_lshlrev_b32_e32 v22, 16, v39
	v_and_b32_e32 v23, 0xffff0000, v39
	v_pk_fma_f32 v[18:19], v[50:51], v[18:19], v[20:21]
	v_mul_f32_e32 v16, 0xbfb8aa3b, v14
	v_mul_f32_e32 v17, 0xbfb8aa3b, v15
	v_pk_fma_f32 v[18:19], v[54:55], v[22:23], v[18:19]
	v_exp_f32_e32 v16, v16
	v_exp_f32_e32 v17, v17
	v_mul_f32_e32 v20, 0xbfb8aa3b, v18
	v_mul_f32_e32 v21, 0xbfb8aa3b, v19
	v_exp_f32_e32 v20, v20
	v_exp_f32_e32 v21, v21
	v_add_f32_e32 v16, 1.0, v16
	v_add_f32_e32 v17, 1.0, v17
	v_rcp_f32_e32 v16, v16
	v_rcp_f32_e32 v17, v17
	v_add_f32_e32 v20, 1.0, v20
	v_add_f32_e32 v21, 1.0, v21
	v_rcp_f32_e32 v20, v20
	v_rcp_f32_e32 v21, v21
	v_pk_mul_f32 v[14:15], v[14:15], v[16:17]
	s_nop 0
	v_pk_mul_f32 v[8:9], v[8:9], v[14:15]
	v_pk_mul_f32 v[14:15], v[18:19], v[20:21]
	s_nop 0
	v_pk_mul_f32 v[10:11], v[10:11], v[14:15]
	v_cvt_pk_bf16_f32 v14, v8, v9
	s_nop 0
	v_cvt_pk_bf16_f32 v15, v10, v11
	s_nop 0
	v_mov_b32_dpp v9, v36 row_ror:2 row_mask:0xf bank_mask:0xf
	global_store_dwordx4 v[88:89], v[12:15], off offset:256
	v_mov_b32_dpp v11, v36 row_ror:1 row_mask:0xf bank_mask:0xf
	v_mov_b32_dpp v9, v32 row_shr:2 row_mask:0xf bank_mask:0xf
	v_lshlrev_b32_e32 v8, 16, v9
	v_mov_b32_dpp v11, v32 row_shr:1 row_mask:0xf bank_mask:0xf
	v_and_b32_e32 v9, 0xffff0000, v9
	v_lshlrev_b32_e32 v10, 16, v11
	v_and_b32_e32 v11, 0xffff0000, v11
	v_pk_fma_f32 v[8:9], v[64:65], v[8:9], v[60:61]
	s_nop 0
	v_pk_fma_f32 v[8:9], v[68:69], v[10:11], v[8:9]
	v_lshlrev_b32_e32 v10, 16, v32
	v_and_b32_e32 v11, 0xffff0000, v32
	v_pk_fma_f32 v[8:9], v[56:57], v[10:11], v[8:9]
	s_nop 0
	v_mul_f32_e32 v10, 0xbfb8aa3b, v8
	v_mul_f32_e32 v11, 0xbfb8aa3b, v9
	v_exp_f32_e32 v10, v10
	v_exp_f32_e32 v11, v11
	v_mov_b32_dpp v14, v37 row_ror:2 row_mask:0xf bank_mask:0xf
	v_mov_b32_dpp v12, v37 row_ror:1 row_mask:0xf bank_mask:0xf
	v_add_f32_e32 v10, 1.0, v10
	v_add_f32_e32 v11, 1.0, v11
	v_rcp_f32_e32 v10, v10
	v_rcp_f32_e32 v11, v11
	v_mov_b32_dpp v14, v33 row_shr:2 row_mask:0xf bank_mask:0xf
	v_mov_b32_dpp v12, v33 row_shr:1 row_mask:0xf bank_mask:0xf
	v_lshlrev_b32_e32 v16, 16, v12
	v_pk_mul_f32 v[8:9], v[8:9], v[10:11]
	v_lshlrev_b32_e32 v10, 16, v14
	v_and_b32_e32 v11, 0xffff0000, v14
	v_and_b32_e32 v17, 0xffff0000, v12
	v_pk_fma_f32 v[10:11], v[66:67], v[10:11], v[62:63]
	s_nop 0
	v_pk_fma_f32 v[10:11], v[70:71], v[16:17], v[10:11]
	v_lshlrev_b32_e32 v16, 16, v33
	v_and_b32_e32 v17, 0xffff0000, v33
	v_mov_b32_dpp v20, v38 row_ror:2 row_mask:0xf bank_mask:0xf
	v_pk_fma_f32 v[10:11], v[58:59], v[16:17], v[10:11]
	v_mov_b32_dpp v19, v38 row_ror:1 row_mask:0xf bank_mask:0xf
	v_mov_b32_dpp v20, v34 row_shr:2 row_mask:0xf bank_mask:0xf
	v_mul_f32_e32 v12, 0xbfb8aa3b, v10
	v_mov_b32_dpp v19, v34 row_shr:1 row_mask:0xf bank_mask:0xf
	v_exp_f32_e32 v12, v12
	v_lshlrev_b32_e32 v16, 16, v20
	v_and_b32_e32 v17, 0xffff0000, v20
	v_lshlrev_b32_e32 v18, 16, v19
	v_and_b32_e32 v19, 0xffff0000, v19
	v_pk_fma_f32 v[16:17], v[40:41], v[16:17], v[44:45]
	v_pk_mul_f32 v[4:5], v[4:5], v[8:9]
	v_pk_fma_f32 v[16:17], v[48:49], v[18:19], v[16:17]
	v_lshlrev_b32_e32 v18, 16, v34
	v_and_b32_e32 v19, 0xffff0000, v34
	v_mul_f32_e32 v8, 0xbfb8aa3b, v11
	v_pk_fma_f32 v[16:17], v[52:53], v[18:19], v[16:17]
	v_exp_f32_e32 v9, v8
	v_add_f32_e32 v8, 1.0, v12
	v_mul_f32_e32 v12, 0xbfb8aa3b, v16
	v_exp_f32_e32 v12, v12
	v_mul_f32_e32 v14, 0xbfb8aa3b, v17
	v_exp_f32_e32 v14, v14
	v_add_f32_e32 v9, 1.0, v9
	s_nop 0
	v_mov_b32_dpp v22, v39 row_ror:2 row_mask:0xf bank_mask:0xf
	v_rcp_f32_e32 v8, v8
	v_rcp_f32_e32 v9, v9
	v_add_f32_e32 v12, 1.0, v12
	v_mov_b32_dpp v21, v39 row_ror:1 row_mask:0xf bank_mask:0xf
	v_mov_b32_dpp v22, v35 row_shr:2 row_mask:0xf bank_mask:0xf
	v_rcp_f32_e32 v18, v12
	v_add_f32_e32 v12, 1.0, v14
	v_mov_b32_dpp v21, v35 row_shr:1 row_mask:0xf bank_mask:0xf
	v_and_b32_e32 v13, 0xffff0000, v22
	v_rcp_f32_e32 v19, v12
	v_lshlrev_b32_e32 v12, 16, v22
	v_and_b32_e32 v15, 0xffff0000, v21
	v_lshlrev_b32_e32 v14, 16, v21
	v_pk_fma_f32 v[12:13], v[42:43], v[12:13], v[46:47]
	v_pk_mul_f32 v[8:9], v[10:11], v[8:9]
	v_lshlrev_b32_e32 v10, 16, v35
	v_and_b32_e32 v11, 0xffff0000, v35
	v_pk_fma_f32 v[12:13], v[50:51], v[14:15], v[12:13]
	v_pk_mul_f32 v[6:7], v[6:7], v[8:9]
	v_pk_fma_f32 v[10:11], v[54:55], v[10:11], v[12:13]
	v_pk_mul_f32 v[8:9], v[16:17], v[18:19]
	v_mul_f32_e32 v12, 0xbfb8aa3b, v10
	v_exp_f32_e32 v12, v12
	v_mul_f32_e32 v13, 0xbfb8aa3b, v11
	v_exp_f32_e32 v13, v13
	v_pk_mul_f32 v[8:9], v[0:1], v[8:9]
	v_add_f32_e32 v0, 1.0, v12
	v_rcp_f32_e32 v12, v0
	v_add_f32_e32 v0, 1.0, v13
	v_rcp_f32_e32 v13, v0
	v_cvt_pk_bf16_f32 v0, v4, v5
	v_cvt_pk_bf16_f32 v1, v6, v7
	v_pk_mul_f32 v[4:5], v[10:11], v[12:13]
	s_nop 0
	v_pk_mul_f32 v[4:5], v[2:3], v[4:5]
	v_cvt_pk_bf16_f32 v2, v8, v9
	v_cvt_pk_bf16_f32 v3, v4, v5
	global_store_dwordx4 v[84:85], v[0:3], off offset:256
	s_cbranch_vccnz .LBB0_967
	s_andn2_b64 vcc, exec, s[10:11]
	s_cbranch_vccnz .LBB0_966
	s_barrier
	s_branch .LBB0_966

.LBB0_1762:
	s_or_b64 exec, exec, s[2:3]
	v_mad_i64_i32 v[230:231], s[2:3], v142, s89, 0
	v_mad_i64_i32 v[232:233], s[2:3], v144, s89, 0
	s_waitcnt lgkmcnt(2)
	v_pk_add_f32 v[142:143], v[154:155], v[156:157]
	v_mov_b64_e32 v[144:145], s[46:47]
	v_pk_fma_f32 v[142:143], v[142:143], s[44:45], v[144:145] op_sel_hi:[1,0,0]
	v_mad_i64_i32 v[234:235], s[2:3], v146, s89, 0
	v_mul_f32_e32 v146, 0x4b800000, v143
	v_cmp_gt_f32_e64 s[4:5], s90, v143
	v_mad_i64_i32 v[198:199], s[2:3], v148, s89, 0
	s_nop 0
	v_cndmask_b32_e64 v143, v143, v146, s[4:5]
	v_rsq_f32_e32 v143, v143
	v_cmp_gt_f32_e64 s[2:3], s90, v142
	s_nop 0
	s_nop 0
	v_mul_f32_e32 v146, 0x45800000, v143
	v_cndmask_b32_e64 v206, v143, v146, s[4:5]
	v_mul_f32_e32 v143, 0x4b800000, v142
	v_cndmask_b32_e64 v142, v142, v143, s[2:3]
	v_rsq_f32_e32 v142, v142
	s_waitcnt vmcnt(0)
	v_mov_b32_dpp v203, v178 row_ror:2 row_mask:0xf bank_mask:0xf
	v_mov_b32_dpp v201, v178 row_ror:1 row_mask:0xf bank_mask:0xf
	s_nop 0
	v_mul_f32_e32 v143, 0x45800000, v142
	v_cndmask_b32_e64 v204, v142, v143, s[2:3]
	s_waitcnt lgkmcnt(0)
	v_pk_add_f32 v[142:143], v[150:151], v[152:153]
	v_mov_b32_dpp v203, v174 row_shr:2 row_mask:0xf bank_mask:0xf
	v_pk_fma_f32 v[142:143], v[142:143], s[44:45], v[144:145] op_sel_hi:[1,0,0]
	v_mov_b32_dpp v201, v174 row_shr:1 row_mask:0xf bank_mask:0xf
	v_mul_f32_e32 v144, 0x4b800000, v143
	v_cmp_gt_f32_e64 s[4:5], s90, v143
	v_cmp_gt_f32_e64 s[2:3], s90, v142
	s_nop 0
	v_cndmask_b32_e64 v143, v143, v144, s[4:5]
	v_rsq_f32_e32 v143, v143
	v_lshlrev_b32_e32 v236, 16, v203
	v_and_b32_e32 v237, 0xffff0000, v203
	v_mov_b32_dpp v205, v179 row_ror:1 row_mask:0xf bank_mask:0xf
	v_mul_f32_e32 v144, 0x45800000, v143
	v_cndmask_b32_e64 v202, v143, v144, s[4:5]
	v_mul_f32_e32 v143, 0x4b800000, v142
	v_cndmask_b32_e64 v142, v142, v143, s[2:3]
	v_rsq_f32_e32 v142, v142
	v_mov_b32_dpp v207, v179 row_ror:2 row_mask:0xf bank_mask:0xf
	v_lshlrev_b32_e32 v178, 16, v201
	v_and_b32_e32 v179, 0xffff0000, v201
	v_mul_f32_e32 v143, 0x45800000, v142
	v_cndmask_b32_e64 v200, v142, v143, s[2:3]
	v_lshlrev_b64 v[142:143], 2, v[208:209]
	v_lshl_add_u64 v[218:219], s[18:19], 0, v[142:143]
	v_lshl_add_u64 v[216:217], s[42:43], 0, v[142:143]
	v_lshl_add_u64 v[214:215], s[20:21], 0, v[142:143]
	v_lshl_add_u64 v[220:221], s[22:23], 0, v[142:143]
	global_load_dwordx4 v[142:145], v[218:219], off offset:16
	global_load_dwordx4 v[158:161], v[218:219], off
	global_load_dwordx4 v[146:149], v[216:217], off offset:16
	global_load_dwordx4 v[166:169], v[216:217], off
	global_load_dwordx4 v[150:153], v[214:215], off offset:16
	global_load_dwordx4 v[162:165], v[214:215], off
	global_load_dwordx4 v[154:157], v[220:221], off offset:16
	global_load_dwordx4 v[170:173], v[220:221], off
	v_lshlrev_b32_e32 v238, 16, v174
	v_and_b32_e32 v239, 0xffff0000, v174
	v_mov_b32_dpp v207, v175 row_shr:2 row_mask:0xf bank_mask:0xf
	v_mov_b32_dpp v205, v175 row_shr:1 row_mask:0xf bank_mask:0xf
	v_lshlrev_b32_e32 v250, 16, v175
	v_and_b32_e32 v251, 0xffff0000, v175
	s_nop 0
	s_waitcnt vmcnt(0)
	v_pk_fma_f32 v[236:237], v[158:159], v[236:237], v[170:171]
	s_nop 0
	v_pk_fma_f32 v[178:179], v[166:167], v[178:179], v[236:237]
	v_mov_b32_dpp v203, v181 row_ror:1 row_mask:0xf bank_mask:0xf
	v_pk_fma_f32 v[178:179], v[162:163], v[238:239], v[178:179]
	v_pk_mul_f32 v[238:239], v[126:127], v[206:207] op_sel_hi:[1,0]
	v_mul_f32_e32 v201, 0xbfb8aa3b, v178
	v_exp_f32_e32 v201, v201
	v_mov_b32_dpp v203, v177 row_shr:1 row_mask:0xf bank_mask:0xf
	v_add_f32_e32 v201, 1.0, v201
	v_rcp_f32_e32 v236, v201
	v_mul_f32_e32 v201, 0xbfb8aa3b, v179
	v_exp_f32_e32 v201, v201
	s_nop 0
	v_add_f32_e32 v201, 1.0, v201
	v_rcp_f32_e32 v237, v201
	s_nop 0
	v_pk_mul_f32 v[178:179], v[178:179], v[236:237]
	s_nop 0
	v_pk_mul_f32 v[178:179], v[238:239], v[178:179]
	v_lshlrev_b32_e32 v238, 16, v207
	v_and_b32_e32 v239, 0xffff0000, v207
	v_lshlrev_b32_e32 v236, 16, v205
	v_and_b32_e32 v237, 0xffff0000, v205
	v_pk_fma_f32 v[238:239], v[160:161], v[238:239], v[172:173]
	s_nop 0
	v_pk_fma_f32 v[236:237], v[168:169], v[236:237], v[238:239]
	s_nop 0
	v_pk_fma_f32 v[236:237], v[164:165], v[250:251], v[236:237]
	v_pk_mul_f32 v[250:251], v[128:129], v[206:207] op_sel_hi:[1,0]
	v_mul_f32_e32 v201, 0xbfb8aa3b, v236
	v_exp_f32_e32 v201, v201
	v_mov_b32_dpp v205, v181 row_ror:2 row_mask:0xf bank_mask:0xf
	v_add_f32_e32 v201, 1.0, v201
	v_rcp_f32_e32 v238, v201
	v_mul_f32_e32 v201, 0xbfb8aa3b, v237
	v_exp_f32_e32 v201, v201
	v_mov_b32_dpp v205, v177 row_shr:2 row_mask:0xf bank_mask:0xf
	v_add_f32_e32 v201, 1.0, v201
	v_rcp_f32_e32 v239, v201
	s_nop 0
	v_pk_mul_f32 v[236:237], v[236:237], v[238:239]
	s_nop 0
	v_pk_mul_f32 v[238:239], v[250:251], v[236:237]
	v_cvt_pk_bf16_f32 v236, v178, v179
	s_nop 0
	v_mov_b32_dpp v201, v180 row_ror:2 row_mask:0xf bank_mask:0xf
	v_cvt_pk_bf16_f32 v237, v238, v239
	v_mov_b32_dpp v179, v180 row_ror:1 row_mask:0xf bank_mask:0xf
	v_mov_b32_dpp v201, v176 row_shr:2 row_mask:0xf bank_mask:0xf
	v_lshlrev_b32_e32 v180, 16, v201
	v_mov_b32_dpp v179, v176 row_shr:1 row_mask:0xf bank_mask:0xf
	v_and_b32_e32 v181, 0xffff0000, v201
	v_lshlrev_b32_e32 v178, 16, v179
	v_and_b32_e32 v179, 0xffff0000, v179
	v_pk_fma_f32 v[180:181], v[142:143], v[180:181], v[154:155]
	v_lshlrev_b32_e32 v238, 16, v176
	v_and_b32_e32 v239, 0xffff0000, v176
	v_pk_fma_f32 v[178:179], v[146:147], v[178:179], v[180:181]
	v_lshlrev_b32_e32 v250, 16, v177
	v_pk_fma_f32 v[178:179], v[150:151], v[238:239], v[178:179]
	v_pk_mul_f32 v[238:239], v[122:123], v[206:207] op_sel_hi:[1,0]
	v_mul_f32_e32 v180, 0xbfb8aa3b, v178
	v_mul_f32_e32 v181, 0xbfb8aa3b, v179
	v_exp_f32_e32 v180, v180
	v_exp_f32_e32 v181, v181
	v_and_b32_e32 v251, 0xffff0000, v177
	v_add_f32_e32 v180, 1.0, v180
	v_add_f32_e32 v181, 1.0, v181
	v_rcp_f32_e32 v180, v180
	v_rcp_f32_e32 v181, v181
	s_nop 0
	v_pk_mul_f32 v[178:179], v[178:179], v[180:181]
	s_nop 0
	v_pk_mul_f32 v[178:179], v[238:239], v[178:179]
	v_lshlrev_b32_e32 v238, 16, v205
	v_and_b32_e32 v239, 0xffff0000, v205
	v_lshlrev_b32_e32 v180, 16, v203
	v_and_b32_e32 v181, 0xffff0000, v203
	v_pk_fma_f32 v[238:239], v[144:145], v[238:239], v[156:157]
	s_nop 0
	v_pk_fma_f32 v[180:181], v[148:149], v[180:181], v[238:239]
	s_nop 0
	v_pk_fma_f32 v[180:181], v[152:153], v[250:251], v[180:181]
	v_pk_mul_f32 v[250:251], v[124:125], v[206:207] op_sel_hi:[1,0]
	v_mul_f32_e32 v201, 0xbfb8aa3b, v180
	v_exp_f32_e32 v201, v201
	v_mov_b32_dpp v203, v175 row_ror:1 row_mask:0xf bank_mask:0xf
	v_mov_b32_dpp v205, v175 row_ror:2 row_mask:0xf bank_mask:0xf
	v_add_f32_e32 v201, 1.0, v201
	v_rcp_f32_e32 v238, v201
	v_mul_f32_e32 v201, 0xbfb8aa3b, v181
	v_exp_f32_e32 v201, v201
	v_mov_b32_dpp v205, v139 row_shr:2 row_mask:0xf bank_mask:0xf
	v_mov_b32_dpp v203, v139 row_shr:1 row_mask:0xf bank_mask:0xf
	v_add_f32_e32 v201, 1.0, v201
	v_rcp_f32_e32 v239, v201
	s_nop 0
	v_pk_mul_f32 v[180:181], v[180:181], v[238:239]
	s_nop 0
	v_pk_mul_f32 v[180:181], v[250:251], v[180:181]
	v_cvt_pk_bf16_f32 v238, v178, v179
	v_cvt_pk_bf16_f32 v239, v180, v181
	v_lshl_add_u64 v[180:181], s[36:37], 0, v[230:231]
	v_lshlrev_b64 v[178:179], 1, v[208:209]
	v_lshl_add_u64 v[230:231], v[180:181], 0, v[178:179]
	s_nop 0
	v_mov_b32_dpp v201, v174 row_ror:2 row_mask:0xf bank_mask:0xf
	global_store_dwordx4 v[230:231], v[236:239], off
	v_mov_b32_dpp v181, v174 row_ror:1 row_mask:0xf bank_mask:0xf
	v_mov_b32_dpp v201, v138 row_shr:2 row_mask:0xf bank_mask:0xf
	v_lshlrev_b32_e32 v180, 16, v201
	v_mov_b32_dpp v181, v138 row_shr:1 row_mask:0xf bank_mask:0xf
	v_lshlrev_b32_e32 v174, 16, v181
	v_and_b32_e32 v175, 0xffff0000, v181
	v_and_b32_e32 v181, 0xffff0000, v201
	v_pk_fma_f32 v[180:181], v[158:159], v[180:181], v[170:171]
	v_lshlrev_b32_e32 v236, 16, v138
	v_and_b32_e32 v237, 0xffff0000, v138
	v_pk_fma_f32 v[174:175], v[166:167], v[174:175], v[180:181]
	v_lshlrev_b32_e32 v238, 16, v139
	v_pk_fma_f32 v[174:175], v[162:163], v[236:237], v[174:175]
	v_pk_mul_f32 v[236:237], v[118:119], v[204:205] op_sel_hi:[1,0]
	v_mul_f32_e32 v180, 0xbfb8aa3b, v174
	v_mul_f32_e32 v181, 0xbfb8aa3b, v175
	v_exp_f32_e32 v180, v180
	v_exp_f32_e32 v181, v181
	v_and_b32_e32 v239, 0xffff0000, v139
	v_add_f32_e32 v180, 1.0, v180
	v_add_f32_e32 v181, 1.0, v181
	v_rcp_f32_e32 v180, v180
	v_rcp_f32_e32 v181, v181
	s_nop 0
	v_pk_mul_f32 v[174:175], v[174:175], v[180:181]
	s_nop 0
	v_pk_mul_f32 v[174:175], v[236:237], v[174:175]
	v_lshlrev_b32_e32 v236, 16, v205
	v_and_b32_e32 v237, 0xffff0000, v205
	v_lshlrev_b32_e32 v180, 16, v203
	v_and_b32_e32 v181, 0xffff0000, v203
	v_pk_fma_f32 v[236:237], v[160:161], v[236:237], v[172:173]
	v_cvt_pk_bf16_f32 v174, v174, v175
	v_pk_fma_f32 v[180:181], v[168:169], v[180:181], v[236:237]
	s_nop 0
	v_pk_fma_f32 v[180:181], v[164:165], v[238:239], v[180:181]
	v_pk_mul_f32 v[238:239], v[120:121], v[204:205] op_sel_hi:[1,0]
	v_mul_f32_e32 v201, 0xbfb8aa3b, v180
	v_exp_f32_e32 v201, v201
	s_nop 0
	v_mov_b32_dpp v203, v177 row_ror:1 row_mask:0xf bank_mask:0xf
	v_add_f32_e32 v201, 1.0, v201
	v_rcp_f32_e32 v236, v201
	v_mul_f32_e32 v201, 0xbfb8aa3b, v181
	v_exp_f32_e32 v201, v201
	v_mov_b32_dpp v205, v177 row_ror:2 row_mask:0xf bank_mask:0xf
	v_mov_b32_dpp v203, v141 row_shr:1 row_mask:0xf bank_mask:0xf
	v_add_f32_e32 v201, 1.0, v201
	v_rcp_f32_e32 v237, v201
	s_nop 0
	v_mov_b32_dpp v205, v141 row_shr:2 row_mask:0xf bank_mask:0xf
	v_pk_mul_f32 v[180:181], v[180:181], v[236:237]
	s_nop 0
	v_pk_mul_f32 v[180:181], v[238:239], v[180:181]
	v_mov_b32_dpp v201, v176 row_ror:2 row_mask:0xf bank_mask:0xf
	v_cvt_pk_bf16_f32 v175, v180, v181
	s_nop 0
	v_mov_b32_dpp v201, v140 row_shr:2 row_mask:0xf bank_mask:0xf
	v_lshlrev_b32_e32 v180, 16, v201
	v_mov_b32_dpp v181, v176 row_ror:1 row_mask:0xf bank_mask:0xf
	v_lshlrev_b32_e32 v236, 16, v140
	v_and_b32_e32 v237, 0xffff0000, v140
	v_mov_b32_dpp v181, v140 row_shr:1 row_mask:0xf bank_mask:0xf
	v_lshlrev_b32_e32 v176, 16, v181
	v_and_b32_e32 v177, 0xffff0000, v181
	v_and_b32_e32 v181, 0xffff0000, v201
	v_pk_fma_f32 v[180:181], v[142:143], v[180:181], v[154:155]
	v_lshlrev_b32_e32 v238, 16, v141
	v_pk_fma_f32 v[176:177], v[146:147], v[176:177], v[180:181]
	v_and_b32_e32 v239, 0xffff0000, v141
	v_pk_fma_f32 v[176:177], v[150:151], v[236:237], v[176:177]
	v_pk_mul_f32 v[236:237], v[114:115], v[204:205] op_sel_hi:[1,0]
	v_mul_f32_e32 v180, 0xbfb8aa3b, v176
	v_mul_f32_e32 v181, 0xbfb8aa3b, v177
	v_exp_f32_e32 v180, v180
	v_exp_f32_e32 v181, v181
	v_add_f32_e32 v180, 1.0, v180
	v_add_f32_e32 v181, 1.0, v181
	v_rcp_f32_e32 v180, v180
	v_rcp_f32_e32 v181, v181
	s_nop 0
	v_pk_mul_f32 v[176:177], v[176:177], v[180:181]
	s_nop 0
	v_pk_mul_f32 v[176:177], v[236:237], v[176:177]
	v_lshlrev_b32_e32 v236, 16, v205
	v_and_b32_e32 v237, 0xffff0000, v205
	v_lshlrev_b32_e32 v180, 16, v203
	v_and_b32_e32 v181, 0xffff0000, v203
	v_pk_fma_f32 v[236:237], v[144:145], v[236:237], v[156:157]
	v_cvt_pk_bf16_f32 v176, v176, v177
	v_pk_fma_f32 v[180:181], v[148:149], v[180:181], v[236:237]
	s_nop 0
	v_pk_fma_f32 v[180:181], v[152:153], v[238:239], v[180:181]
	v_pk_mul_f32 v[238:239], v[116:117], v[204:205] op_sel_hi:[1,0]
	v_mul_f32_e32 v201, 0xbfb8aa3b, v180
	v_exp_f32_e32 v201, v201
	s_nop 0
	v_add_f32_e32 v201, 1.0, v201
	v_rcp_f32_e32 v236, v201
	v_mul_f32_e32 v201, 0xbfb8aa3b, v181
	v_exp_f32_e32 v201, v201
	s_nop 0
	v_add_f32_e32 v201, 1.0, v201
	v_rcp_f32_e32 v237, v201
	s_nop 0
	v_pk_mul_f32 v[180:181], v[180:181], v[236:237]
	s_nop 0
	v_pk_mul_f32 v[180:181], v[238:239], v[180:181]
	s_nop 0
	v_cvt_pk_bf16_f32 v177, v180, v181
	v_lshl_add_u64 v[180:181], s[36:37], 0, v[232:233]
	v_lshl_add_u64 v[232:233], v[180:181], 0, v[178:179]
	global_store_dwordx4 v[232:233], v[174:177], off
	s_nop 0
	s_nop 0
	s_nop 0
	s_nop 0
	v_mov_b32_dpp v180, v139 row_ror:1 row_mask:0xf bank_mask:0xf
	v_mov_b32_dpp v175, v138 row_ror:1 row_mask:0xf bank_mask:0xf
	v_mov_b32_dpp v176, v138 row_ror:2 row_mask:0xf bank_mask:0xf
	v_mov_b32_dpp v181, v139 row_ror:2 row_mask:0xf bank_mask:0xf
	v_mov_b32_dpp v175, v134 row_shr:1 row_mask:0xf bank_mask:0xf
	v_mov_b32_dpp v176, v134 row_shr:2 row_mask:0xf bank_mask:0xf
	v_lshlrev_b32_e32 v138, 16, v175
	v_lshlrev_b32_e32 v174, 16, v176
	v_and_b32_e32 v139, 0xffff0000, v175
	v_and_b32_e32 v175, 0xffff0000, v176
	v_pk_fma_f32 v[174:175], v[158:159], v[174:175], v[170:171]
	v_lshlrev_b32_e32 v176, 16, v134
	v_and_b32_e32 v177, 0xffff0000, v134
	v_pk_fma_f32 v[138:139], v[166:167], v[138:139], v[174:175]
	v_mov_b32_dpp v181, v135 row_shr:2 row_mask:0xf bank_mask:0xf
	v_pk_fma_f32 v[138:139], v[162:163], v[176:177], v[138:139]
	v_pk_mul_f32 v[176:177], v[110:111], v[202:203] op_sel_hi:[1,0]
	v_mul_f32_e32 v174, 0xbfb8aa3b, v138
	v_mul_f32_e32 v175, 0xbfb8aa3b, v139
	v_exp_f32_e32 v174, v174
	v_exp_f32_e32 v175, v175
	v_mov_b32_dpp v180, v135 row_shr:1 row_mask:0xf bank_mask:0xf
	v_add_f32_e32 v174, 1.0, v174
	v_add_f32_e32 v175, 1.0, v175
	v_rcp_f32_e32 v174, v174
	v_rcp_f32_e32 v175, v175
	s_nop 0
	v_pk_mul_f32 v[138:139], v[138:139], v[174:175]
	s_nop 0
	v_pk_mul_f32 v[138:139], v[176:177], v[138:139]
	v_lshlrev_b32_e32 v176, 16, v181
	v_and_b32_e32 v177, 0xffff0000, v181
	v_lshlrev_b32_e32 v174, 16, v180
	v_and_b32_e32 v175, 0xffff0000, v180
	v_pk_fma_f32 v[176:177], v[160:161], v[176:177], v[172:173]
	v_lshlrev_b32_e32 v180, 16, v135
	v_and_b32_e32 v181, 0xffff0000, v135
	v_pk_fma_f32 v[174:175], v[168:169], v[174:175], v[176:177]
	v_cvt_pk_bf16_f32 v138, v138, v139
	v_pk_fma_f32 v[174:175], v[164:165], v[180:181], v[174:175]
	v_pk_mul_f32 v[180:181], v[112:113], v[202:203] op_sel_hi:[1,0]
	v_mul_f32_e32 v176, 0xbfb8aa3b, v174
	v_mul_f32_e32 v177, 0xbfb8aa3b, v175
	v_exp_f32_e32 v176, v176
	v_exp_f32_e32 v177, v177
	v_add_f32_e32 v176, 1.0, v176
	v_add_f32_e32 v177, 1.0, v177
	v_rcp_f32_e32 v176, v176
	v_rcp_f32_e32 v177, v177
	s_nop 0
	v_pk_mul_f32 v[174:175], v[174:175], v[176:177]
	s_nop 0
	v_pk_mul_f32 v[174:175], v[180:181], v[174:175]
	s_nop 0
	v_cvt_pk_bf16_f32 v139, v174, v175
	s_nop 0
	v_mov_b32_dpp v176, v140 row_ror:2 row_mask:0xf bank_mask:0xf
	s_nop 0
	v_mov_b32_dpp v175, v140 row_ror:1 row_mask:0xf bank_mask:0xf
	v_mov_b32_dpp v176, v136 row_shr:2 row_mask:0xf bank_mask:0xf
	s_nop 0
	v_mov_b32_dpp v175, v136 row_shr:1 row_mask:0xf bank_mask:0xf
	v_mov_b32_dpp v180, v141 row_ror:1 row_mask:0xf bank_mask:0xf
	v_mov_b32_dpp v181, v141 row_ror:2 row_mask:0xf bank_mask:0xf
	v_lshlrev_b32_e32 v140, 16, v175
	v_lshlrev_b32_e32 v174, 16, v176
	v_and_b32_e32 v141, 0xffff0000, v175
	v_and_b32_e32 v175, 0xffff0000, v176
	v_pk_fma_f32 v[174:175], v[142:143], v[174:175], v[154:155]
	v_lshlrev_b32_e32 v176, 16, v136
	v_and_b32_e32 v177, 0xffff0000, v136
	v_pk_fma_f32 v[140:141], v[146:147], v[140:141], v[174:175]
	v_mov_b32_dpp v181, v137 row_shr:2 row_mask:0xf bank_mask:0xf
	v_pk_fma_f32 v[140:141], v[150:151], v[176:177], v[140:141]
	v_pk_mul_f32 v[176:177], v[106:107], v[202:203] op_sel_hi:[1,0]
	v_mul_f32_e32 v174, 0xbfb8aa3b, v140
	v_mul_f32_e32 v175, 0xbfb8aa3b, v141
	v_exp_f32_e32 v174, v174
	v_exp_f32_e32 v175, v175
	v_mov_b32_dpp v180, v137 row_shr:1 row_mask:0xf bank_mask:0xf
	v_add_f32_e32 v174, 1.0, v174
	v_add_f32_e32 v175, 1.0, v175
	v_rcp_f32_e32 v174, v174
	v_rcp_f32_e32 v175, v175
	s_nop 0
	v_pk_mul_f32 v[140:141], v[140:141], v[174:175]
	s_nop 0
	v_pk_mul_f32 v[140:141], v[176:177], v[140:141]
	v_lshlrev_b32_e32 v176, 16, v181
	v_and_b32_e32 v177, 0xffff0000, v181
	v_lshlrev_b32_e32 v174, 16, v180
	v_and_b32_e32 v175, 0xffff0000, v180
	v_pk_fma_f32 v[176:177], v[144:145], v[176:177], v[156:157]
	v_lshlrev_b32_e32 v180, 16, v137
	v_and_b32_e32 v181, 0xffff0000, v137
	v_pk_fma_f32 v[174:175], v[148:149], v[174:175], v[176:177]
	v_cvt_pk_bf16_f32 v140, v140, v141
	v_pk_fma_f32 v[174:175], v[152:153], v[180:181], v[174:175]
	v_pk_mul_f32 v[180:181], v[108:109], v[202:203] op_sel_hi:[1,0]
	v_mul_f32_e32 v176, 0xbfb8aa3b, v174
	v_mul_f32_e32 v177, 0xbfb8aa3b, v175
	v_exp_f32_e32 v176, v176
	v_exp_f32_e32 v177, v177
	v_add_f32_e32 v176, 1.0, v176
	v_add_f32_e32 v177, 1.0, v177
	v_rcp_f32_e32 v176, v176
	v_rcp_f32_e32 v177, v177
	s_nop 0
	v_pk_mul_f32 v[174:175], v[174:175], v[176:177]
	s_nop 0
	v_pk_mul_f32 v[174:175], v[180:181], v[174:175]
	s_nop 0
	v_cvt_pk_bf16_f32 v141, v174, v175
	v_lshl_add_u64 v[174:175], s[36:37], 0, v[234:235]
	v_lshl_add_u64 v[234:235], v[174:175], 0, v[178:179]
	global_store_dwordx4 v[234:235], v[138:141], off
	s_nop 0
	s_nop 0
	s_nop 0
	s_nop 0
	v_mov_b32_dpp v174, v135 row_ror:2 row_mask:0xf bank_mask:0xf
	v_mov_b32_dpp v139, v134 row_ror:2 row_mask:0xf bank_mask:0xf
	v_mov_b32_dpp v141, v134 row_ror:1 row_mask:0xf bank_mask:0xf
	s_nop 0
	v_mov_b32_dpp v139, v130 row_shr:2 row_mask:0xf bank_mask:0xf
	v_mov_b32_dpp v141, v130 row_shr:1 row_mask:0xf bank_mask:0xf
	v_lshlrev_b32_e32 v138, 16, v139
	v_and_b32_e32 v139, 0xffff0000, v139
	v_lshlrev_b32_e32 v140, 16, v141
	v_and_b32_e32 v141, 0xffff0000, v141
	v_pk_fma_f32 v[138:139], v[158:159], v[138:139], v[170:171]
	v_mov_b32_dpp v134, v135 row_ror:1 row_mask:0xf bank_mask:0xf
	v_pk_fma_f32 v[138:139], v[166:167], v[140:141], v[138:139]
	v_lshlrev_b32_e32 v140, 16, v130
	v_and_b32_e32 v141, 0xffff0000, v130
	v_pk_fma_f32 v[138:139], v[162:163], v[140:141], v[138:139]
	v_mov_b32_dpp v174, v131 row_shr:2 row_mask:0xf bank_mask:0xf
	v_mul_f32_e32 v130, 0xbfb8aa3b, v138
	v_exp_f32_e32 v130, v130
	v_mov_b32_dpp v134, v131 row_shr:1 row_mask:0xf bank_mask:0xf
	v_pk_mul_f32 v[158:159], v[102:103], v[200:201] op_sel_hi:[1,0]
	v_mov_b32_dpp v176, v136 row_ror:2 row_mask:0xf bank_mask:0xf
	v_add_f32_e32 v130, 1.0, v130
	v_rcp_f32_e32 v140, v130
	v_mul_f32_e32 v130, 0xbfb8aa3b, v139
	v_exp_f32_e32 v130, v130
	v_mov_b32_dpp v175, v136 row_ror:1 row_mask:0xf bank_mask:0xf
	v_mov_b32_dpp v176, v132 row_shr:2 row_mask:0xf bank_mask:0xf
	s_nop 0
	v_add_f32_e32 v130, 1.0, v130
	v_rcp_f32_e32 v141, v130
	v_lshlrev_b32_e32 v130, 16, v131
	v_and_b32_e32 v131, 0xffff0000, v131
	v_mov_b32_dpp v175, v132 row_shr:1 row_mask:0xf bank_mask:0xf
	v_pk_mul_f32 v[138:139], v[138:139], v[140:141]
	v_lshlrev_b32_e32 v140, 16, v174
	v_and_b32_e32 v141, 0xffff0000, v174
	v_pk_mul_f32 v[138:139], v[158:159], v[138:139]
	v_lshlrev_b32_e32 v158, 16, v134
	v_and_b32_e32 v159, 0xffff0000, v134
	v_pk_fma_f32 v[140:141], v[160:161], v[140:141], v[172:173]
	s_nop 0
	v_pk_fma_f32 v[140:141], v[168:169], v[158:159], v[140:141]
	v_pk_mul_f32 v[158:159], v[104:105], v[200:201] op_sel_hi:[1,0]
	v_pk_fma_f32 v[130:131], v[164:165], v[130:131], v[140:141]
	v_mov_b32_dpp v177, v137 row_ror:2 row_mask:0xf bank_mask:0xf
	v_mul_f32_e32 v134, 0xbfb8aa3b, v130
	v_exp_f32_e32 v134, v134
	v_mov_b32_dpp v136, v137 row_ror:1 row_mask:0xf bank_mask:0xf
	v_mov_b32_dpp v177, v133 row_shr:2 row_mask:0xf bank_mask:0xf
	v_and_b32_e32 v135, 0xffff0000, v177
	v_add_f32_e32 v134, 1.0, v134
	v_rcp_f32_e32 v140, v134
	v_mul_f32_e32 v134, 0xbfb8aa3b, v131
	v_exp_f32_e32 v134, v134
	v_mov_b32_dpp v136, v133 row_shr:1 row_mask:0xf bank_mask:0xf
	v_and_b32_e32 v137, 0xffff0000, v136
	v_lshlrev_b32_e32 v136, 16, v136
	v_add_f32_e32 v134, 1.0, v134
	v_rcp_f32_e32 v141, v134
	v_lshlrev_b32_e32 v134, 16, v177
	v_pk_fma_f32 v[134:135], v[144:145], v[134:135], v[156:157]
	v_pk_mul_f32 v[130:131], v[130:131], v[140:141]
	s_nop 0
	v_pk_mul_f32 v[140:141], v[158:159], v[130:131]
	v_lshlrev_b32_e32 v130, 16, v176
	v_and_b32_e32 v131, 0xffff0000, v176
	v_lshlrev_b32_e32 v158, 16, v175
	v_and_b32_e32 v159, 0xffff0000, v175
	v_pk_fma_f32 v[130:131], v[142:143], v[130:131], v[154:155]
	v_lshlrev_b32_e32 v142, 16, v132
	v_pk_fma_f32 v[130:131], v[146:147], v[158:159], v[130:131]
	v_and_b32_e32 v143, 0xffff0000, v132
	v_pk_fma_f32 v[130:131], v[150:151], v[142:143], v[130:131]
	v_pk_fma_f32 v[134:135], v[148:149], v[136:137], v[134:135]
	v_mul_f32_e32 v132, 0xbfb8aa3b, v130
	v_exp_f32_e32 v132, v132
	v_pk_mul_f32 v[136:137], v[100:101], v[200:201] op_sel_hi:[1,0]
	v_pk_mul_f32 v[146:147], v[98:99], v[200:201] op_sel_hi:[1,0]
	v_add_f32_e32 v132, 1.0, v132
	v_rcp_f32_e32 v142, v132
	v_mul_f32_e32 v132, 0xbfb8aa3b, v131
	v_exp_f32_e32 v132, v132
	s_nop 0
	v_add_f32_e32 v132, 1.0, v132
	v_rcp_f32_e32 v143, v132
	v_lshlrev_b32_e32 v132, 16, v133
	v_and_b32_e32 v133, 0xffff0000, v133
	v_pk_fma_f32 v[132:133], v[152:153], v[132:133], v[134:135]
	v_pk_mul_f32 v[130:131], v[130:131], v[142:143]
	v_mul_f32_e32 v134, 0xbfb8aa3b, v132
	v_mul_f32_e32 v135, 0xbfb8aa3b, v133
	v_exp_f32_e32 v134, v134
	v_exp_f32_e32 v135, v135
	v_pk_mul_f32 v[142:143], v[146:147], v[130:131]
	v_cvt_pk_bf16_f32 v130, v138, v139
	v_add_f32_e32 v134, 1.0, v134
	v_add_f32_e32 v135, 1.0, v135
	v_rcp_f32_e32 v134, v134
	v_rcp_f32_e32 v135, v135
	v_cvt_pk_bf16_f32 v131, v140, v141
	v_pk_mul_f32 v[132:133], v[132:133], v[134:135]
	s_nop 0
	v_pk_mul_f32 v[134:135], v[136:137], v[132:133]
	v_cvt_pk_bf16_f32 v132, v142, v143
	v_cvt_pk_bf16_f32 v133, v134, v135
	v_lshl_add_u64 v[134:135], s[36:37], 0, v[198:199]
	v_lshl_add_u64 v[236:237], v[134:135], 0, v[178:179]
	global_store_dwordx4 v[236:237], v[130:133], off
	global_load_dwordx4 v[174:177], v[222:223], off offset:256
	global_load_dwordx4 v[138:141], v[224:225], off offset:256
	global_load_dwordx4 v[134:137], v[226:227], off offset:256
	s_nop 0
	global_load_dwordx4 v[130:133], v[228:229], off offset:256
	s_and_saveexec_b64 s[2:3], vcc
	s_xor_b64 s[4:5], exec, s[2:3]
	s_cbranch_execz .LBB0_1766
	v_mov_b32_e32 v181, 0
	v_mov_b32_e32 v180, 0
	v_mov_b32_e32 v179, 0
	v_mov_b32_e32 v178, 0
	s_and_saveexec_b64 s[6:7], s[0:1]
	s_cbranch_execz .LBB0_1765
	v_readlane_b32 s2, v254, 11
	v_lshlrev_b32_e32 v142, 2, v1
	v_readlane_b32 s3, v254, 12
	s_nop 4
	global_load_dword v150, v142, s[2:3]
	v_readlane_b32 s2, v254, 19
	v_readlane_b32 s3, v254, 20
	s_waitcnt vmcnt(0)
	v_fmamk_f32 v150, v150, 0x3a800000, v247
	v_lshl_add_u64 v[142:143], s[2:3], 0, v[210:211]
	v_lshl_add_u64 v[146:147], v[208:209], 2, v[142:143]
	global_load_dwordx4 v[142:145], v[146:147], off offset:512
	s_nop 0
	global_load_dwordx4 v[146:149], v[146:147], off offset:528
	v_mul_f32_e32 v151, 0x4b800000, v150
	v_cmp_gt_f32_e64 s[2:3], s90, v150
	s_nop 1
	v_cndmask_b32_e64 v150, v150, v151, s[2:3]
	v_rsq_f32_e32 v150, v150
	s_nop 0
	v_mul_f32_e32 v151, 0x45800000, v150
	v_cndmask_b32_e64 v150, v150, v151, s[2:3]
	s_waitcnt vmcnt(1)
	v_pk_mul_f32 v[142:143], v[142:143], v[150:151] op_sel_hi:[1,0]
	v_pk_mul_f32 v[144:145], v[144:145], v[150:151] op_sel_hi:[1,0]
	s_waitcnt vmcnt(0)
	v_pk_mul_f32 v[146:147], v[146:147], v[150:151] op_sel_hi:[1,0]
	v_pk_mul_f32 v[148:149], v[150:151], v[148:149] op_sel_hi:[0,1]
	v_cvt_pk_bf16_f32 v178, v142, v143
	v_cvt_pk_bf16_f32 v179, v144, v145
	v_cvt_pk_bf16_f32 v180, v146, v147
	v_cvt_pk_bf16_f32 v181, v148, v149

.LBB0_1768:
	s_or_b64 exec, exec, s[2:3]
	global_load_dwordx4 v[142:145], v[218:219], off offset:528
	global_load_dwordx4 v[158:161], v[218:219], off offset:512
	global_load_dwordx4 v[146:149], v[216:217], off offset:528
	global_load_dwordx4 v[166:169], v[216:217], off offset:512
	global_load_dwordx4 v[150:153], v[214:215], off offset:528
	global_load_dwordx4 v[162:165], v[214:215], off offset:512
	global_load_dwordx4 v[154:157], v[220:221], off offset:528
	global_load_dwordx4 v[170:173], v[220:221], off offset:512
	s_nop 0
	s_nop 0
	s_nop 0
	s_waitcnt vmcnt(8)
	v_mov_b32_dpp v239, v178 row_ror:1 row_mask:0xf bank_mask:0xf
	v_mov_b32_dpp v249, v178 row_ror:2 row_mask:0xf bank_mask:0xf
	s_nop 0
	v_mov_b32_dpp v239, v174 row_shr:1 row_mask:0xf bank_mask:0xf
	v_mov_b32_dpp v249, v174 row_shr:2 row_mask:0xf bank_mask:0xf
	v_mov_b32_dpp v252, v179 row_ror:1 row_mask:0xf bank_mask:0xf
	v_mov_b32_dpp v253, v179 row_ror:2 row_mask:0xf bank_mask:0xf
	v_lshlrev_b32_e32 v178, 16, v239
	v_lshlrev_b32_e32 v238, 16, v249
	v_and_b32_e32 v179, 0xffff0000, v239
	v_and_b32_e32 v239, 0xffff0000, v249
	v_lshlrev_b32_e32 v250, 16, v174
	v_and_b32_e32 v251, 0xffff0000, v174
	v_mov_b32_e32 v207, v206
	v_mov_b32_dpp v253, v175 row_shr:2 row_mask:0xf bank_mask:0xf
	v_mov_b32_dpp v252, v175 row_shr:1 row_mask:0xf bank_mask:0xf
	v_mov_b32_e32 v205, v204
	v_mov_b32_e32 v203, v202
	v_mov_b32_e32 v201, v200
	s_waitcnt vmcnt(0)
	v_pk_fma_f32 v[238:239], v[158:159], v[238:239], v[170:171]
	s_nop 0
	v_pk_fma_f32 v[178:179], v[166:167], v[178:179], v[238:239]
	s_nop 0
	v_pk_fma_f32 v[178:179], v[162:163], v[250:251], v[178:179]
	v_pk_mul_f32 v[250:251], v[94:95], v[206:207]
	v_mul_f32_e32 v238, 0xbfb8aa3b, v178
	v_mul_f32_e32 v239, 0xbfb8aa3b, v179
	v_exp_f32_e32 v238, v238
	v_exp_f32_e32 v239, v239
	v_add_f32_e32 v238, 1.0, v238
	v_add_f32_e32 v239, 1.0, v239
	v_rcp_f32_e32 v238, v238
	v_rcp_f32_e32 v239, v239
	s_nop 0
	v_pk_mul_f32 v[178:179], v[178:179], v[238:239]
	s_nop 0
	v_pk_mul_f32 v[178:179], v[250:251], v[178:179]
	v_lshlrev_b32_e32 v250, 16, v253
	v_and_b32_e32 v251, 0xffff0000, v253
	v_lshlrev_b32_e32 v238, 16, v252
	v_and_b32_e32 v239, 0xffff0000, v252
	v_pk_fma_f32 v[250:251], v[160:161], v[250:251], v[172:173]
	v_lshlrev_b32_e32 v252, 16, v175
	v_and_b32_e32 v253, 0xffff0000, v175
	v_pk_fma_f32 v[238:239], v[168:169], v[238:239], v[250:251]
	v_cvt_pk_bf16_f32 v178, v178, v179
	v_pk_fma_f32 v[238:239], v[164:165], v[252:253], v[238:239]
	v_pk_mul_f32 v[252:253], v[96:97], v[206:207]
	v_mul_f32_e32 v249, 0xbfb8aa3b, v238
	v_exp_f32_e32 v249, v249
	s_nop 0
	v_add_f32_e32 v249, 1.0, v249
	v_rcp_f32_e32 v250, v249
	v_mul_f32_e32 v249, 0xbfb8aa3b, v239
	v_exp_f32_e32 v249, v249
	s_nop 0
	v_add_f32_e32 v249, 1.0, v249
	v_rcp_f32_e32 v251, v249
	s_nop 0
	v_pk_mul_f32 v[238:239], v[238:239], v[250:251]
	s_nop 0
	v_pk_mul_f32 v[238:239], v[252:253], v[238:239]
	v_mov_b32_dpp v249, v180 row_ror:2 row_mask:0xf bank_mask:0xf
	v_cvt_pk_bf16_f32 v179, v238, v239
	s_nop 0
	v_mov_b32_dpp v249, v176 row_shr:2 row_mask:0xf bank_mask:0xf
	s_nop 0
	v_mov_b32_dpp v239, v180 row_ror:1 row_mask:0xf bank_mask:0xf
	s_nop 0
	v_mov_b32_dpp v252, v181 row_ror:1 row_mask:0xf bank_mask:0xf
	v_mov_b32_dpp v239, v176 row_shr:1 row_mask:0xf bank_mask:0xf
	v_mov_b32_dpp v253, v181 row_ror:2 row_mask:0xf bank_mask:0xf
	v_lshlrev_b32_e32 v180, 16, v239
	v_lshlrev_b32_e32 v238, 16, v249
	v_and_b32_e32 v181, 0xffff0000, v239
	v_and_b32_e32 v239, 0xffff0000, v249
	v_pk_fma_f32 v[238:239], v[142:143], v[238:239], v[154:155]
	v_lshlrev_b32_e32 v250, 16, v176
	v_and_b32_e32 v251, 0xffff0000, v176
	v_pk_fma_f32 v[180:181], v[146:147], v[180:181], v[238:239]
	v_mov_b32_dpp v253, v177 row_shr:2 row_mask:0xf bank_mask:0xf
	v_pk_fma_f32 v[180:181], v[150:151], v[250:251], v[180:181]
	v_pk_mul_f32 v[250:251], v[90:91], v[206:207]
	v_mul_f32_e32 v238, 0xbfb8aa3b, v180
	v_mul_f32_e32 v239, 0xbfb8aa3b, v181
	v_exp_f32_e32 v238, v238
	v_exp_f32_e32 v239, v239
	v_mov_b32_dpp v252, v177 row_shr:1 row_mask:0xf bank_mask:0xf
	v_add_f32_e32 v238, 1.0, v238
	v_add_f32_e32 v239, 1.0, v239
	v_rcp_f32_e32 v238, v238
	v_rcp_f32_e32 v239, v239
	s_nop 0
	v_pk_mul_f32 v[180:181], v[180:181], v[238:239]
	s_nop 0
	v_pk_mul_f32 v[180:181], v[250:251], v[180:181]
	v_lshlrev_b32_e32 v250, 16, v253
	v_and_b32_e32 v251, 0xffff0000, v253
	v_lshlrev_b32_e32 v238, 16, v252
	v_and_b32_e32 v239, 0xffff0000, v252
	v_pk_fma_f32 v[250:251], v[144:145], v[250:251], v[156:157]
	v_lshlrev_b32_e32 v252, 16, v177
	v_and_b32_e32 v253, 0xffff0000, v177
	v_pk_fma_f32 v[238:239], v[148:149], v[238:239], v[250:251]
	v_cvt_pk_bf16_f32 v180, v180, v181
	v_pk_fma_f32 v[238:239], v[152:153], v[252:253], v[238:239]
	v_pk_mul_f32 v[252:253], v[92:93], v[206:207]
	v_mul_f32_e32 v249, 0xbfb8aa3b, v238
	v_exp_f32_e32 v249, v249
	s_nop 0
	v_add_f32_e32 v249, 1.0, v249
	v_rcp_f32_e32 v250, v249
	v_mul_f32_e32 v249, 0xbfb8aa3b, v239
	v_exp_f32_e32 v249, v249
	s_nop 0
	v_add_f32_e32 v249, 1.0, v249
	v_rcp_f32_e32 v251, v249
	s_nop 0
	v_pk_mul_f32 v[238:239], v[238:239], v[250:251]
	s_nop 0
	v_pk_mul_f32 v[238:239], v[252:253], v[238:239]
	s_nop 0
	v_cvt_pk_bf16_f32 v181, v238, v239
	global_store_dwordx4 v[230:231], v[178:181], off offset:256
	s_nop 0
	s_nop 0
	s_nop 0
	s_nop 0
	v_mov_b32_dpp v238, v175 row_ror:1 row_mask:0xf bank_mask:0xf
	v_mov_b32_dpp v179, v174 row_ror:1 row_mask:0xf bank_mask:0xf
	v_mov_b32_dpp v180, v174 row_ror:2 row_mask:0xf bank_mask:0xf
	v_mov_b32_dpp v239, v175 row_ror:2 row_mask:0xf bank_mask:0xf
	v_mov_b32_dpp v179, v138 row_shr:1 row_mask:0xf bank_mask:0xf
	v_mov_b32_dpp v180, v138 row_shr:2 row_mask:0xf bank_mask:0xf
	v_lshlrev_b32_e32 v174, 16, v179
	v_lshlrev_b32_e32 v178, 16, v180
	v_and_b32_e32 v175, 0xffff0000, v179
	v_and_b32_e32 v179, 0xffff0000, v180
	v_pk_fma_f32 v[178:179], v[158:159], v[178:179], v[170:171]
	v_lshlrev_b32_e32 v180, 16, v138
	v_and_b32_e32 v181, 0xffff0000, v138
	v_pk_fma_f32 v[174:175], v[166:167], v[174:175], v[178:179]
	v_mov_b32_dpp v239, v139 row_shr:2 row_mask:0xf bank_mask:0xf
	v_pk_fma_f32 v[174:175], v[162:163], v[180:181], v[174:175]
	v_pk_mul_f32 v[180:181], v[86:87], v[204:205]
	v_mul_f32_e32 v178, 0xbfb8aa3b, v174
	v_mul_f32_e32 v179, 0xbfb8aa3b, v175
	v_exp_f32_e32 v178, v178
	v_exp_f32_e32 v179, v179
	v_mov_b32_dpp v238, v139 row_shr:1 row_mask:0xf bank_mask:0xf
	v_add_f32_e32 v178, 1.0, v178
	v_add_f32_e32 v179, 1.0, v179
	v_rcp_f32_e32 v178, v178
	v_rcp_f32_e32 v179, v179
	s_nop 0
	v_pk_mul_f32 v[174:175], v[174:175], v[178:179]
	s_nop 0
	v_pk_mul_f32 v[174:175], v[180:181], v[174:175]
	v_lshlrev_b32_e32 v180, 16, v239
	v_and_b32_e32 v181, 0xffff0000, v239
	v_lshlrev_b32_e32 v178, 16, v238
	v_and_b32_e32 v179, 0xffff0000, v238
	v_pk_fma_f32 v[180:181], v[160:161], v[180:181], v[172:173]
	v_lshlrev_b32_e32 v238, 16, v139
	v_and_b32_e32 v239, 0xffff0000, v139
	v_pk_fma_f32 v[178:179], v[168:169], v[178:179], v[180:181]
	v_cvt_pk_bf16_f32 v174, v174, v175
	v_pk_fma_f32 v[178:179], v[164:165], v[238:239], v[178:179]
	v_pk_mul_f32 v[238:239], v[88:89], v[204:205]
	v_mul_f32_e32 v180, 0xbfb8aa3b, v178
	v_mul_f32_e32 v181, 0xbfb8aa3b, v179
	v_exp_f32_e32 v180, v180
	v_exp_f32_e32 v181, v181
	v_add_f32_e32 v180, 1.0, v180
	v_add_f32_e32 v181, 1.0, v181
	v_rcp_f32_e32 v180, v180
	v_rcp_f32_e32 v181, v181
	s_nop 0
	v_pk_mul_f32 v[178:179], v[178:179], v[180:181]
	s_nop 0
	v_pk_mul_f32 v[178:179], v[238:239], v[178:179]
	s_nop 0
	v_cvt_pk_bf16_f32 v175, v178, v179
	s_nop 0
	v_mov_b32_dpp v180, v176 row_ror:2 row_mask:0xf bank_mask:0xf
	s_nop 0
	v_mov_b32_dpp v179, v176 row_ror:1 row_mask:0xf bank_mask:0xf
	v_mov_b32_dpp v180, v140 row_shr:2 row_mask:0xf bank_mask:0xf
	s_nop 0
	v_mov_b32_dpp v179, v140 row_shr:1 row_mask:0xf bank_mask:0xf
	v_mov_b32_dpp v238, v177 row_ror:1 row_mask:0xf bank_mask:0xf
	v_mov_b32_dpp v239, v177 row_ror:2 row_mask:0xf bank_mask:0xf
	v_lshlrev_b32_e32 v176, 16, v179
	v_lshlrev_b32_e32 v178, 16, v180
	v_and_b32_e32 v177, 0xffff0000, v179
	v_and_b32_e32 v179, 0xffff0000, v180
	v_pk_fma_f32 v[178:179], v[142:143], v[178:179], v[154:155]
	v_lshlrev_b32_e32 v180, 16, v140
	v_and_b32_e32 v181, 0xffff0000, v140
	v_pk_fma_f32 v[176:177], v[146:147], v[176:177], v[178:179]
	v_mov_b32_dpp v239, v141 row_shr:2 row_mask:0xf bank_mask:0xf
	v_pk_fma_f32 v[176:177], v[150:151], v[180:181], v[176:177]
	v_pk_mul_f32 v[180:181], v[82:83], v[204:205]
	v_mul_f32_e32 v178, 0xbfb8aa3b, v176
	v_mul_f32_e32 v179, 0xbfb8aa3b, v177
	v_exp_f32_e32 v178, v178
	v_exp_f32_e32 v179, v179
	v_mov_b32_dpp v238, v141 row_shr:1 row_mask:0xf bank_mask:0xf
	v_add_f32_e32 v178, 1.0, v178
	v_add_f32_e32 v179, 1.0, v179
	v_rcp_f32_e32 v178, v178
	v_rcp_f32_e32 v179, v179
	s_nop 0
	v_pk_mul_f32 v[176:177], v[176:177], v[178:179]
	s_nop 0
	v_pk_mul_f32 v[176:177], v[180:181], v[176:177]
	v_lshlrev_b32_e32 v180, 16, v239
	v_and_b32_e32 v181, 0xffff0000, v239
	v_lshlrev_b32_e32 v178, 16, v238
	v_and_b32_e32 v179, 0xffff0000, v238
	v_pk_fma_f32 v[180:181], v[144:145], v[180:181], v[156:157]
	v_lshlrev_b32_e32 v238, 16, v141
	v_and_b32_e32 v239, 0xffff0000, v141
	v_pk_fma_f32 v[178:179], v[148:149], v[178:179], v[180:181]
	v_cvt_pk_bf16_f32 v176, v176, v177
	v_pk_fma_f32 v[178:179], v[152:153], v[238:239], v[178:179]
	v_pk_mul_f32 v[238:239], v[84:85], v[204:205]
	v_mul_f32_e32 v180, 0xbfb8aa3b, v178
	v_mul_f32_e32 v181, 0xbfb8aa3b, v179
	v_exp_f32_e32 v180, v180
	v_exp_f32_e32 v181, v181
	v_add_f32_e32 v180, 1.0, v180
	v_add_f32_e32 v181, 1.0, v181
	v_rcp_f32_e32 v180, v180
	v_rcp_f32_e32 v181, v181
	s_nop 0
	v_pk_mul_f32 v[178:179], v[178:179], v[180:181]
	s_nop 0
	v_pk_mul_f32 v[178:179], v[238:239], v[178:179]
	s_nop 0
	v_cvt_pk_bf16_f32 v177, v178, v179
	global_store_dwordx4 v[232:233], v[174:177], off offset:256
	s_nop 0
	s_nop 0
	s_nop 0
	s_nop 0
	v_mov_b32_dpp v178, v139 row_ror:1 row_mask:0xf bank_mask:0xf
	v_mov_b32_dpp v175, v138 row_ror:1 row_mask:0xf bank_mask:0xf
	v_mov_b32_dpp v176, v138 row_ror:2 row_mask:0xf bank_mask:0xf
	v_mov_b32_dpp v179, v139 row_ror:2 row_mask:0xf bank_mask:0xf
	v_mov_b32_dpp v175, v134 row_shr:1 row_mask:0xf bank_mask:0xf
	v_mov_b32_dpp v176, v134 row_shr:2 row_mask:0xf bank_mask:0xf
	v_lshlrev_b32_e32 v138, 16, v175
	v_lshlrev_b32_e32 v174, 16, v176
	v_and_b32_e32 v139, 0xffff0000, v175
	v_and_b32_e32 v175, 0xffff0000, v176
	v_pk_fma_f32 v[174:175], v[158:159], v[174:175], v[170:171]
	v_lshlrev_b32_e32 v176, 16, v134
	v_and_b32_e32 v177, 0xffff0000, v134
	v_pk_fma_f32 v[138:139], v[166:167], v[138:139], v[174:175]
	v_mov_b32_dpp v179, v135 row_shr:2 row_mask:0xf bank_mask:0xf
	v_pk_fma_f32 v[138:139], v[162:163], v[176:177], v[138:139]
	v_pk_mul_f32 v[176:177], v[78:79], v[202:203]
	v_mul_f32_e32 v174, 0xbfb8aa3b, v138
	v_mul_f32_e32 v175, 0xbfb8aa3b, v139
	v_exp_f32_e32 v174, v174
	v_exp_f32_e32 v175, v175
	v_mov_b32_dpp v178, v135 row_shr:1 row_mask:0xf bank_mask:0xf
	v_add_f32_e32 v174, 1.0, v174
	v_add_f32_e32 v175, 1.0, v175
	v_rcp_f32_e32 v174, v174
	v_rcp_f32_e32 v175, v175
	s_nop 0
	v_pk_mul_f32 v[138:139], v[138:139], v[174:175]
	s_nop 0
	v_pk_mul_f32 v[138:139], v[176:177], v[138:139]
	v_lshlrev_b32_e32 v176, 16, v179
	v_and_b32_e32 v177, 0xffff0000, v179
	v_lshlrev_b32_e32 v174, 16, v178
	v_and_b32_e32 v175, 0xffff0000, v178
	v_pk_fma_f32 v[176:177], v[160:161], v[176:177], v[172:173]
	v_lshlrev_b32_e32 v178, 16, v135
	v_and_b32_e32 v179, 0xffff0000, v135
	v_pk_fma_f32 v[174:175], v[168:169], v[174:175], v[176:177]
	v_cvt_pk_bf16_f32 v138, v138, v139
	v_pk_fma_f32 v[174:175], v[164:165], v[178:179], v[174:175]
	v_pk_mul_f32 v[178:179], v[80:81], v[202:203]
	v_mul_f32_e32 v176, 0xbfb8aa3b, v174
	v_mul_f32_e32 v177, 0xbfb8aa3b, v175
	v_exp_f32_e32 v176, v176
	v_exp_f32_e32 v177, v177
	v_add_f32_e32 v176, 1.0, v176
	v_add_f32_e32 v177, 1.0, v177
	v_rcp_f32_e32 v176, v176
	v_rcp_f32_e32 v177, v177
	s_nop 0
	v_pk_mul_f32 v[174:175], v[174:175], v[176:177]
	s_nop 0
	v_pk_mul_f32 v[174:175], v[178:179], v[174:175]
	s_nop 0
	v_cvt_pk_bf16_f32 v139, v174, v175
	s_nop 0
	v_mov_b32_dpp v176, v140 row_ror:2 row_mask:0xf bank_mask:0xf
	s_nop 0
	v_mov_b32_dpp v175, v140 row_ror:1 row_mask:0xf bank_mask:0xf
	v_mov_b32_dpp v176, v136 row_shr:2 row_mask:0xf bank_mask:0xf
	s_nop 0
	v_mov_b32_dpp v175, v136 row_shr:1 row_mask:0xf bank_mask:0xf
	v_mov_b32_dpp v178, v141 row_ror:1 row_mask:0xf bank_mask:0xf
	v_mov_b32_dpp v179, v141 row_ror:2 row_mask:0xf bank_mask:0xf
	v_lshlrev_b32_e32 v140, 16, v175
	v_lshlrev_b32_e32 v174, 16, v176
	v_and_b32_e32 v141, 0xffff0000, v175
	v_and_b32_e32 v175, 0xffff0000, v176
	v_pk_fma_f32 v[174:175], v[142:143], v[174:175], v[154:155]
	v_lshlrev_b32_e32 v176, 16, v136
	v_and_b32_e32 v177, 0xffff0000, v136
	v_pk_fma_f32 v[140:141], v[146:147], v[140:141], v[174:175]
	v_mov_b32_dpp v179, v137 row_shr:2 row_mask:0xf bank_mask:0xf
	v_pk_fma_f32 v[140:141], v[150:151], v[176:177], v[140:141]
	v_pk_mul_f32 v[176:177], v[74:75], v[202:203]
	v_mul_f32_e32 v174, 0xbfb8aa3b, v140
	v_mul_f32_e32 v175, 0xbfb8aa3b, v141
	v_exp_f32_e32 v174, v174
	v_exp_f32_e32 v175, v175
	v_mov_b32_dpp v178, v137 row_shr:1 row_mask:0xf bank_mask:0xf
	v_add_f32_e32 v174, 1.0, v174
	v_add_f32_e32 v175, 1.0, v175
	v_rcp_f32_e32 v174, v174
	v_rcp_f32_e32 v175, v175
	s_nop 0
	v_pk_mul_f32 v[140:141], v[140:141], v[174:175]
	s_nop 0
	v_pk_mul_f32 v[140:141], v[176:177], v[140:141]
	v_lshlrev_b32_e32 v176, 16, v179
	v_and_b32_e32 v177, 0xffff0000, v179
	v_lshlrev_b32_e32 v174, 16, v178
	v_and_b32_e32 v175, 0xffff0000, v178
	v_pk_fma_f32 v[176:177], v[144:145], v[176:177], v[156:157]
	v_lshlrev_b32_e32 v178, 16, v137
	v_and_b32_e32 v179, 0xffff0000, v137
	v_pk_fma_f32 v[174:175], v[148:149], v[174:175], v[176:177]
	v_cvt_pk_bf16_f32 v140, v140, v141
	v_pk_fma_f32 v[174:175], v[152:153], v[178:179], v[174:175]
	v_pk_mul_f32 v[178:179], v[76:77], v[202:203]
	v_mul_f32_e32 v176, 0xbfb8aa3b, v174
	v_mul_f32_e32 v177, 0xbfb8aa3b, v175
	v_exp_f32_e32 v176, v176
	v_exp_f32_e32 v177, v177
	v_add_f32_e32 v176, 1.0, v176
	v_add_f32_e32 v177, 1.0, v177
	v_rcp_f32_e32 v176, v176
	v_rcp_f32_e32 v177, v177
	s_nop 0
	v_pk_mul_f32 v[174:175], v[174:175], v[176:177]
	s_nop 0
	v_pk_mul_f32 v[174:175], v[178:179], v[174:175]
	s_nop 0
	v_cvt_pk_bf16_f32 v141, v174, v175
	global_store_dwordx4 v[234:235], v[138:141], off offset:256
	s_nop 0
	s_nop 0
	s_nop 0
	s_nop 0
	v_mov_b32_dpp v174, v135 row_ror:2 row_mask:0xf bank_mask:0xf
	v_mov_b32_dpp v139, v134 row_ror:2 row_mask:0xf bank_mask:0xf
	v_mov_b32_dpp v141, v134 row_ror:1 row_mask:0xf bank_mask:0xf
	s_nop 0
	v_mov_b32_dpp v139, v130 row_shr:2 row_mask:0xf bank_mask:0xf
	v_mov_b32_dpp v141, v130 row_shr:1 row_mask:0xf bank_mask:0xf
	v_lshlrev_b32_e32 v138, 16, v139
	v_and_b32_e32 v139, 0xffff0000, v139
	v_lshlrev_b32_e32 v140, 16, v141
	v_and_b32_e32 v141, 0xffff0000, v141
	v_pk_fma_f32 v[138:139], v[158:159], v[138:139], v[170:171]
	v_mov_b32_dpp v134, v135 row_ror:1 row_mask:0xf bank_mask:0xf
	v_pk_fma_f32 v[138:139], v[166:167], v[140:141], v[138:139]
	v_lshlrev_b32_e32 v140, 16, v130
	v_and_b32_e32 v141, 0xffff0000, v130
	v_pk_fma_f32 v[138:139], v[162:163], v[140:141], v[138:139]
	v_mov_b32_dpp v174, v131 row_shr:2 row_mask:0xf bank_mask:0xf
	v_mul_f32_e32 v130, 0xbfb8aa3b, v138
	v_exp_f32_e32 v130, v130
	v_mov_b32_dpp v134, v131 row_shr:1 row_mask:0xf bank_mask:0xf
	v_pk_mul_f32 v[158:159], v[70:71], v[200:201]
	v_mov_b32_dpp v176, v136 row_ror:2 row_mask:0xf bank_mask:0xf
	v_add_f32_e32 v130, 1.0, v130
	v_rcp_f32_e32 v140, v130
	v_mul_f32_e32 v130, 0xbfb8aa3b, v139
	v_exp_f32_e32 v130, v130
	v_mov_b32_dpp v175, v136 row_ror:1 row_mask:0xf bank_mask:0xf
	v_mov_b32_dpp v176, v132 row_shr:2 row_mask:0xf bank_mask:0xf
	s_nop 0
	v_add_f32_e32 v130, 1.0, v130
	v_rcp_f32_e32 v141, v130
	v_lshlrev_b32_e32 v130, 16, v131
	v_and_b32_e32 v131, 0xffff0000, v131
	v_mov_b32_dpp v175, v132 row_shr:1 row_mask:0xf bank_mask:0xf
	v_pk_mul_f32 v[138:139], v[138:139], v[140:141]
	v_lshlrev_b32_e32 v140, 16, v174
	v_and_b32_e32 v141, 0xffff0000, v174
	v_pk_mul_f32 v[138:139], v[158:159], v[138:139]
	v_lshlrev_b32_e32 v158, 16, v134
	v_and_b32_e32 v159, 0xffff0000, v134
	v_pk_fma_f32 v[140:141], v[160:161], v[140:141], v[172:173]
	s_nop 0
	v_pk_fma_f32 v[140:141], v[168:169], v[158:159], v[140:141]
	v_pk_mul_f32 v[158:159], v[72:73], v[200:201]
	v_pk_fma_f32 v[130:131], v[164:165], v[130:131], v[140:141]
	v_mov_b32_dpp v177, v137 row_ror:2 row_mask:0xf bank_mask:0xf
	v_mul_f32_e32 v134, 0xbfb8aa3b, v130
	v_exp_f32_e32 v134, v134
	v_mov_b32_dpp v136, v137 row_ror:1 row_mask:0xf bank_mask:0xf
	v_mov_b32_dpp v177, v133 row_shr:2 row_mask:0xf bank_mask:0xf
	v_and_b32_e32 v135, 0xffff0000, v177
	v_add_f32_e32 v134, 1.0, v134
	v_rcp_f32_e32 v140, v134
	v_mul_f32_e32 v134, 0xbfb8aa3b, v131
	v_exp_f32_e32 v134, v134
	v_mov_b32_dpp v136, v133 row_shr:1 row_mask:0xf bank_mask:0xf
	v_and_b32_e32 v137, 0xffff0000, v136
	v_lshlrev_b32_e32 v136, 16, v136
	v_add_f32_e32 v134, 1.0, v134
	v_rcp_f32_e32 v141, v134
	v_lshlrev_b32_e32 v134, 16, v177
	v_pk_fma_f32 v[134:135], v[144:145], v[134:135], v[156:157]
	v_pk_mul_f32 v[130:131], v[130:131], v[140:141]
	s_nop 0
	v_pk_mul_f32 v[140:141], v[158:159], v[130:131]
	v_lshlrev_b32_e32 v130, 16, v176
	v_and_b32_e32 v131, 0xffff0000, v176
	v_lshlrev_b32_e32 v158, 16, v175
	v_and_b32_e32 v159, 0xffff0000, v175
	v_pk_fma_f32 v[130:131], v[142:143], v[130:131], v[154:155]
	v_lshlrev_b32_e32 v142, 16, v132
	v_pk_fma_f32 v[130:131], v[146:147], v[158:159], v[130:131]
	v_and_b32_e32 v143, 0xffff0000, v132
	v_pk_fma_f32 v[130:131], v[150:151], v[142:143], v[130:131]
	v_pk_fma_f32 v[134:135], v[148:149], v[136:137], v[134:135]
	v_mul_f32_e32 v132, 0xbfb8aa3b, v130
	v_exp_f32_e32 v132, v132
	v_pk_mul_f32 v[146:147], v[66:67], v[200:201]
	v_pk_mul_f32 v[136:137], v[68:69], v[200:201]
	v_add_f32_e32 v132, 1.0, v132
	v_rcp_f32_e32 v142, v132
	v_mul_f32_e32 v132, 0xbfb8aa3b, v131
	v_exp_f32_e32 v132, v132
	s_nop 0
	v_add_f32_e32 v132, 1.0, v132
	v_rcp_f32_e32 v143, v132
	v_lshlrev_b32_e32 v132, 16, v133
	v_and_b32_e32 v133, 0xffff0000, v133
	v_pk_fma_f32 v[132:133], v[152:153], v[132:133], v[134:135]
	v_pk_mul_f32 v[130:131], v[130:131], v[142:143]
	v_mul_f32_e32 v134, 0xbfb8aa3b, v132
	v_mul_f32_e32 v135, 0xbfb8aa3b, v133
	v_exp_f32_e32 v134, v134
	v_exp_f32_e32 v135, v135
	v_pk_mul_f32 v[142:143], v[146:147], v[130:131]
	v_cvt_pk_bf16_f32 v130, v138, v139
	v_add_f32_e32 v134, 1.0, v134
	v_add_f32_e32 v135, 1.0, v135
	v_rcp_f32_e32 v134, v134
	v_rcp_f32_e32 v135, v135
	v_cvt_pk_bf16_f32 v131, v140, v141
	v_pk_mul_f32 v[132:133], v[132:133], v[134:135]
	s_nop 0
	v_pk_mul_f32 v[134:135], v[136:137], v[132:133]
	v_cvt_pk_bf16_f32 v132, v142, v143
	v_cvt_pk_bf16_f32 v133, v134, v135
	global_store_dwordx4 v[236:237], v[130:133], off offset:256
	global_load_dwordx4 v[174:177], v[222:223], off offset:512
	global_load_dwordx4 v[170:173], v[224:225], off offset:512
	global_load_dwordx4 v[166:169], v[226:227], off offset:512
	s_nop 0
	global_load_dwordx4 v[130:133], v[228:229], off offset:512
	s_and_saveexec_b64 s[2:3], vcc
	s_xor_b64 s[2:3], exec, s[2:3]
	s_cbranch_execz .LBB0_1772
	v_mov_b32_e32 v181, 0
	v_mov_b32_e32 v180, 0
	v_mov_b32_e32 v179, 0
	v_mov_b32_e32 v178, 0
	s_and_saveexec_b64 s[4:5], s[0:1]
	s_cbranch_execz .LBB0_1771
	v_readlane_b32 s6, v254, 11
	v_lshlrev_b32_e32 v1, 2, v1
	v_readlane_b32 s7, v254, 12
	s_nop 4
	global_load_dword v1, v1, s[6:7]
	v_readlane_b32 s6, v254, 19
	v_readlane_b32 s7, v254, 20
	s_waitcnt vmcnt(0)
	v_fmamk_f32 v1, v1, 0x3a800000, v247
	v_lshl_add_u64 v[134:135], s[6:7], 0, v[210:211]
	v_lshl_add_u64 v[138:139], v[208:209], 2, v[134:135]
	global_load_dwordx4 v[134:137], v[138:139], off offset:1024
	s_nop 0
	global_load_dwordx4 v[138:141], v[138:139], off offset:1040
	v_mul_f32_e32 v142, 0x4b800000, v1
	v_cmp_gt_f32_e32 vcc, s90, v1
	s_nop 1
	v_cndmask_b32_e32 v1, v1, v142, vcc
	v_rsq_f32_e32 v1, v1
	s_nop 0
	v_mul_f32_e32 v142, 0x45800000, v1
	v_cndmask_b32_e32 v142, v1, v142, vcc
	s_waitcnt vmcnt(1)
	v_pk_mul_f32 v[134:135], v[134:135], v[142:143] op_sel_hi:[1,0]
	v_pk_mul_f32 v[136:137], v[136:137], v[142:143] op_sel_hi:[1,0]
	s_waitcnt vmcnt(0)
	v_pk_mul_f32 v[138:139], v[138:139], v[142:143] op_sel_hi:[1,0]
	v_pk_mul_f32 v[140:141], v[142:143], v[140:141] op_sel_hi:[0,1]
	v_cvt_pk_bf16_f32 v178, v134, v135
	v_cvt_pk_bf16_f32 v179, v136, v137
	v_cvt_pk_bf16_f32 v180, v138, v139
	v_cvt_pk_bf16_f32 v181, v140, v141

.LBB0_1774:
	s_or_b64 exec, exec, s[2:3]
	global_load_dwordx4 v[158:161], v[220:221], off offset:1024
	global_load_dwordx4 v[150:153], v[218:219], off offset:1024
	global_load_dwordx4 v[134:137], v[218:219], off offset:1040
	global_load_dwordx4 v[146:149], v[220:221], off offset:1040
	global_load_dwordx4 v[162:165], v[216:217], off offset:1024
	global_load_dwordx4 v[138:141], v[216:217], off offset:1040
	global_load_dwordx4 v[154:157], v[214:215], off offset:1024
	global_load_dwordx4 v[142:145], v[214:215], off offset:1040
	s_nop 0
	s_nop 0
	s_nop 0
	s_nop 0
	s_nop 0
	s_waitcnt vmcnt(8)
	v_mov_b32_dpp v201, v178 row_ror:2 row_mask:0xf bank_mask:0xf
	v_mov_b32_dpp v225, v179 row_ror:2 row_mask:0xf bank_mask:0xf
	s_nop 0
	s_nop 0
	s_nop 0
	v_mov_b32_dpp v1, v178 row_ror:1 row_mask:0xf bank_mask:0xf
	v_mov_b32_dpp v223, v179 row_ror:1 row_mask:0xf bank_mask:0xf
	v_mov_b32_dpp v229, v180 row_ror:2 row_mask:0xf bank_mask:0xf
	v_mov_b32_dpp v201, v174 row_shr:2 row_mask:0xf bank_mask:0xf
	v_mov_b32_dpp v225, v175 row_shr:2 row_mask:0xf bank_mask:0xf
	v_mov_b32_dpp v227, v180 row_ror:1 row_mask:0xf bank_mask:0xf
	v_mov_b32_dpp v237, v181 row_ror:1 row_mask:0xf bank_mask:0xf
	v_mov_b32_dpp v239, v181 row_ror:2 row_mask:0xf bank_mask:0xf
	v_mov_b32_dpp v1, v174 row_shr:1 row_mask:0xf bank_mask:0xf
	v_mov_b32_dpp v223, v175 row_shr:1 row_mask:0xf bank_mask:0xf
	v_mov_b32_dpp v229, v176 row_shr:2 row_mask:0xf bank_mask:0xf
	v_lshlrev_b32_e32 v180, 16, v201
	v_and_b32_e32 v181, 0xffff0000, v201
	v_lshlrev_b32_e32 v224, 16, v225
	v_and_b32_e32 v225, 0xffff0000, v225
	v_mov_b32_dpp v227, v176 row_shr:1 row_mask:0xf bank_mask:0xf
	v_lshlrev_b32_e32 v178, 16, v1
	v_and_b32_e32 v179, 0xffff0000, v1
	v_lshlrev_b32_e32 v222, 16, v223
	v_and_b32_e32 v223, 0xffff0000, v223
	v_lshlrev_b32_e32 v228, 16, v229
	v_and_b32_e32 v229, 0xffff0000, v229
	v_lshlrev_b32_e32 v210, 16, v174
	v_and_b32_e32 v211, 0xffff0000, v174
	v_lshlrev_b32_e32 v214, 16, v175
	v_and_b32_e32 v215, 0xffff0000, v175
	v_lshlrev_b32_e32 v226, 16, v227
	v_and_b32_e32 v227, 0xffff0000, v227
	v_lshlrev_b32_e32 v218, 16, v176
	v_and_b32_e32 v219, 0xffff0000, v176
	v_mov_b32_dpp v239, v177 row_shr:2 row_mask:0xf bank_mask:0xf
	v_pk_mul_f32 v[212:213], v[62:63], v[206:207]
	v_pk_mul_f32 v[216:217], v[64:65], v[206:207]
	v_mov_b32_dpp v237, v177 row_shr:1 row_mask:0xf bank_mask:0xf
	v_lshlrev_b32_e32 v238, 16, v239
	v_and_b32_e32 v239, 0xffff0000, v239
	v_lshlrev_b32_e32 v236, 16, v237
	v_and_b32_e32 v237, 0xffff0000, v237
	v_pk_mul_f32 v[220:221], v[58:59], v[206:207]
	v_pk_mul_f32 v[206:207], v[60:61], v[206:207]
	v_add_u32_e32 v208, 0x100, v208
	v_ashrrev_i32_e32 v209, 31, v208
	s_waitcnt vmcnt(6)
	v_pk_fma_f32 v[180:181], v[150:151], v[180:181], v[158:159]
	v_pk_fma_f32 v[224:225], v[152:153], v[224:225], v[160:161]
	s_waitcnt vmcnt(4)
	v_pk_fma_f32 v[228:229], v[134:135], v[228:229], v[146:147]
	s_waitcnt vmcnt(3)
	v_pk_fma_f32 v[178:179], v[162:163], v[178:179], v[180:181]
	v_pk_fma_f32 v[180:181], v[164:165], v[222:223], v[224:225]
	s_waitcnt vmcnt(2)
	v_pk_fma_f32 v[222:223], v[138:139], v[226:227], v[228:229]
	s_waitcnt vmcnt(1)
	v_pk_fma_f32 v[178:179], v[154:155], v[210:211], v[178:179]
	v_pk_fma_f32 v[180:181], v[156:157], v[214:215], v[180:181]
	s_waitcnt vmcnt(0)
	v_pk_fma_f32 v[210:211], v[142:143], v[218:219], v[222:223]
	v_mul_f32_e32 v1, 0xbfb8aa3b, v178
	v_mul_f32_e32 v201, 0xbfb8aa3b, v179
	v_mul_f32_e32 v214, 0xbfb8aa3b, v180
	v_mul_f32_e32 v215, 0xbfb8aa3b, v181
	v_mul_f32_e32 v218, 0xbfb8aa3b, v210
	v_exp_f32_e32 v1, v1
	v_exp_f32_e32 v201, v201
	v_exp_f32_e32 v214, v214
	v_exp_f32_e32 v215, v215
	v_exp_f32_e32 v218, v218
	v_mul_f32_e32 v219, 0xbfb8aa3b, v211
	v_exp_f32_e32 v222, v219
	v_add_f32_e32 v1, 1.0, v1
	v_add_f32_e32 v201, 1.0, v201
	v_add_f32_e32 v219, 1.0, v214
	v_add_f32_e32 v223, 1.0, v215
	v_add_f32_e32 v224, 1.0, v218
	v_rcp_f32_e32 v214, v1
	v_rcp_f32_e32 v215, v201
	v_rcp_f32_e32 v218, v219
	v_rcp_f32_e32 v219, v223
	v_add_f32_e32 v1, 1.0, v222
	v_pk_mul_f32 v[178:179], v[178:179], v[214:215]
	v_rcp_f32_e32 v223, v1
	v_pk_mul_f32 v[180:181], v[180:181], v[218:219]
	v_pk_mul_f32 v[178:179], v[212:213], v[178:179]
	v_pk_mul_f32 v[180:181], v[216:217], v[180:181]
	v_pk_fma_f32 v[212:213], v[136:137], v[238:239], v[148:149]
	v_cvt_pk_bf16_f32 v178, v178, v179
	v_cvt_pk_bf16_f32 v179, v180, v181
	v_lshlrev_b32_e32 v180, 16, v177
	v_and_b32_e32 v181, 0xffff0000, v177
	v_pk_fma_f32 v[212:213], v[140:141], v[236:237], v[212:213]
	v_rcp_f32_e32 v222, v224
	v_pk_fma_f32 v[180:181], v[144:145], v[180:181], v[212:213]
	v_pk_mul_f32 v[210:211], v[210:211], v[222:223]
	v_mul_f32_e32 v201, 0xbfb8aa3b, v180
	v_exp_f32_e32 v201, v201
	v_mul_f32_e32 v212, 0xbfb8aa3b, v181
	v_exp_f32_e32 v213, v212
	v_pk_mul_f32 v[210:211], v[220:221], v[210:211]
	v_add_f32_e32 v1, 1.0, v201
	v_rcp_f32_e32 v212, v1
	v_add_f32_e32 v1, 1.0, v213
	v_rcp_f32_e32 v213, v1
	s_nop 0
	s_nop 0
	v_pk_mul_f32 v[180:181], v[180:181], v[212:213]
	s_nop 0
	v_pk_mul_f32 v[206:207], v[206:207], v[180:181]
	v_cvt_pk_bf16_f32 v180, v210, v211
	v_cvt_pk_bf16_f32 v181, v206, v207
	global_store_dwordx4 v[230:231], v[178:181], off offset:512
	v_mov_b32_dpp v1, v174 row_ror:1 row_mask:0xf bank_mask:0xf
	s_nop 0
	s_nop 0
	v_mov_b32_dpp v1, v170 row_shr:1 row_mask:0xf bank_mask:0xf
	v_mov_b32_dpp v201, v175 row_ror:1 row_mask:0xf bank_mask:0xf
	v_mov_b32_dpp v179, v174 row_ror:2 row_mask:0xf bank_mask:0xf
	v_mov_b32_dpp v211, v175 row_ror:2 row_mask:0xf bank_mask:0xf
	v_lshlrev_b32_e32 v174, 16, v1
	v_mov_b32_dpp v179, v170 row_shr:2 row_mask:0xf bank_mask:0xf
	v_lshlrev_b32_e32 v178, 16, v179
	v_and_b32_e32 v179, 0xffff0000, v179
	v_and_b32_e32 v175, 0xffff0000, v1
	v_pk_fma_f32 v[178:179], v[150:151], v[178:179], v[158:159]
	v_lshlrev_b32_e32 v180, 16, v170
	v_and_b32_e32 v181, 0xffff0000, v170
	v_pk_fma_f32 v[174:175], v[162:163], v[174:175], v[178:179]
	v_mov_b32_dpp v211, v171 row_shr:2 row_mask:0xf bank_mask:0xf
	v_pk_fma_f32 v[174:175], v[154:155], v[180:181], v[174:175]
	v_mov_b32_dpp v201, v171 row_shr:1 row_mask:0xf bank_mask:0xf
	v_mul_f32_e32 v1, 0xbfb8aa3b, v174
	v_exp_f32_e32 v1, v1
	v_mul_f32_e32 v178, 0xbfb8aa3b, v175
	v_exp_f32_e32 v179, v178
	v_lshlrev_b32_e32 v210, 16, v211
	v_and_b32_e32 v211, 0xffff0000, v211
	v_lshlrev_b32_e32 v206, 16, v201
	v_and_b32_e32 v207, 0xffff0000, v201
	v_pk_fma_f32 v[210:211], v[152:153], v[210:211], v[160:161]
	v_lshlrev_b32_e32 v212, 16, v171
	v_and_b32_e32 v213, 0xffff0000, v171
	v_pk_fma_f32 v[206:207], v[164:165], v[206:207], v[210:211]
	v_add_f32_e32 v1, 1.0, v1
	v_pk_fma_f32 v[206:207], v[156:157], v[212:213], v[206:207]
	v_rcp_f32_e32 v178, v1
	v_add_f32_e32 v1, 1.0, v179
	v_mul_f32_e32 v179, 0xbfb8aa3b, v206
	v_exp_f32_e32 v201, v179
	v_mul_f32_e32 v179, 0xbfb8aa3b, v207
	v_exp_f32_e32 v211, v179
	v_rcp_f32_e32 v179, v1
	v_add_f32_e32 v1, 1.0, v201
	v_rcp_f32_e32 v210, v1
	v_add_f32_e32 v1, 1.0, v211
	v_rcp_f32_e32 v211, v1
	v_pk_mul_f32 v[180:181], v[54:55], v[204:205]
	v_pk_mul_f32 v[174:175], v[174:175], v[178:179]
	v_pk_mul_f32 v[178:179], v[56:57], v[204:205]
	v_pk_mul_f32 v[174:175], v[180:181], v[174:175]
	v_pk_mul_f32 v[180:181], v[206:207], v[210:211]
	v_cvt_pk_bf16_f32 v174, v174, v175
	v_pk_mul_f32 v[178:179], v[178:179], v[180:181]
	s_nop 0
	v_cvt_pk_bf16_f32 v175, v178, v179
	s_nop 0
	v_mov_b32_dpp v1, v176 row_ror:1 row_mask:0xf bank_mask:0xf
	s_nop 0
	v_mov_b32_dpp v179, v176 row_ror:2 row_mask:0xf bank_mask:0xf
	v_mov_b32_dpp v1, v172 row_shr:1 row_mask:0xf bank_mask:0xf
	s_nop 0
	v_mov_b32_dpp v179, v172 row_shr:2 row_mask:0xf bank_mask:0xf
	v_lshlrev_b32_e32 v178, 16, v179
	v_and_b32_e32 v179, 0xffff0000, v179
	v_mov_b32_dpp v201, v177 row_ror:1 row_mask:0xf bank_mask:0xf
	v_mov_b32_dpp v211, v177 row_ror:2 row_mask:0xf bank_mask:0xf
	v_lshlrev_b32_e32 v176, 16, v1
	v_and_b32_e32 v177, 0xffff0000, v1
	v_pk_fma_f32 v[178:179], v[134:135], v[178:179], v[146:147]
	v_lshlrev_b32_e32 v180, 16, v172
	v_and_b32_e32 v181, 0xffff0000, v172
	v_pk_fma_f32 v[176:177], v[138:139], v[176:177], v[178:179]
	v_mov_b32_dpp v211, v173 row_shr:2 row_mask:0xf bank_mask:0xf
	v_pk_fma_f32 v[176:177], v[142:143], v[180:181], v[176:177]
	v_mov_b32_dpp v201, v173 row_shr:1 row_mask:0xf bank_mask:0xf
	v_mul_f32_e32 v1, 0xbfb8aa3b, v176
	v_exp_f32_e32 v1, v1
	v_mul_f32_e32 v178, 0xbfb8aa3b, v177
	v_exp_f32_e32 v179, v178
	v_lshlrev_b32_e32 v210, 16, v211
	v_and_b32_e32 v211, 0xffff0000, v211
	v_lshlrev_b32_e32 v206, 16, v201
	v_and_b32_e32 v207, 0xffff0000, v201
	v_pk_fma_f32 v[210:211], v[136:137], v[210:211], v[148:149]
	v_lshlrev_b32_e32 v212, 16, v173
	v_and_b32_e32 v213, 0xffff0000, v173
	v_pk_fma_f32 v[206:207], v[140:141], v[206:207], v[210:211]
	v_add_f32_e32 v1, 1.0, v1
	v_pk_fma_f32 v[206:207], v[144:145], v[212:213], v[206:207]
	v_rcp_f32_e32 v178, v1
	v_add_f32_e32 v1, 1.0, v179
	v_mul_f32_e32 v179, 0xbfb8aa3b, v206
	v_exp_f32_e32 v201, v179
	v_mul_f32_e32 v179, 0xbfb8aa3b, v207
	v_exp_f32_e32 v211, v179
	v_rcp_f32_e32 v179, v1
	v_add_f32_e32 v1, 1.0, v201
	v_rcp_f32_e32 v210, v1
	v_add_f32_e32 v1, 1.0, v211
	v_rcp_f32_e32 v211, v1
	v_pk_mul_f32 v[180:181], v[50:51], v[204:205]
	v_pk_mul_f32 v[176:177], v[176:177], v[178:179]
	v_pk_mul_f32 v[178:179], v[52:53], v[204:205]
	v_pk_mul_f32 v[176:177], v[180:181], v[176:177]
	v_pk_mul_f32 v[180:181], v[206:207], v[210:211]
	v_cvt_pk_bf16_f32 v176, v176, v177
	v_pk_mul_f32 v[178:179], v[178:179], v[180:181]
	s_nop 0
	v_cvt_pk_bf16_f32 v177, v178, v179
	global_store_dwordx4 v[232:233], v[174:177], off offset:512
	v_mov_b32_dpp v1, v170 row_ror:1 row_mask:0xf bank_mask:0xf
	s_nop 0
	s_nop 0
	v_mov_b32_dpp v1, v166 row_shr:1 row_mask:0xf bank_mask:0xf
	s_nop 0
	v_mov_b32_dpp v175, v170 row_ror:2 row_mask:0xf bank_mask:0xf
	v_mov_b32_dpp v179, v171 row_ror:1 row_mask:0xf bank_mask:0xf
	v_mov_b32_dpp v181, v171 row_ror:2 row_mask:0xf bank_mask:0xf
	v_mov_b32_dpp v175, v166 row_shr:2 row_mask:0xf bank_mask:0xf
	v_lshlrev_b32_e32 v174, 16, v175
	v_and_b32_e32 v175, 0xffff0000, v175
	v_lshlrev_b32_e32 v170, 16, v1
	v_and_b32_e32 v171, 0xffff0000, v1
	v_pk_fma_f32 v[174:175], v[150:151], v[174:175], v[158:159]
	v_lshlrev_b32_e32 v176, 16, v166
	v_and_b32_e32 v177, 0xffff0000, v166
	v_pk_fma_f32 v[170:171], v[162:163], v[170:171], v[174:175]
	v_mov_b32_dpp v181, v167 row_shr:2 row_mask:0xf bank_mask:0xf
	v_pk_fma_f32 v[170:171], v[154:155], v[176:177], v[170:171]
	v_mov_b32_dpp v179, v167 row_shr:1 row_mask:0xf bank_mask:0xf
	v_mul_f32_e32 v1, 0xbfb8aa3b, v170
	v_exp_f32_e32 v1, v1
	v_mul_f32_e32 v174, 0xbfb8aa3b, v171
	v_exp_f32_e32 v175, v174
	v_lshlrev_b32_e32 v180, 16, v181
	v_and_b32_e32 v181, 0xffff0000, v181
	v_lshlrev_b32_e32 v178, 16, v179
	v_and_b32_e32 v179, 0xffff0000, v179
	v_pk_fma_f32 v[180:181], v[152:153], v[180:181], v[160:161]
	v_lshlrev_b32_e32 v204, 16, v167
	v_and_b32_e32 v205, 0xffff0000, v167
	v_pk_fma_f32 v[178:179], v[164:165], v[178:179], v[180:181]
	v_add_f32_e32 v1, 1.0, v1
	v_pk_fma_f32 v[178:179], v[156:157], v[204:205], v[178:179]
	v_rcp_f32_e32 v174, v1
	v_add_f32_e32 v1, 1.0, v175
	v_mul_f32_e32 v175, 0xbfb8aa3b, v178
	v_exp_f32_e32 v180, v175
	v_mul_f32_e32 v175, 0xbfb8aa3b, v179
	v_exp_f32_e32 v181, v175
	v_rcp_f32_e32 v175, v1
	v_add_f32_e32 v1, 1.0, v180
	v_rcp_f32_e32 v180, v1
	v_add_f32_e32 v1, 1.0, v181
	v_rcp_f32_e32 v181, v1
	v_pk_mul_f32 v[176:177], v[42:43], v[202:203]
	v_pk_mul_f32 v[170:171], v[170:171], v[174:175]
	v_pk_mul_f32 v[174:175], v[44:45], v[202:203]
	v_pk_mul_f32 v[170:171], v[176:177], v[170:171]
	v_pk_mul_f32 v[176:177], v[178:179], v[180:181]
	v_cvt_pk_bf16_f32 v170, v170, v171
	v_pk_mul_f32 v[174:175], v[174:175], v[176:177]
	s_nop 0
	v_cvt_pk_bf16_f32 v171, v174, v175
	s_nop 0
	v_mov_b32_dpp v1, v172 row_ror:1 row_mask:0xf bank_mask:0xf
	s_nop 0
	v_mov_b32_dpp v175, v172 row_ror:2 row_mask:0xf bank_mask:0xf
	v_mov_b32_dpp v1, v168 row_shr:1 row_mask:0xf bank_mask:0xf
	s_nop 0
	v_mov_b32_dpp v175, v168 row_shr:2 row_mask:0xf bank_mask:0xf
	v_lshlrev_b32_e32 v174, 16, v175
	v_and_b32_e32 v175, 0xffff0000, v175
	v_mov_b32_dpp v179, v173 row_ror:1 row_mask:0xf bank_mask:0xf
	v_mov_b32_dpp v181, v173 row_ror:2 row_mask:0xf bank_mask:0xf
	v_lshlrev_b32_e32 v172, 16, v1
	v_and_b32_e32 v173, 0xffff0000, v1
	v_pk_fma_f32 v[174:175], v[134:135], v[174:175], v[146:147]
	v_lshlrev_b32_e32 v176, 16, v168
	v_and_b32_e32 v177, 0xffff0000, v168
	v_pk_fma_f32 v[172:173], v[138:139], v[172:173], v[174:175]
	v_mov_b32_dpp v181, v169 row_shr:2 row_mask:0xf bank_mask:0xf
	v_pk_fma_f32 v[172:173], v[142:143], v[176:177], v[172:173]
	v_mov_b32_dpp v179, v169 row_shr:1 row_mask:0xf bank_mask:0xf
	v_mul_f32_e32 v1, 0xbfb8aa3b, v172
	v_exp_f32_e32 v1, v1
	v_mul_f32_e32 v174, 0xbfb8aa3b, v173
	v_exp_f32_e32 v175, v174
	v_lshlrev_b32_e32 v180, 16, v181
	v_and_b32_e32 v181, 0xffff0000, v181
	v_lshlrev_b32_e32 v178, 16, v179
	v_and_b32_e32 v179, 0xffff0000, v179
	v_pk_fma_f32 v[180:181], v[136:137], v[180:181], v[148:149]
	v_lshlrev_b32_e32 v204, 16, v169
	v_and_b32_e32 v205, 0xffff0000, v169
	v_pk_fma_f32 v[178:179], v[140:141], v[178:179], v[180:181]
	v_add_f32_e32 v1, 1.0, v1
	v_pk_fma_f32 v[178:179], v[144:145], v[204:205], v[178:179]
	v_rcp_f32_e32 v174, v1
	v_add_f32_e32 v1, 1.0, v175
	v_mul_f32_e32 v175, 0xbfb8aa3b, v178
	v_exp_f32_e32 v180, v175
	v_mul_f32_e32 v175, 0xbfb8aa3b, v179
	v_exp_f32_e32 v181, v175
	v_rcp_f32_e32 v175, v1
	v_add_f32_e32 v1, 1.0, v180
	v_rcp_f32_e32 v180, v1
	v_add_f32_e32 v1, 1.0, v181
	v_rcp_f32_e32 v181, v1
	v_pk_mul_f32 v[176:177], v[34:35], v[202:203]
	v_pk_mul_f32 v[172:173], v[172:173], v[174:175]
	v_pk_mul_f32 v[174:175], v[36:37], v[202:203]
	v_pk_mul_f32 v[172:173], v[176:177], v[172:173]
	v_pk_mul_f32 v[176:177], v[178:179], v[180:181]
	v_cvt_pk_bf16_f32 v172, v172, v173
	v_pk_mul_f32 v[174:175], v[174:175], v[176:177]
	s_nop 0
	v_cvt_pk_bf16_f32 v173, v174, v175
	global_store_dwordx4 v[234:235], v[170:173], off offset:512
	s_nop 0
	v_mov_b32_dpp v1, v169 row_ror:1 row_mask:0xf bank_mask:0xf
	s_nop 0
	s_nop 0
	s_nop 0
	v_mov_b32_dpp v173, v166 row_ror:1 row_mask:0xf bank_mask:0xf
	v_mov_b32_dpp v174, v166 row_ror:2 row_mask:0xf bank_mask:0xf
	v_mov_b32_dpp v171, v167 row_ror:1 row_mask:0xf bank_mask:0xf
	v_mov_b32_dpp v172, v167 row_ror:2 row_mask:0xf bank_mask:0xf
	s_nop 0
	s_nop 0
	s_nop 0
	v_mov_b32_dpp v166, v168 row_ror:1 row_mask:0xf bank_mask:0xf
	v_mov_b32_dpp v170, v168 row_ror:2 row_mask:0xf bank_mask:0xf
	v_mov_b32_dpp v167, v169 row_ror:2 row_mask:0xf bank_mask:0xf
	v_mov_b32_dpp v173, v130 row_shr:1 row_mask:0xf bank_mask:0xf
	v_mov_b32_dpp v174, v130 row_shr:2 row_mask:0xf bank_mask:0xf
	v_mov_b32_dpp v171, v131 row_shr:1 row_mask:0xf bank_mask:0xf
	v_mov_b32_dpp v172, v131 row_shr:2 row_mask:0xf bank_mask:0xf
	v_mov_b32_dpp v166, v132 row_shr:1 row_mask:0xf bank_mask:0xf
	v_mov_b32_dpp v170, v132 row_shr:2 row_mask:0xf bank_mask:0xf
	v_mov_b32_dpp v1, v133 row_shr:1 row_mask:0xf bank_mask:0xf
	v_mov_b32_dpp v167, v133 row_shr:2 row_mask:0xf bank_mask:0xf
	s_branch .LBB0_1803

.LBB0_1781:
	s_or_b64 exec, exec, s[2:3]
	v_lshlrev_b64 v[146:147], 2, v[202:203]
	v_lshl_add_u64 v[204:205], s[18:19], 0, v[146:147]
	v_lshl_add_u64 v[206:207], s[22:23], 0, v[146:147]
	global_load_dwordx4 v[142:145], v[204:205], off
	global_load_dwordx4 v[166:169], v[206:207], off
	v_lshl_add_u64 v[210:211], s[42:43], 0, v[146:147]
	global_load_dwordx4 v[158:161], v[210:211], off
	v_lshl_add_u64 v[212:213], s[20:21], 0, v[146:147]
	global_load_dwordx4 v[146:149], v[212:213], off
	v_mad_i64_i32 v[230:231], s[2:3], v150, s89, 0
	v_mad_i64_i32 v[228:229], s[2:3], v152, s89, 0
	v_mad_i64_i32 v[226:227], s[2:3], v154, s89, 0
	s_waitcnt lgkmcnt(2)
	v_pk_add_f32 v[150:151], v[162:163], v[170:171]
	v_mov_b64_e32 v[152:153], s[46:47]
	s_waitcnt lgkmcnt(0)
	v_pk_add_f32 v[154:155], v[156:157], v[164:165]
	v_pk_fma_f32 v[216:217], v[150:151], s[44:45], v[152:153] op_sel_hi:[1,0,0]
	v_pk_fma_f32 v[218:219], v[154:155], s[44:45], v[152:153] op_sel_hi:[1,0,0]
	global_load_dwordx4 v[150:153], v[204:205], off offset:16
	global_load_dwordx4 v[154:157], v[210:211], off offset:16
	global_load_dwordx4 v[162:165], v[212:213], off offset:16
	global_load_dwordx4 v[170:173], v[206:207], off offset:16
	v_mad_i64_i32 v[232:233], s[2:3], v198, s89, 0
	s_nop 0
	s_nop 0
	s_nop 0
	s_nop 0
	s_waitcnt vmcnt(8)
	v_mov_b32_dpp v214, v178 row_ror:1 row_mask:0xf bank_mask:0xf
	v_mov_b32_dpp v220, v178 row_ror:2 row_mask:0xf bank_mask:0xf
	v_mov_b32_dpp v221, v179 row_ror:1 row_mask:0xf bank_mask:0xf
	v_mov_b32_dpp v249, v179 row_ror:2 row_mask:0xf bank_mask:0xf
	v_mul_f32_e32 v178, 0x4b800000, v217
	v_mul_f32_e32 v179, 0x4b800000, v216
	v_mul_f32_e32 v236, 0x4b800000, v219
	v_cmp_gt_f32_e64 s[2:3], s90, v217
	v_cmp_gt_f32_e64 s[4:5], s90, v216
	v_cmp_gt_f32_e64 s[6:7], s90, v219
	v_mul_f32_e32 v237, 0x4b800000, v218
	v_mov_b32_dpp v214, v174 row_shr:1 row_mask:0xf bank_mask:0xf
	v_cndmask_b32_e64 v217, v217, v178, s[2:3]
	v_cndmask_b32_e64 v216, v216, v179, s[4:5]
	v_cndmask_b32_e64 v219, v219, v236, s[6:7]
	v_cmp_gt_f32_e64 s[8:9], s90, v218
	v_mov_b32_dpp v220, v174 row_shr:2 row_mask:0xf bank_mask:0xf
	v_lshlrev_b32_e32 v178, 16, v214
	v_cndmask_b32_e64 v218, v218, v237, s[8:9]
	v_and_b32_e32 v179, 0xffff0000, v214
	v_rsq_f32_e32 v214, v217
	v_rsq_f32_e32 v216, v216
	v_rsq_f32_e32 v217, v219
	v_mov_b32_dpp v249, v175 row_shr:2 row_mask:0xf bank_mask:0xf
	v_lshlrev_b32_e32 v236, 16, v220
	v_and_b32_e32 v237, 0xffff0000, v220
	v_rsq_f32_e32 v219, v218
	v_mov_b32_dpp v221, v175 row_shr:1 row_mask:0xf bank_mask:0xf
	v_lshlrev_b32_e32 v250, 16, v249
	v_and_b32_e32 v251, 0xffff0000, v249
	v_lshlrev_b32_e32 v208, 16, v174
	v_and_b32_e32 v209, 0xffff0000, v174
	v_lshlrev_b32_e32 v238, 16, v221
	v_and_b32_e32 v239, 0xffff0000, v221
	v_lshlrev_b32_e32 v234, 16, v175
	v_and_b32_e32 v235, 0xffff0000, v175
	v_mul_f32_e32 v218, 0x45800000, v214
	v_mul_f32_e32 v221, 0x45800000, v216
	v_mul_f32_e32 v249, 0x45800000, v217
	v_mul_f32_e32 v252, 0x45800000, v219
	v_cndmask_b32_e64 v220, v214, v218, s[2:3]
	v_cndmask_b32_e64 v218, v216, v221, s[4:5]
	v_cndmask_b32_e64 v216, v217, v249, s[6:7]
	v_cndmask_b32_e64 v214, v219, v252, s[8:9]
	v_pk_mul_f32 v[126:127], v[126:127], v[220:221] op_sel_hi:[1,0]
	v_pk_mul_f32 v[102:103], v[102:103], v[214:215] op_sel_hi:[1,0]
	v_pk_mul_f32 v[104:105], v[104:105], v[214:215] op_sel_hi:[1,0]
	v_pk_mul_f32 v[98:99], v[98:99], v[214:215] op_sel_hi:[1,0]
	v_pk_mul_f32 v[100:101], v[100:101], v[214:215] op_sel_hi:[1,0]
	s_waitcnt vmcnt(6)
	v_pk_fma_f32 v[236:237], v[142:143], v[236:237], v[166:167]
	v_pk_fma_f32 v[250:251], v[144:145], v[250:251], v[168:169]
	s_waitcnt vmcnt(5)
	v_pk_fma_f32 v[178:179], v[158:159], v[178:179], v[236:237]
	v_pk_fma_f32 v[236:237], v[160:161], v[238:239], v[250:251]
	s_waitcnt vmcnt(4)
	v_pk_fma_f32 v[178:179], v[146:147], v[208:209], v[178:179]
	v_pk_fma_f32 v[208:209], v[148:149], v[234:235], v[236:237]
	v_mul_f32_e32 v217, 0xbfb8aa3b, v178
	v_mul_f32_e32 v219, 0xbfb8aa3b, v179
	v_mul_f32_e32 v221, 0xbfb8aa3b, v208
	v_exp_f32_e32 v217, v217
	v_mul_f32_e32 v234, 0xbfb8aa3b, v209
	v_exp_f32_e32 v219, v219
	v_exp_f32_e32 v221, v221
	v_exp_f32_e32 v237, v234
	v_add_f32_e32 v217, 1.0, v217
	v_add_f32_e32 v219, 1.0, v219
	v_rcp_f32_e32 v234, v217
	v_add_f32_e32 v217, 1.0, v221
	v_rcp_f32_e32 v235, v219
	v_rcp_f32_e32 v236, v217
	v_add_f32_e32 v217, 1.0, v237
	v_rcp_f32_e32 v237, v217
	v_pk_mul_f32 v[178:179], v[178:179], v[234:235]
	v_pk_mul_f32 v[128:129], v[128:129], v[220:221] op_sel_hi:[1,0]
	v_pk_mul_f32 v[126:127], v[126:127], v[178:179]
	v_pk_mul_f32 v[178:179], v[208:209], v[236:237]
	v_cvt_pk_bf16_f32 v126, v126, v127
	v_pk_mul_f32 v[128:129], v[128:129], v[178:179]
	s_nop 0
	v_cvt_pk_bf16_f32 v127, v128, v129
	s_nop 0
	v_mov_b32_dpp v179, v180 row_ror:2 row_mask:0xf bank_mask:0xf
	s_nop 0
	v_mov_b32_dpp v129, v180 row_ror:1 row_mask:0xf bank_mask:0xf
	v_mov_b32_dpp v179, v176 row_shr:2 row_mask:0xf bank_mask:0xf
	s_nop 0
	v_mov_b32_dpp v129, v176 row_shr:1 row_mask:0xf bank_mask:0xf
	v_lshlrev_b32_e32 v178, 16, v179
	v_and_b32_e32 v179, 0xffff0000, v179
	v_mov_b32_dpp v209, v181 row_ror:1 row_mask:0xf bank_mask:0xf
	v_mov_b32_dpp v217, v181 row_ror:2 row_mask:0xf bank_mask:0xf
	v_lshlrev_b32_e32 v128, 16, v129
	v_and_b32_e32 v129, 0xffff0000, v129
	s_waitcnt vmcnt(0)
	v_pk_fma_f32 v[178:179], v[150:151], v[178:179], v[170:171]
	v_mov_b32_dpp v209, v177 row_shr:1 row_mask:0xf bank_mask:0xf
	v_lshlrev_b32_e32 v180, 16, v176
	v_and_b32_e32 v181, 0xffff0000, v176
	v_pk_fma_f32 v[128:129], v[154:155], v[128:129], v[178:179]
	v_mov_b32_dpp v217, v177 row_shr:2 row_mask:0xf bank_mask:0xf
	v_pk_fma_f32 v[128:129], v[162:163], v[180:181], v[128:129]
	v_lshlrev_b32_e32 v180, 16, v209
	v_lshlrev_b32_e32 v208, 16, v217
	v_and_b32_e32 v181, 0xffff0000, v209
	v_and_b32_e32 v209, 0xffff0000, v217
	v_pk_fma_f32 v[208:209], v[152:153], v[208:209], v[172:173]
	v_lshlrev_b32_e32 v234, 16, v177
	v_and_b32_e32 v235, 0xffff0000, v177
	v_pk_fma_f32 v[180:181], v[156:157], v[180:181], v[208:209]
	v_mul_f32_e32 v178, 0xbfb8aa3b, v128
	v_mul_f32_e32 v179, 0xbfb8aa3b, v129
	v_pk_fma_f32 v[180:181], v[164:165], v[234:235], v[180:181]
	v_exp_f32_e32 v178, v178
	v_exp_f32_e32 v179, v179
	v_mul_f32_e32 v208, 0xbfb8aa3b, v180
	v_mul_f32_e32 v209, 0xbfb8aa3b, v181
	v_exp_f32_e32 v208, v208
	v_exp_f32_e32 v209, v209
	v_add_f32_e32 v178, 1.0, v178
	v_add_f32_e32 v179, 1.0, v179
	v_rcp_f32_e32 v178, v178
	v_rcp_f32_e32 v179, v179
	v_add_f32_e32 v208, 1.0, v208
	v_add_f32_e32 v209, 1.0, v209
	v_rcp_f32_e32 v208, v208
	v_rcp_f32_e32 v209, v209
	v_pk_mul_f32 v[122:123], v[122:123], v[220:221] op_sel_hi:[1,0]
	v_pk_mul_f32 v[128:129], v[128:129], v[178:179]
	v_pk_mul_f32 v[124:125], v[124:125], v[220:221] op_sel_hi:[1,0]
	v_pk_mul_f32 v[122:123], v[122:123], v[128:129]
	v_pk_mul_f32 v[128:129], v[180:181], v[208:209]
	v_lshlrev_b64 v[178:179], 1, v[202:203]
	v_pk_mul_f32 v[124:125], v[124:125], v[128:129]
	v_cvt_pk_bf16_f32 v128, v122, v123
	v_cvt_pk_bf16_f32 v129, v124, v125
	v_lshl_add_u64 v[122:123], s[36:37], 0, v[232:233]
	s_nop 0
	v_lshl_add_u64 v[180:181], v[122:123], 0, v[178:179]
	s_nop 0
	v_mov_b32_dpp v125, v174 row_ror:2 row_mask:0xf bank_mask:0xf
	global_store_dwordx4 v[180:181], v[126:129], off
	v_mov_b32_dpp v123, v174 row_ror:1 row_mask:0xf bank_mask:0xf
	v_mov_b32_dpp v125, v138 row_shr:2 row_mask:0xf bank_mask:0xf
	s_nop 0
	v_mov_b32_dpp v123, v138 row_shr:1 row_mask:0xf bank_mask:0xf
	s_nop 0
	v_lshlrev_b32_e32 v124, 16, v125
	v_and_b32_e32 v125, 0xffff0000, v125
	v_mov_b32_dpp v129, v175 row_ror:1 row_mask:0xf bank_mask:0xf
	v_mov_b32_dpp v174, v175 row_ror:2 row_mask:0xf bank_mask:0xf
	v_lshlrev_b32_e32 v122, 16, v123
	v_and_b32_e32 v123, 0xffff0000, v123
	v_pk_fma_f32 v[124:125], v[142:143], v[124:125], v[166:167]
	v_mov_b32_dpp v129, v139 row_shr:1 row_mask:0xf bank_mask:0xf
	v_lshlrev_b32_e32 v126, 16, v138
	v_and_b32_e32 v127, 0xffff0000, v138
	v_pk_fma_f32 v[122:123], v[158:159], v[122:123], v[124:125]
	v_mov_b32_dpp v174, v139 row_shr:2 row_mask:0xf bank_mask:0xf
	v_pk_fma_f32 v[122:123], v[146:147], v[126:127], v[122:123]
	v_lshlrev_b32_e32 v126, 16, v129
	v_lshlrev_b32_e32 v128, 16, v174
	v_and_b32_e32 v127, 0xffff0000, v129
	v_and_b32_e32 v129, 0xffff0000, v174
	v_pk_fma_f32 v[128:129], v[144:145], v[128:129], v[168:169]
	v_lshlrev_b32_e32 v174, 16, v139
	v_and_b32_e32 v175, 0xffff0000, v139
	v_pk_fma_f32 v[126:127], v[160:161], v[126:127], v[128:129]
	v_mul_f32_e32 v124, 0xbfb8aa3b, v122
	v_mul_f32_e32 v125, 0xbfb8aa3b, v123
	v_pk_fma_f32 v[126:127], v[148:149], v[174:175], v[126:127]
	v_exp_f32_e32 v124, v124
	v_exp_f32_e32 v125, v125
	v_mul_f32_e32 v128, 0xbfb8aa3b, v126
	v_mul_f32_e32 v129, 0xbfb8aa3b, v127
	v_exp_f32_e32 v128, v128
	v_exp_f32_e32 v129, v129
	v_add_f32_e32 v124, 1.0, v124
	v_add_f32_e32 v125, 1.0, v125
	v_rcp_f32_e32 v124, v124
	v_rcp_f32_e32 v125, v125
	v_add_f32_e32 v128, 1.0, v128
	v_add_f32_e32 v129, 1.0, v129
	v_rcp_f32_e32 v128, v128
	v_rcp_f32_e32 v129, v129
	v_pk_mul_f32 v[118:119], v[118:119], v[218:219] op_sel_hi:[1,0]
	v_pk_mul_f32 v[122:123], v[122:123], v[124:125]
	v_pk_mul_f32 v[120:121], v[120:121], v[218:219] op_sel_hi:[1,0]
	v_pk_mul_f32 v[118:119], v[118:119], v[122:123]
	v_pk_mul_f32 v[122:123], v[126:127], v[128:129]
	v_cvt_pk_bf16_f32 v118, v118, v119
	v_pk_mul_f32 v[120:121], v[120:121], v[122:123]
	s_nop 0
	v_cvt_pk_bf16_f32 v119, v120, v121
	s_nop 0
	v_mov_b32_dpp v123, v176 row_ror:2 row_mask:0xf bank_mask:0xf
	s_nop 0
	v_mov_b32_dpp v121, v176 row_ror:1 row_mask:0xf bank_mask:0xf
	v_mov_b32_dpp v123, v140 row_shr:2 row_mask:0xf bank_mask:0xf
	s_nop 0
	v_mov_b32_dpp v121, v140 row_shr:1 row_mask:0xf bank_mask:0xf
	v_lshlrev_b32_e32 v122, 16, v123
	v_and_b32_e32 v123, 0xffff0000, v123
	v_mov_b32_dpp v127, v177 row_ror:1 row_mask:0xf bank_mask:0xf
	v_mov_b32_dpp v128, v177 row_ror:2 row_mask:0xf bank_mask:0xf
	v_lshlrev_b32_e32 v120, 16, v121
	v_and_b32_e32 v121, 0xffff0000, v121
	v_pk_fma_f32 v[122:123], v[150:151], v[122:123], v[170:171]
	v_mov_b32_dpp v127, v141 row_shr:1 row_mask:0xf bank_mask:0xf
	v_lshlrev_b32_e32 v124, 16, v140
	v_and_b32_e32 v125, 0xffff0000, v140
	v_pk_fma_f32 v[120:121], v[154:155], v[120:121], v[122:123]
	v_mov_b32_dpp v128, v141 row_shr:2 row_mask:0xf bank_mask:0xf
	v_pk_fma_f32 v[120:121], v[162:163], v[124:125], v[120:121]
	v_lshlrev_b32_e32 v124, 16, v127
	v_lshlrev_b32_e32 v126, 16, v128
	v_and_b32_e32 v125, 0xffff0000, v127
	v_and_b32_e32 v127, 0xffff0000, v128
	v_pk_fma_f32 v[126:127], v[152:153], v[126:127], v[172:173]
	v_lshlrev_b32_e32 v128, 16, v141
	v_and_b32_e32 v129, 0xffff0000, v141
	v_pk_fma_f32 v[124:125], v[156:157], v[124:125], v[126:127]
	v_mul_f32_e32 v122, 0xbfb8aa3b, v120
	v_mul_f32_e32 v123, 0xbfb8aa3b, v121
	v_pk_fma_f32 v[124:125], v[164:165], v[128:129], v[124:125]
	v_exp_f32_e32 v122, v122
	v_exp_f32_e32 v123, v123
	v_mul_f32_e32 v126, 0xbfb8aa3b, v124
	v_mul_f32_e32 v127, 0xbfb8aa3b, v125
	v_exp_f32_e32 v126, v126
	v_exp_f32_e32 v127, v127
	v_add_f32_e32 v122, 1.0, v122
	v_add_f32_e32 v123, 1.0, v123
	v_rcp_f32_e32 v122, v122
	v_rcp_f32_e32 v123, v123
	v_add_f32_e32 v126, 1.0, v126
	v_add_f32_e32 v127, 1.0, v127
	v_rcp_f32_e32 v126, v126
	v_rcp_f32_e32 v127, v127
	v_pk_mul_f32 v[114:115], v[114:115], v[218:219] op_sel_hi:[1,0]
	v_pk_mul_f32 v[120:121], v[120:121], v[122:123]
	v_pk_mul_f32 v[116:117], v[116:117], v[218:219] op_sel_hi:[1,0]
	v_pk_mul_f32 v[114:115], v[114:115], v[120:121]
	v_pk_mul_f32 v[120:121], v[124:125], v[126:127]
	s_nop 0
	v_pk_mul_f32 v[116:117], v[116:117], v[120:121]
	v_cvt_pk_bf16_f32 v120, v114, v115
	v_cvt_pk_bf16_f32 v121, v116, v117
	v_lshl_add_u64 v[114:115], s[36:37], 0, v[230:231]
	s_nop 0
	v_lshl_add_u64 v[174:175], v[114:115], 0, v[178:179]
	s_nop 0
	v_mov_b32_dpp v117, v138 row_ror:2 row_mask:0xf bank_mask:0xf
	global_store_dwordx4 v[174:175], v[118:121], off
	v_mov_b32_dpp v115, v138 row_ror:1 row_mask:0xf bank_mask:0xf
	v_mov_b32_dpp v117, v134 row_shr:2 row_mask:0xf bank_mask:0xf
	s_nop 0
	v_mov_b32_dpp v115, v134 row_shr:1 row_mask:0xf bank_mask:0xf
	v_lshlrev_b32_e32 v116, 16, v117
	v_and_b32_e32 v117, 0xffff0000, v117
	v_mov_b32_dpp v121, v139 row_ror:1 row_mask:0xf bank_mask:0xf
	v_mov_b32_dpp v122, v139 row_ror:2 row_mask:0xf bank_mask:0xf
	v_lshlrev_b32_e32 v114, 16, v115
	v_and_b32_e32 v115, 0xffff0000, v115
	v_pk_fma_f32 v[116:117], v[142:143], v[116:117], v[166:167]
	v_mov_b32_dpp v121, v135 row_shr:1 row_mask:0xf bank_mask:0xf
	v_lshlrev_b32_e32 v118, 16, v134
	v_and_b32_e32 v119, 0xffff0000, v134
	v_pk_fma_f32 v[114:115], v[158:159], v[114:115], v[116:117]
	v_mov_b32_dpp v122, v135 row_shr:2 row_mask:0xf bank_mask:0xf
	v_pk_fma_f32 v[114:115], v[146:147], v[118:119], v[114:115]
	v_lshlrev_b32_e32 v118, 16, v121
	v_lshlrev_b32_e32 v120, 16, v122
	v_and_b32_e32 v119, 0xffff0000, v121
	v_and_b32_e32 v121, 0xffff0000, v122
	v_pk_fma_f32 v[120:121], v[144:145], v[120:121], v[168:169]
	v_lshlrev_b32_e32 v122, 16, v135
	v_and_b32_e32 v123, 0xffff0000, v135
	v_pk_fma_f32 v[118:119], v[160:161], v[118:119], v[120:121]
	v_mul_f32_e32 v116, 0xbfb8aa3b, v114
	v_mul_f32_e32 v117, 0xbfb8aa3b, v115
	v_pk_fma_f32 v[118:119], v[148:149], v[122:123], v[118:119]
	v_exp_f32_e32 v116, v116
	v_exp_f32_e32 v117, v117
	v_mul_f32_e32 v120, 0xbfb8aa3b, v118
	v_mul_f32_e32 v121, 0xbfb8aa3b, v119
	v_exp_f32_e32 v120, v120
	v_exp_f32_e32 v121, v121
	v_add_f32_e32 v116, 1.0, v116
	v_add_f32_e32 v117, 1.0, v117
	v_rcp_f32_e32 v116, v116
	v_rcp_f32_e32 v117, v117
	v_add_f32_e32 v120, 1.0, v120
	v_add_f32_e32 v121, 1.0, v121
	v_rcp_f32_e32 v120, v120
	v_rcp_f32_e32 v121, v121
	v_pk_mul_f32 v[110:111], v[110:111], v[216:217] op_sel_hi:[1,0]
	v_pk_mul_f32 v[114:115], v[114:115], v[116:117]
	v_pk_mul_f32 v[112:113], v[112:113], v[216:217] op_sel_hi:[1,0]
	v_pk_mul_f32 v[110:111], v[110:111], v[114:115]
	v_pk_mul_f32 v[114:115], v[118:119], v[120:121]
	v_cvt_pk_bf16_f32 v110, v110, v111
	v_pk_mul_f32 v[112:113], v[112:113], v[114:115]
	s_nop 0
	v_cvt_pk_bf16_f32 v111, v112, v113
	s_nop 0
	v_mov_b32_dpp v115, v140 row_ror:2 row_mask:0xf bank_mask:0xf
	s_nop 0
	v_mov_b32_dpp v113, v140 row_ror:1 row_mask:0xf bank_mask:0xf
	v_mov_b32_dpp v115, v136 row_shr:2 row_mask:0xf bank_mask:0xf
	s_nop 0
	v_mov_b32_dpp v113, v136 row_shr:1 row_mask:0xf bank_mask:0xf
	v_lshlrev_b32_e32 v114, 16, v115
	v_and_b32_e32 v115, 0xffff0000, v115
	v_mov_b32_dpp v119, v141 row_ror:1 row_mask:0xf bank_mask:0xf
	v_mov_b32_dpp v120, v141 row_ror:2 row_mask:0xf bank_mask:0xf
	v_lshlrev_b32_e32 v112, 16, v113
	v_and_b32_e32 v113, 0xffff0000, v113
	v_pk_fma_f32 v[114:115], v[150:151], v[114:115], v[170:171]
	v_mov_b32_dpp v119, v137 row_shr:1 row_mask:0xf bank_mask:0xf
	v_lshlrev_b32_e32 v116, 16, v136
	v_and_b32_e32 v117, 0xffff0000, v136
	v_pk_fma_f32 v[112:113], v[154:155], v[112:113], v[114:115]
	v_mov_b32_dpp v120, v137 row_shr:2 row_mask:0xf bank_mask:0xf
	v_pk_fma_f32 v[112:113], v[162:163], v[116:117], v[112:113]
	v_lshlrev_b32_e32 v116, 16, v119
	v_lshlrev_b32_e32 v118, 16, v120
	v_and_b32_e32 v117, 0xffff0000, v119
	v_and_b32_e32 v119, 0xffff0000, v120
	v_pk_fma_f32 v[118:119], v[152:153], v[118:119], v[172:173]
	v_lshlrev_b32_e32 v120, 16, v137
	v_and_b32_e32 v121, 0xffff0000, v137
	v_pk_fma_f32 v[116:117], v[156:157], v[116:117], v[118:119]
	v_mul_f32_e32 v114, 0xbfb8aa3b, v112
	v_mul_f32_e32 v115, 0xbfb8aa3b, v113
	v_pk_fma_f32 v[116:117], v[164:165], v[120:121], v[116:117]
	v_exp_f32_e32 v114, v114
	v_exp_f32_e32 v115, v115
	v_mul_f32_e32 v118, 0xbfb8aa3b, v116
	v_mul_f32_e32 v119, 0xbfb8aa3b, v117
	v_exp_f32_e32 v118, v118
	v_exp_f32_e32 v119, v119
	v_add_f32_e32 v114, 1.0, v114
	v_add_f32_e32 v115, 1.0, v115
	v_rcp_f32_e32 v114, v114
	v_rcp_f32_e32 v115, v115
	v_add_f32_e32 v118, 1.0, v118
	v_add_f32_e32 v119, 1.0, v119
	v_rcp_f32_e32 v118, v118
	v_rcp_f32_e32 v119, v119
	v_pk_mul_f32 v[106:107], v[106:107], v[216:217] op_sel_hi:[1,0]
	v_pk_mul_f32 v[112:113], v[112:113], v[114:115]
	v_pk_mul_f32 v[108:109], v[108:109], v[216:217] op_sel_hi:[1,0]
	v_pk_mul_f32 v[106:107], v[106:107], v[112:113]
	v_pk_mul_f32 v[112:113], v[116:117], v[118:119]
	s_nop 0
	v_pk_mul_f32 v[108:109], v[108:109], v[112:113]
	v_cvt_pk_bf16_f32 v112, v106, v107
	v_lshl_add_u64 v[106:107], s[36:37], 0, v[228:229]
	v_lshl_add_u64 v[176:177], v[106:107], 0, v[178:179]
	s_nop 0
	v_cvt_pk_bf16_f32 v113, v108, v109
	s_nop 0
	v_mov_b32_dpp v107, v134 row_ror:2 row_mask:0xf bank_mask:0xf
	global_store_dwordx4 v[176:177], v[110:113], off
	v_mov_b32_dpp v109, v134 row_ror:1 row_mask:0xf bank_mask:0xf
	v_mov_b32_dpp v107, v130 row_shr:2 row_mask:0xf bank_mask:0xf
	v_lshlrev_b32_e32 v106, 16, v107
	v_mov_b32_dpp v109, v130 row_shr:1 row_mask:0xf bank_mask:0xf
	v_and_b32_e32 v107, 0xffff0000, v107
	v_lshlrev_b32_e32 v108, 16, v109
	v_and_b32_e32 v109, 0xffff0000, v109
	v_pk_fma_f32 v[106:107], v[142:143], v[106:107], v[166:167]
	s_nop 0
	v_pk_fma_f32 v[106:107], v[158:159], v[108:109], v[106:107]
	v_lshlrev_b32_e32 v108, 16, v130
	v_and_b32_e32 v109, 0xffff0000, v130
	v_pk_fma_f32 v[106:107], v[146:147], v[108:109], v[106:107]
	s_nop 0
	v_mul_f32_e32 v108, 0xbfb8aa3b, v106
	v_mul_f32_e32 v109, 0xbfb8aa3b, v107
	v_exp_f32_e32 v108, v108
	v_exp_f32_e32 v109, v109
	v_mov_b32_dpp v112, v135 row_ror:2 row_mask:0xf bank_mask:0xf
	v_mov_b32_dpp v110, v135 row_ror:1 row_mask:0xf bank_mask:0xf
	v_add_f32_e32 v108, 1.0, v108
	v_add_f32_e32 v109, 1.0, v109
	v_rcp_f32_e32 v108, v108
	v_rcp_f32_e32 v109, v109
	v_mov_b32_dpp v112, v131 row_shr:2 row_mask:0xf bank_mask:0xf
	v_mov_b32_dpp v110, v131 row_shr:1 row_mask:0xf bank_mask:0xf
	v_lshlrev_b32_e32 v114, 16, v110
	v_pk_mul_f32 v[106:107], v[106:107], v[108:109]
	v_lshlrev_b32_e32 v108, 16, v112
	v_and_b32_e32 v109, 0xffff0000, v112
	v_and_b32_e32 v115, 0xffff0000, v110
	v_pk_fma_f32 v[108:109], v[144:145], v[108:109], v[168:169]
	s_nop 0
	v_pk_fma_f32 v[108:109], v[160:161], v[114:115], v[108:109]
	v_lshlrev_b32_e32 v114, 16, v131
	v_and_b32_e32 v115, 0xffff0000, v131
	v_mov_b32_dpp v118, v136 row_ror:2 row_mask:0xf bank_mask:0xf
	v_pk_fma_f32 v[108:109], v[148:149], v[114:115], v[108:109]
	v_mov_b32_dpp v117, v136 row_ror:1 row_mask:0xf bank_mask:0xf
	v_mov_b32_dpp v118, v132 row_shr:2 row_mask:0xf bank_mask:0xf
	v_mul_f32_e32 v110, 0xbfb8aa3b, v108
	v_mov_b32_dpp v117, v132 row_shr:1 row_mask:0xf bank_mask:0xf
	v_exp_f32_e32 v110, v110
	v_lshlrev_b32_e32 v114, 16, v118
	v_and_b32_e32 v115, 0xffff0000, v118
	v_lshlrev_b32_e32 v116, 16, v117
	v_and_b32_e32 v117, 0xffff0000, v117
	v_pk_fma_f32 v[114:115], v[150:151], v[114:115], v[170:171]
	v_pk_mul_f32 v[102:103], v[102:103], v[106:107]
	v_pk_fma_f32 v[114:115], v[154:155], v[116:117], v[114:115]
	v_lshlrev_b32_e32 v116, 16, v132
	v_and_b32_e32 v117, 0xffff0000, v132
	v_mul_f32_e32 v106, 0xbfb8aa3b, v109
	v_pk_fma_f32 v[114:115], v[162:163], v[116:117], v[114:115]
	v_exp_f32_e32 v107, v106
	v_add_f32_e32 v106, 1.0, v110
	v_mul_f32_e32 v110, 0xbfb8aa3b, v114
	v_exp_f32_e32 v110, v110
	v_mul_f32_e32 v112, 0xbfb8aa3b, v115
	v_exp_f32_e32 v112, v112
	s_nop 0
	v_add_f32_e32 v107, 1.0, v107
	s_nop 0
	v_mov_b32_dpp v120, v137 row_ror:2 row_mask:0xf bank_mask:0xf
	v_rcp_f32_e32 v106, v106
	v_rcp_f32_e32 v107, v107
	v_add_f32_e32 v110, 1.0, v110
	v_mov_b32_dpp v119, v137 row_ror:1 row_mask:0xf bank_mask:0xf
	v_mov_b32_dpp v120, v133 row_shr:2 row_mask:0xf bank_mask:0xf
	v_rcp_f32_e32 v116, v110
	v_add_f32_e32 v110, 1.0, v112
	v_mov_b32_dpp v119, v133 row_shr:1 row_mask:0xf bank_mask:0xf
	v_and_b32_e32 v111, 0xffff0000, v120
	v_rcp_f32_e32 v117, v110
	v_lshlrev_b32_e32 v110, 16, v120
	v_and_b32_e32 v113, 0xffff0000, v119
	v_lshlrev_b32_e32 v112, 16, v119
	v_pk_fma_f32 v[110:111], v[152:153], v[110:111], v[172:173]
	v_pk_mul_f32 v[106:107], v[108:109], v[106:107]
	v_lshlrev_b32_e32 v108, 16, v133
	v_and_b32_e32 v109, 0xffff0000, v133
	v_pk_fma_f32 v[110:111], v[156:157], v[112:113], v[110:111]
	v_pk_mul_f32 v[104:105], v[104:105], v[106:107]
	v_pk_fma_f32 v[108:109], v[164:165], v[108:109], v[110:111]
	v_pk_mul_f32 v[106:107], v[114:115], v[116:117]
	v_mul_f32_e32 v110, 0xbfb8aa3b, v108
	v_exp_f32_e32 v110, v110
	v_mul_f32_e32 v111, 0xbfb8aa3b, v109
	v_exp_f32_e32 v111, v111
	v_pk_mul_f32 v[106:107], v[98:99], v[106:107]
	v_add_f32_e32 v98, 1.0, v110
	v_rcp_f32_e32 v110, v98
	v_add_f32_e32 v98, 1.0, v111
	v_rcp_f32_e32 v111, v98
	v_cvt_pk_bf16_f32 v98, v102, v103
	v_or_b32_e32 v208, 0x80, v202
	v_cvt_pk_bf16_f32 v99, v104, v105
	v_pk_mul_f32 v[102:103], v[108:109], v[110:111]
	v_ashrrev_i32_e32 v209, 31, v208
	v_pk_mul_f32 v[102:103], v[100:101], v[102:103]
	v_cvt_pk_bf16_f32 v100, v106, v107
	v_cvt_pk_bf16_f32 v101, v102, v103
	v_lshl_add_u64 v[102:103], s[36:37], 0, v[226:227]
	v_lshl_add_u64 v[152:153], v[102:103], 0, v[178:179]
	global_store_dwordx4 v[152:153], v[98:101], off
	v_lshlrev_b64 v[150:151], 1, v[208:209]
	s_nop 0
	v_lshl_add_u64 v[98:99], s[24:25], 0, v[232:233]
	v_lshl_add_u64 v[100:101], s[24:25], 0, v[230:231]
	v_lshl_add_u64 v[98:99], v[98:99], 0, v[150:151]
	v_lshl_add_u64 v[100:101], v[100:101], 0, v[150:151]
	global_load_dwordx4 v[142:145], v[98:99], off
	global_load_dwordx4 v[138:141], v[100:101], off
	v_lshl_add_u64 v[98:99], s[24:25], 0, v[228:229]
	v_lshl_add_u64 v[100:101], s[24:25], 0, v[226:227]
	v_lshl_add_u64 v[98:99], v[98:99], 0, v[150:151]
	v_lshl_add_u64 v[100:101], v[100:101], 0, v[150:151]
	global_load_dwordx4 v[102:105], v[98:99], off
	s_nop 0
	global_load_dwordx4 v[98:101], v[100:101], off
	s_and_saveexec_b64 s[2:3], vcc
	s_xor_b64 s[2:3], exec, s[2:3]
	s_cbranch_execz .LBB0_1785
	v_mov_b32_e32 v149, 0
	v_mov_b32_e32 v148, 0
	v_mov_b32_e32 v147, 0
	v_mov_b32_e32 v146, 0
	s_and_saveexec_b64 s[4:5], s[0:1]
	s_cbranch_execz .LBB0_1784
	v_readlane_b32 s6, v254, 11
	v_lshlrev_b32_e32 v106, 2, v215
	v_readlane_b32 s7, v254, 12
	s_nop 4
	global_load_dword v114, v106, s[6:7]
	v_readlane_b32 s6, v254, 19
	v_readlane_b32 s7, v254, 20
	s_waitcnt vmcnt(0)
	v_fmamk_f32 v114, v114, 0x3a800000, v247
	v_lshl_add_u64 v[106:107], s[6:7], 0, v[222:223]
	v_lshl_add_u64 v[110:111], v[202:203], 2, v[106:107]
	global_load_dwordx4 v[106:109], v[110:111], off offset:512
	s_nop 0
	global_load_dwordx4 v[110:113], v[110:111], off offset:528
	v_mul_f32_e32 v115, 0x4b800000, v114
	v_cmp_gt_f32_e32 vcc, s90, v114
	s_nop 1
	v_cndmask_b32_e32 v114, v114, v115, vcc
	v_rsq_f32_e32 v114, v114
	s_nop 0
	v_mul_f32_e32 v115, 0x45800000, v114
	v_cndmask_b32_e32 v114, v114, v115, vcc
	s_waitcnt vmcnt(1)
	v_pk_mul_f32 v[106:107], v[106:107], v[114:115] op_sel_hi:[1,0]
	v_pk_mul_f32 v[108:109], v[108:109], v[114:115] op_sel_hi:[1,0]
	s_waitcnt vmcnt(0)
	v_pk_mul_f32 v[110:111], v[110:111], v[114:115] op_sel_hi:[1,0]
	v_pk_mul_f32 v[112:113], v[114:115], v[112:113] op_sel_hi:[0,1]
	v_cvt_pk_bf16_f32 v146, v106, v107
	v_cvt_pk_bf16_f32 v147, v108, v109
	v_cvt_pk_bf16_f32 v148, v110, v111
	v_cvt_pk_bf16_f32 v149, v112, v113

.LBB0_1787:
	s_or_b64 exec, exec, s[2:3]
	v_lshlrev_b64 v[118:119], 2, v[208:209]
	v_lshl_add_u64 v[154:155], s[18:19], 0, v[118:119]
	v_lshl_add_u64 v[156:157], s[22:23], 0, v[118:119]
	global_load_dwordx4 v[106:109], v[154:155], off offset:16
	global_load_dwordx4 v[122:125], v[154:155], off
	global_load_dwordx4 v[134:137], v[156:157], off
	global_load_dwordx4 v[110:113], v[156:157], off offset:16
	v_lshl_add_u64 v[166:167], s[42:43], 0, v[118:119]
	global_load_dwordx4 v[130:133], v[166:167], off
	global_load_dwordx4 v[114:117], v[166:167], off offset:16
	v_lshl_add_u64 v[168:169], s[20:21], 0, v[118:119]
	global_load_dwordx4 v[126:129], v[168:169], off
	global_load_dwordx4 v[118:121], v[168:169], off offset:16
	s_nop 0
	s_nop 0
	s_nop 0
	s_nop 0
	s_nop 0
	s_waitcnt vmcnt(8)
	v_mov_b32_dpp v164, v146 row_ror:1 row_mask:0xf bank_mask:0xf
	v_mov_b32_dpp v165, v146 row_ror:2 row_mask:0xf bank_mask:0xf
	v_mov_b32_dpp v171, v147 row_ror:1 row_mask:0xf bank_mask:0xf
	v_mov_b32_dpp v172, v147 row_ror:2 row_mask:0xf bank_mask:0xf
	s_nop 0
	s_nop 0
	s_nop 0
	v_mov_b32_dpp v223, v148 row_ror:2 row_mask:0xf bank_mask:0xf
	v_mov_b32_dpp v164, v142 row_shr:1 row_mask:0xf bank_mask:0xf
	v_mov_b32_dpp v165, v142 row_shr:2 row_mask:0xf bank_mask:0xf
	v_mov_b32_dpp v171, v143 row_shr:1 row_mask:0xf bank_mask:0xf
	v_mov_b32_dpp v172, v143 row_shr:2 row_mask:0xf bank_mask:0xf
	v_mov_b32_dpp v173, v148 row_ror:1 row_mask:0xf bank_mask:0xf
	v_mov_b32_dpp v224, v149 row_ror:1 row_mask:0xf bank_mask:0xf
	v_mov_b32_dpp v225, v149 row_ror:2 row_mask:0xf bank_mask:0xf
	v_mov_b32_dpp v223, v144 row_shr:2 row_mask:0xf bank_mask:0xf
	v_lshlrev_b32_e32 v146, 16, v164
	v_lshlrev_b32_e32 v148, 16, v165
	v_and_b32_e32 v147, 0xffff0000, v164
	v_and_b32_e32 v149, 0xffff0000, v165
	v_lshlrev_b32_e32 v164, 16, v171
	v_lshlrev_b32_e32 v170, 16, v172
	v_and_b32_e32 v165, 0xffff0000, v171
	v_and_b32_e32 v171, 0xffff0000, v172
	v_mov_b32_dpp v173, v144 row_shr:1 row_mask:0xf bank_mask:0xf
	v_lshlrev_b32_e32 v222, 16, v223
	v_and_b32_e32 v223, 0xffff0000, v223
	v_lshlrev_b32_e32 v158, 16, v142
	v_and_b32_e32 v159, 0xffff0000, v142
	v_lshlrev_b32_e32 v160, 16, v143
	v_and_b32_e32 v161, 0xffff0000, v143
	v_lshlrev_b32_e32 v172, 16, v173
	v_and_b32_e32 v173, 0xffff0000, v173
	v_lshlrev_b32_e32 v162, 16, v144
	v_and_b32_e32 v163, 0xffff0000, v144
	v_mov_b32_e32 v221, v220
	v_pk_mul_f32 v[94:95], v[94:95], v[220:221]
	v_pk_mul_f32 v[96:97], v[96:97], v[220:221]
	v_mov_b32_dpp v225, v145 row_shr:2 row_mask:0xf bank_mask:0xf
	v_mov_b32_dpp v224, v145 row_shr:1 row_mask:0xf bank_mask:0xf
	v_pk_mul_f32 v[92:93], v[92:93], v[220:221]
	v_pk_mul_f32 v[90:91], v[90:91], v[220:221]
	v_mov_b32_e32 v219, v218
	v_pk_mul_f32 v[86:87], v[86:87], v[218:219]
	v_pk_mul_f32 v[88:89], v[88:89], v[218:219]
	v_pk_mul_f32 v[82:83], v[82:83], v[218:219]
	v_pk_mul_f32 v[84:85], v[84:85], v[218:219]
	v_mov_b32_e32 v217, v216
	v_pk_mul_f32 v[78:79], v[78:79], v[216:217]
	v_pk_mul_f32 v[80:81], v[80:81], v[216:217]
	v_pk_mul_f32 v[74:75], v[74:75], v[216:217]
	v_pk_mul_f32 v[76:77], v[76:77], v[216:217]
	v_mov_b32_e32 v215, v214
	v_pk_mul_f32 v[70:71], v[70:71], v[214:215]
	v_pk_mul_f32 v[72:73], v[72:73], v[214:215]
	v_pk_mul_f32 v[66:67], v[66:67], v[214:215]
	v_pk_mul_f32 v[68:69], v[68:69], v[214:215]
	s_waitcnt vmcnt(5)
	v_pk_fma_f32 v[148:149], v[122:123], v[148:149], v[134:135]
	v_pk_fma_f32 v[170:171], v[124:125], v[170:171], v[136:137]
	s_waitcnt vmcnt(4)
	v_pk_fma_f32 v[222:223], v[106:107], v[222:223], v[110:111]
	s_waitcnt vmcnt(3)
	v_pk_fma_f32 v[146:147], v[130:131], v[146:147], v[148:149]
	v_pk_fma_f32 v[148:149], v[132:133], v[164:165], v[170:171]
	s_waitcnt vmcnt(2)
	v_pk_fma_f32 v[164:165], v[114:115], v[172:173], v[222:223]
	s_waitcnt vmcnt(1)
	v_pk_fma_f32 v[146:147], v[126:127], v[158:159], v[146:147]
	v_pk_fma_f32 v[148:149], v[128:129], v[160:161], v[148:149]
	s_waitcnt vmcnt(0)
	v_pk_fma_f32 v[158:159], v[118:119], v[162:163], v[164:165]
	v_mul_f32_e32 v160, 0xbfb8aa3b, v146
	v_mul_f32_e32 v161, 0xbfb8aa3b, v147
	v_mul_f32_e32 v162, 0xbfb8aa3b, v148
	v_mul_f32_e32 v163, 0xbfb8aa3b, v149
	v_exp_f32_e32 v160, v160
	v_exp_f32_e32 v161, v161
	v_exp_f32_e32 v162, v162
	v_exp_f32_e32 v163, v163
	v_add_f32_e32 v160, 1.0, v160
	v_add_f32_e32 v161, 1.0, v161
	v_add_f32_e32 v162, 1.0, v162
	v_add_f32_e32 v163, 1.0, v163
	v_rcp_f32_e32 v160, v160
	v_rcp_f32_e32 v161, v161
	v_rcp_f32_e32 v162, v162
	v_rcp_f32_e32 v163, v163
	v_mul_f32_e32 v164, 0xbfb8aa3b, v158
	v_pk_mul_f32 v[146:147], v[146:147], v[160:161]
	v_mul_f32_e32 v165, 0xbfb8aa3b, v159
	v_pk_mul_f32 v[148:149], v[148:149], v[162:163]
	v_pk_mul_f32 v[94:95], v[94:95], v[146:147]
	v_pk_mul_f32 v[96:97], v[96:97], v[148:149]
	v_lshlrev_b32_e32 v146, 16, v225
	v_and_b32_e32 v147, 0xffff0000, v225
	v_cvt_pk_bf16_f32 v94, v94, v95
	v_cvt_pk_bf16_f32 v95, v96, v97
	v_lshlrev_b32_e32 v96, 16, v224
	v_and_b32_e32 v97, 0xffff0000, v224
	v_pk_fma_f32 v[146:147], v[108:109], v[146:147], v[112:113]
	v_lshlrev_b32_e32 v148, 16, v145
	v_and_b32_e32 v149, 0xffff0000, v145
	v_pk_fma_f32 v[96:97], v[116:117], v[96:97], v[146:147]
	v_exp_f32_e32 v164, v164
	v_pk_fma_f32 v[96:97], v[120:121], v[148:149], v[96:97]
	v_exp_f32_e32 v165, v165
	v_mul_f32_e32 v146, 0xbfb8aa3b, v96
	v_mul_f32_e32 v147, 0xbfb8aa3b, v97
	v_exp_f32_e32 v146, v146
	v_exp_f32_e32 v147, v147
	v_add_f32_e32 v164, 1.0, v164
	v_add_f32_e32 v160, 1.0, v165
	v_add_f32_e32 v146, 1.0, v146
	v_add_f32_e32 v147, 1.0, v147
	v_rcp_f32_e32 v146, v146
	v_rcp_f32_e32 v147, v147
	v_rcp_f32_e32 v164, v164
	v_rcp_f32_e32 v165, v160
	v_pk_mul_f32 v[96:97], v[96:97], v[146:147]
	s_nop 0
	v_pk_mul_f32 v[92:93], v[92:93], v[96:97]
	v_pk_mul_f32 v[148:149], v[158:159], v[164:165]
	v_cvt_pk_bf16_f32 v97, v92, v93
	v_pk_mul_f32 v[90:91], v[90:91], v[148:149]
	s_nop 0
	v_cvt_pk_bf16_f32 v96, v90, v91
	s_nop 0
	v_mov_b32_dpp v93, v142 row_ror:2 row_mask:0xf bank_mask:0xf
	global_store_dwordx4 v[180:181], v[94:97], off offset:256
	v_mov_b32_dpp v91, v142 row_ror:1 row_mask:0xf bank_mask:0xf
	v_mov_b32_dpp v93, v138 row_shr:2 row_mask:0xf bank_mask:0xf
	s_nop 0
	v_mov_b32_dpp v91, v138 row_shr:1 row_mask:0xf bank_mask:0xf
	s_nop 0
	v_lshlrev_b32_e32 v92, 16, v93
	v_and_b32_e32 v93, 0xffff0000, v93
	v_mov_b32_dpp v97, v143 row_ror:1 row_mask:0xf bank_mask:0xf
	v_mov_b32_dpp v142, v143 row_ror:2 row_mask:0xf bank_mask:0xf
	v_lshlrev_b32_e32 v90, 16, v91
	v_and_b32_e32 v91, 0xffff0000, v91
	v_pk_fma_f32 v[92:93], v[122:123], v[92:93], v[134:135]
	v_mov_b32_dpp v97, v139 row_shr:1 row_mask:0xf bank_mask:0xf
	v_lshlrev_b32_e32 v94, 16, v138
	v_and_b32_e32 v95, 0xffff0000, v138
	v_pk_fma_f32 v[90:91], v[130:131], v[90:91], v[92:93]
	v_mov_b32_dpp v142, v139 row_shr:2 row_mask:0xf bank_mask:0xf
	v_pk_fma_f32 v[90:91], v[126:127], v[94:95], v[90:91]
	v_lshlrev_b32_e32 v94, 16, v97
	v_lshlrev_b32_e32 v96, 16, v142
	v_and_b32_e32 v95, 0xffff0000, v97
	v_and_b32_e32 v97, 0xffff0000, v142
	v_pk_fma_f32 v[96:97], v[124:125], v[96:97], v[136:137]
	v_lshlrev_b32_e32 v142, 16, v139
	v_and_b32_e32 v143, 0xffff0000, v139
	v_pk_fma_f32 v[94:95], v[132:133], v[94:95], v[96:97]
	v_mul_f32_e32 v92, 0xbfb8aa3b, v90
	v_mul_f32_e32 v93, 0xbfb8aa3b, v91
	v_pk_fma_f32 v[94:95], v[128:129], v[142:143], v[94:95]
	v_exp_f32_e32 v92, v92
	v_exp_f32_e32 v93, v93
	v_mul_f32_e32 v96, 0xbfb8aa3b, v94
	v_mul_f32_e32 v97, 0xbfb8aa3b, v95
	v_exp_f32_e32 v96, v96
	v_exp_f32_e32 v97, v97
	v_add_f32_e32 v92, 1.0, v92
	v_add_f32_e32 v93, 1.0, v93
	v_rcp_f32_e32 v92, v92
	v_rcp_f32_e32 v93, v93
	v_add_f32_e32 v96, 1.0, v96
	v_add_f32_e32 v97, 1.0, v97
	v_rcp_f32_e32 v96, v96
	v_rcp_f32_e32 v97, v97
	v_pk_mul_f32 v[90:91], v[90:91], v[92:93]
	v_lshlrev_b32_e32 v92, 16, v140
	v_pk_mul_f32 v[86:87], v[86:87], v[90:91]
	v_pk_mul_f32 v[90:91], v[94:95], v[96:97]
	v_cvt_pk_bf16_f32 v86, v86, v87
	v_pk_mul_f32 v[88:89], v[88:89], v[90:91]
	s_nop 0
	v_cvt_pk_bf16_f32 v87, v88, v89
	s_nop 0
	v_mov_b32_dpp v91, v144 row_ror:2 row_mask:0xf bank_mask:0xf
	s_nop 0
	v_mov_b32_dpp v89, v144 row_ror:1 row_mask:0xf bank_mask:0xf
	v_mov_b32_dpp v91, v140 row_shr:2 row_mask:0xf bank_mask:0xf
	s_nop 0
	v_mov_b32_dpp v89, v140 row_shr:1 row_mask:0xf bank_mask:0xf
	v_lshlrev_b32_e32 v90, 16, v91
	v_and_b32_e32 v91, 0xffff0000, v91
	v_mov_b32_dpp v95, v145 row_ror:1 row_mask:0xf bank_mask:0xf
	v_mov_b32_dpp v96, v145 row_ror:2 row_mask:0xf bank_mask:0xf
	v_lshlrev_b32_e32 v88, 16, v89
	v_and_b32_e32 v89, 0xffff0000, v89
	v_pk_fma_f32 v[90:91], v[106:107], v[90:91], v[110:111]
	v_mov_b32_dpp v95, v141 row_shr:1 row_mask:0xf bank_mask:0xf
	v_and_b32_e32 v93, 0xffff0000, v140
	v_pk_fma_f32 v[88:89], v[114:115], v[88:89], v[90:91]
	v_mov_b32_dpp v96, v141 row_shr:2 row_mask:0xf bank_mask:0xf
	v_pk_fma_f32 v[88:89], v[118:119], v[92:93], v[88:89]
	v_lshlrev_b32_e32 v92, 16, v95
	v_lshlrev_b32_e32 v94, 16, v96
	v_and_b32_e32 v93, 0xffff0000, v95
	v_and_b32_e32 v95, 0xffff0000, v96
	v_pk_fma_f32 v[94:95], v[108:109], v[94:95], v[112:113]
	v_lshlrev_b32_e32 v96, 16, v141
	v_and_b32_e32 v97, 0xffff0000, v141
	v_pk_fma_f32 v[92:93], v[116:117], v[92:93], v[94:95]
	v_mul_f32_e32 v90, 0xbfb8aa3b, v88
	v_mul_f32_e32 v91, 0xbfb8aa3b, v89
	v_pk_fma_f32 v[92:93], v[120:121], v[96:97], v[92:93]
	v_exp_f32_e32 v90, v90
	v_exp_f32_e32 v91, v91
	v_mul_f32_e32 v94, 0xbfb8aa3b, v92
	v_mul_f32_e32 v95, 0xbfb8aa3b, v93
	v_exp_f32_e32 v94, v94
	v_exp_f32_e32 v95, v95
	v_add_f32_e32 v90, 1.0, v90
	v_add_f32_e32 v91, 1.0, v91
	v_rcp_f32_e32 v90, v90
	v_rcp_f32_e32 v91, v91
	v_add_f32_e32 v94, 1.0, v94
	v_add_f32_e32 v95, 1.0, v95
	v_rcp_f32_e32 v94, v94
	v_rcp_f32_e32 v95, v95
	v_pk_mul_f32 v[88:89], v[88:89], v[90:91]
	s_nop 0
	v_pk_mul_f32 v[82:83], v[82:83], v[88:89]
	v_pk_mul_f32 v[88:89], v[92:93], v[94:95]
	v_mov_b32_dpp v90, v139 row_ror:2 row_mask:0xf bank_mask:0xf
	v_pk_mul_f32 v[84:85], v[84:85], v[88:89]
	v_cvt_pk_bf16_f32 v88, v82, v83
	v_cvt_pk_bf16_f32 v89, v84, v85
	s_nop 0
	s_nop 0
	global_store_dwordx4 v[174:175], v[86:89], off offset:256
	v_mov_b32_dpp v85, v138 row_ror:2 row_mask:0xf bank_mask:0xf
	v_mov_b32_dpp v83, v138 row_ror:1 row_mask:0xf bank_mask:0xf
	s_nop 0
	v_mov_b32_dpp v85, v102 row_shr:2 row_mask:0xf bank_mask:0xf
	v_mov_b32_dpp v83, v102 row_shr:1 row_mask:0xf bank_mask:0xf
	v_lshlrev_b32_e32 v84, 16, v85
	v_and_b32_e32 v85, 0xffff0000, v85
	v_mov_b32_dpp v89, v139 row_ror:1 row_mask:0xf bank_mask:0xf
	v_lshlrev_b32_e32 v82, 16, v83
	v_and_b32_e32 v83, 0xffff0000, v83
	v_pk_fma_f32 v[84:85], v[122:123], v[84:85], v[134:135]
	v_mov_b32_dpp v89, v103 row_shr:1 row_mask:0xf bank_mask:0xf
	v_lshlrev_b32_e32 v86, 16, v102
	v_and_b32_e32 v87, 0xffff0000, v102
	v_pk_fma_f32 v[82:83], v[130:131], v[82:83], v[84:85]
	v_mov_b32_dpp v90, v103 row_shr:2 row_mask:0xf bank_mask:0xf
	v_pk_fma_f32 v[82:83], v[126:127], v[86:87], v[82:83]
	v_lshlrev_b32_e32 v86, 16, v89
	v_lshlrev_b32_e32 v88, 16, v90
	v_and_b32_e32 v87, 0xffff0000, v89
	v_and_b32_e32 v89, 0xffff0000, v90
	v_pk_fma_f32 v[88:89], v[124:125], v[88:89], v[136:137]
	v_lshlrev_b32_e32 v90, 16, v103
	v_and_b32_e32 v91, 0xffff0000, v103
	v_pk_fma_f32 v[86:87], v[132:133], v[86:87], v[88:89]
	v_mul_f32_e32 v84, 0xbfb8aa3b, v82
	v_mul_f32_e32 v85, 0xbfb8aa3b, v83
	v_pk_fma_f32 v[86:87], v[128:129], v[90:91], v[86:87]
	v_exp_f32_e32 v84, v84
	v_exp_f32_e32 v85, v85
	v_mul_f32_e32 v88, 0xbfb8aa3b, v86
	v_mul_f32_e32 v89, 0xbfb8aa3b, v87
	v_exp_f32_e32 v88, v88
	v_exp_f32_e32 v89, v89
	v_add_f32_e32 v84, 1.0, v84
	v_add_f32_e32 v85, 1.0, v85
	v_rcp_f32_e32 v84, v84
	v_rcp_f32_e32 v85, v85
	v_add_f32_e32 v88, 1.0, v88
	v_add_f32_e32 v89, 1.0, v89
	v_rcp_f32_e32 v88, v88
	v_rcp_f32_e32 v89, v89
	v_pk_mul_f32 v[82:83], v[82:83], v[84:85]
	v_lshlrev_b32_e32 v84, 16, v104
	v_pk_mul_f32 v[78:79], v[78:79], v[82:83]
	v_pk_mul_f32 v[82:83], v[86:87], v[88:89]
	v_cvt_pk_bf16_f32 v78, v78, v79
	v_pk_mul_f32 v[80:81], v[80:81], v[82:83]
	s_nop 0
	v_cvt_pk_bf16_f32 v79, v80, v81
	s_nop 0
	v_mov_b32_dpp v83, v140 row_ror:2 row_mask:0xf bank_mask:0xf
	s_nop 0
	v_mov_b32_dpp v81, v140 row_ror:1 row_mask:0xf bank_mask:0xf
	v_mov_b32_dpp v83, v104 row_shr:2 row_mask:0xf bank_mask:0xf
	s_nop 0
	v_mov_b32_dpp v81, v104 row_shr:1 row_mask:0xf bank_mask:0xf
	v_lshlrev_b32_e32 v82, 16, v83
	v_and_b32_e32 v83, 0xffff0000, v83
	v_mov_b32_dpp v87, v141 row_ror:1 row_mask:0xf bank_mask:0xf
	v_mov_b32_dpp v88, v141 row_ror:2 row_mask:0xf bank_mask:0xf
	v_lshlrev_b32_e32 v80, 16, v81
	v_and_b32_e32 v81, 0xffff0000, v81
	v_pk_fma_f32 v[82:83], v[106:107], v[82:83], v[110:111]
	v_mov_b32_dpp v87, v105 row_shr:1 row_mask:0xf bank_mask:0xf
	v_and_b32_e32 v85, 0xffff0000, v104
	v_pk_fma_f32 v[80:81], v[114:115], v[80:81], v[82:83]
	v_mov_b32_dpp v88, v105 row_shr:2 row_mask:0xf bank_mask:0xf
	v_pk_fma_f32 v[80:81], v[118:119], v[84:85], v[80:81]
	v_lshlrev_b32_e32 v84, 16, v87
	v_lshlrev_b32_e32 v86, 16, v88
	v_and_b32_e32 v85, 0xffff0000, v87
	v_and_b32_e32 v87, 0xffff0000, v88
	v_pk_fma_f32 v[86:87], v[108:109], v[86:87], v[112:113]
	v_lshlrev_b32_e32 v88, 16, v105
	v_and_b32_e32 v89, 0xffff0000, v105
	v_pk_fma_f32 v[84:85], v[116:117], v[84:85], v[86:87]
	v_mul_f32_e32 v82, 0xbfb8aa3b, v80
	v_mul_f32_e32 v83, 0xbfb8aa3b, v81
	v_pk_fma_f32 v[84:85], v[120:121], v[88:89], v[84:85]
	v_exp_f32_e32 v82, v82
	v_exp_f32_e32 v83, v83
	v_mul_f32_e32 v86, 0xbfb8aa3b, v84
	v_mul_f32_e32 v87, 0xbfb8aa3b, v85
	v_exp_f32_e32 v86, v86
	v_exp_f32_e32 v87, v87
	v_add_f32_e32 v82, 1.0, v82
	v_add_f32_e32 v83, 1.0, v83
	v_rcp_f32_e32 v82, v82
	v_rcp_f32_e32 v83, v83
	v_add_f32_e32 v86, 1.0, v86
	v_add_f32_e32 v87, 1.0, v87
	v_rcp_f32_e32 v86, v86
	v_rcp_f32_e32 v87, v87
	v_pk_mul_f32 v[80:81], v[80:81], v[82:83]
	s_nop 0
	v_pk_mul_f32 v[74:75], v[74:75], v[80:81]
	v_pk_mul_f32 v[80:81], v[84:85], v[86:87]
	s_nop 0
	v_pk_mul_f32 v[76:77], v[76:77], v[80:81]
	v_cvt_pk_bf16_f32 v80, v74, v75
	s_nop 0
	v_cvt_pk_bf16_f32 v81, v76, v77
	s_nop 0
	v_mov_b32_dpp v75, v102 row_ror:2 row_mask:0xf bank_mask:0xf
	global_store_dwordx4 v[176:177], v[78:81], off offset:256
	v_mov_b32_dpp v77, v102 row_ror:1 row_mask:0xf bank_mask:0xf
	v_mov_b32_dpp v75, v98 row_shr:2 row_mask:0xf bank_mask:0xf
	v_lshlrev_b32_e32 v74, 16, v75
	v_mov_b32_dpp v77, v98 row_shr:1 row_mask:0xf bank_mask:0xf
	v_and_b32_e32 v75, 0xffff0000, v75
	v_lshlrev_b32_e32 v76, 16, v77
	v_and_b32_e32 v77, 0xffff0000, v77
	v_pk_fma_f32 v[74:75], v[122:123], v[74:75], v[134:135]
	s_nop 0
	v_pk_fma_f32 v[74:75], v[130:131], v[76:77], v[74:75]
	v_lshlrev_b32_e32 v76, 16, v98
	v_and_b32_e32 v77, 0xffff0000, v98
	v_pk_fma_f32 v[74:75], v[126:127], v[76:77], v[74:75]
	s_nop 0
	v_mul_f32_e32 v76, 0xbfb8aa3b, v74
	v_mul_f32_e32 v77, 0xbfb8aa3b, v75
	v_exp_f32_e32 v76, v76
	v_exp_f32_e32 v77, v77
	v_mov_b32_dpp v80, v103 row_ror:2 row_mask:0xf bank_mask:0xf
	v_mov_b32_dpp v78, v103 row_ror:1 row_mask:0xf bank_mask:0xf
	v_add_f32_e32 v76, 1.0, v76
	v_add_f32_e32 v77, 1.0, v77
	v_rcp_f32_e32 v76, v76
	v_rcp_f32_e32 v77, v77
	v_mov_b32_dpp v80, v99 row_shr:2 row_mask:0xf bank_mask:0xf
	v_mov_b32_dpp v78, v99 row_shr:1 row_mask:0xf bank_mask:0xf
	v_lshlrev_b32_e32 v82, 16, v78
	v_pk_mul_f32 v[74:75], v[74:75], v[76:77]
	v_lshlrev_b32_e32 v76, 16, v80
	v_and_b32_e32 v77, 0xffff0000, v80
	v_and_b32_e32 v83, 0xffff0000, v78
	v_pk_fma_f32 v[76:77], v[124:125], v[76:77], v[136:137]
	s_nop 0
	v_pk_fma_f32 v[76:77], v[132:133], v[82:83], v[76:77]
	v_lshlrev_b32_e32 v82, 16, v99
	v_and_b32_e32 v83, 0xffff0000, v99
	v_mov_b32_dpp v86, v104 row_ror:2 row_mask:0xf bank_mask:0xf
	v_pk_fma_f32 v[76:77], v[128:129], v[82:83], v[76:77]
	v_mov_b32_dpp v85, v104 row_ror:1 row_mask:0xf bank_mask:0xf
	v_mov_b32_dpp v86, v100 row_shr:2 row_mask:0xf bank_mask:0xf
	v_mul_f32_e32 v78, 0xbfb8aa3b, v76
	v_mov_b32_dpp v85, v100 row_shr:1 row_mask:0xf bank_mask:0xf
	v_exp_f32_e32 v78, v78
	v_lshlrev_b32_e32 v82, 16, v86
	v_and_b32_e32 v83, 0xffff0000, v86
	v_lshlrev_b32_e32 v84, 16, v85
	v_and_b32_e32 v85, 0xffff0000, v85
	v_pk_fma_f32 v[82:83], v[106:107], v[82:83], v[110:111]
	v_pk_mul_f32 v[70:71], v[70:71], v[74:75]
	v_pk_fma_f32 v[82:83], v[114:115], v[84:85], v[82:83]
	v_lshlrev_b32_e32 v84, 16, v100
	v_and_b32_e32 v85, 0xffff0000, v100
	v_mul_f32_e32 v74, 0xbfb8aa3b, v77
	v_pk_fma_f32 v[82:83], v[118:119], v[84:85], v[82:83]
	v_exp_f32_e32 v75, v74
	v_add_f32_e32 v74, 1.0, v78
	v_mul_f32_e32 v78, 0xbfb8aa3b, v82
	v_exp_f32_e32 v78, v78
	v_mul_f32_e32 v80, 0xbfb8aa3b, v83
	v_exp_f32_e32 v80, v80
	v_add_f32_e32 v75, 1.0, v75
	s_nop 0
	v_mov_b32_dpp v88, v105 row_ror:2 row_mask:0xf bank_mask:0xf
	v_rcp_f32_e32 v74, v74
	v_rcp_f32_e32 v75, v75
	v_add_f32_e32 v78, 1.0, v78
	v_mov_b32_dpp v87, v105 row_ror:1 row_mask:0xf bank_mask:0xf
	v_mov_b32_dpp v88, v101 row_shr:2 row_mask:0xf bank_mask:0xf
	v_rcp_f32_e32 v84, v78
	v_add_f32_e32 v78, 1.0, v80
	v_mov_b32_dpp v87, v101 row_shr:1 row_mask:0xf bank_mask:0xf
	v_and_b32_e32 v79, 0xffff0000, v88
	v_rcp_f32_e32 v85, v78
	v_lshlrev_b32_e32 v78, 16, v88
	v_and_b32_e32 v81, 0xffff0000, v87
	v_lshlrev_b32_e32 v80, 16, v87
	v_pk_fma_f32 v[78:79], v[108:109], v[78:79], v[112:113]
	v_pk_mul_f32 v[74:75], v[76:77], v[74:75]
	v_lshlrev_b32_e32 v76, 16, v101
	v_and_b32_e32 v77, 0xffff0000, v101
	v_pk_fma_f32 v[78:79], v[116:117], v[80:81], v[78:79]
	v_pk_mul_f32 v[72:73], v[72:73], v[74:75]
	v_pk_fma_f32 v[76:77], v[120:121], v[76:77], v[78:79]
	v_pk_mul_f32 v[74:75], v[82:83], v[84:85]
	v_mul_f32_e32 v78, 0xbfb8aa3b, v76
	v_exp_f32_e32 v78, v78
	v_mul_f32_e32 v79, 0xbfb8aa3b, v77
	v_exp_f32_e32 v79, v79
	v_pk_mul_f32 v[74:75], v[66:67], v[74:75]
	v_add_f32_e32 v66, 1.0, v78
	v_rcp_f32_e32 v78, v66
	v_add_f32_e32 v66, 1.0, v79
	v_rcp_f32_e32 v79, v66
	v_cvt_pk_bf16_f32 v66, v70, v71
	v_add_u32_e32 v118, 0x80, v198
	v_cvt_pk_bf16_f32 v67, v72, v73
	v_pk_mul_f32 v[70:71], v[76:77], v[78:79]
	v_ashrrev_i32_e32 v119, 31, v118
	v_pk_mul_f32 v[70:71], v[68:69], v[70:71]
	v_cvt_pk_bf16_f32 v68, v74, v75
	v_cvt_pk_bf16_f32 v69, v70, v71
	global_store_dwordx4 v[152:153], v[66:69], off offset:256
	v_add_u32_e32 v120, 0x90, v198
	v_ashrrev_i32_e32 v121, 31, v120
	v_lshlrev_b64 v[66:67], 6, v[118:119]
	v_lshl_add_u64 v[66:67], v[190:191], 0, v[66:67]
	global_load_dwordx4 v[74:77], v[66:67], off
	v_lshlrev_b64 v[66:67], 6, v[120:121]
	v_add_u32_e32 v126, 0xa0, v198
	v_lshl_add_u64 v[66:67], v[190:191], 0, v[66:67]
	v_ashrrev_i32_e32 v127, 31, v126
	global_load_dwordx4 v[78:81], v[66:67], off
	v_lshlrev_b64 v[66:67], 6, v[126:127]
	v_add_u32_e32 v132, 0xb0, v198
	v_lshl_add_u64 v[66:67], v[190:191], 0, v[66:67]
	v_ashrrev_i32_e32 v133, 31, v132
	global_load_dwordx4 v[82:85], v[66:67], off
	v_lshlrev_b64 v[66:67], 6, v[132:133]
	v_lshl_add_u64 v[66:67], v[190:191], 0, v[66:67]
	global_load_dwordx4 v[86:89], v[66:67], off
	v_mad_i64_i32 v[66:67], s[2:3], v118, s89, v[200:201]
	v_mad_i64_i32 v[68:69], s[2:3], v120, s89, v[200:201]
	global_load_dwordx4 v[110:113], v[66:67], off
	global_load_dwordx4 v[90:93], v[68:69], off
	v_mad_i64_i32 v[66:67], s[2:3], v126, s89, v[200:201]
	v_mad_i64_i32 v[68:69], s[2:3], v132, s89, v[200:201]
	global_load_dwordx4 v[70:73], v[66:67], off
	s_nop 0
	global_load_dwordx4 v[66:69], v[68:69], off
	s_waitcnt vmcnt(7)
	v_mov_b32_e32 v94, v75
	v_mov_b32_e32 v95, v76
	v_mov_b32_e32 v75, v77
	v_pk_add_f32 v[74:75], v[94:95], v[74:75]
	s_waitcnt vmcnt(6)
	v_mov_b32_e32 v76, v79
	v_mov_b32_e32 v77, v80
	v_mov_b32_e32 v79, v81
	v_pk_add_f32 v[76:77], v[76:77], v[78:79]
	v_mov_b32_e32 v79, v74
	v_mov_b32_e32 v78, v76
	v_mov_b32_e32 v74, v77
	v_pk_add_f32 v[74:75], v[78:79], v[74:75]
	s_waitcnt vmcnt(5)
	v_mov_b32_e32 v78, v83
	v_mov_b32_e32 v79, v84
	v_mov_b32_e32 v83, v85
	s_waitcnt vmcnt(4)
	v_mov_b32_e32 v80, v87
	v_mov_b32_e32 v81, v88
	v_mov_b32_e32 v87, v89
	v_pk_add_f32 v[78:79], v[78:79], v[82:83]
	v_pk_add_f32 v[80:81], v[80:81], v[86:87]
	v_mov_b32_e32 v83, v78
	v_mov_b32_e32 v82, v80
	v_mov_b32_e32 v78, v81
	v_pk_add_f32 v[78:79], v[82:83], v[78:79]
	ds_bpermute_b32 v77, v1, v75
	ds_bpermute_b32 v76, v1, v74
	ds_bpermute_b32 v81, v1, v79
	ds_bpermute_b32 v80, v1, v78
	v_and_b32_e32 v1, 0x1fcf, v118
	v_cmp_gt_u32_e32 vcc, 16, v1
	s_waitcnt lgkmcnt(2)
	v_pk_add_f32 v[134:135], v[74:75], v[76:77]
	ds_bpermute_b32 v139, v199, v135
	s_waitcnt lgkmcnt(1)
	v_pk_add_f32 v[136:137], v[78:79], v[80:81]
	ds_bpermute_b32 v138, v199, v134
	ds_bpermute_b32 v141, v199, v137
	ds_bpermute_b32 v140, v199, v136
	v_mul_hi_u32_u24_e32 v123, 0x2c00, v1
	v_mul_u32_u24_e32 v122, 0x2c00, v1
	s_and_saveexec_b64 s[2:3], vcc
	s_xor_b64 s[4:5], exec, s[2:3]
	s_cbranch_execz .LBB0_1791
	v_mov_b32_e32 v117, 0
	v_mov_b32_e32 v116, 0
	v_mov_b32_e32 v115, 0
	v_mov_b32_e32 v114, 0
	s_and_saveexec_b64 s[6:7], s[0:1]
	s_cbranch_execz .LBB0_1790
	v_readlane_b32 s2, v254, 11
	v_lshlrev_b32_e32 v74, 2, v1
	v_readlane_b32 s3, v254, 12
	s_nop 4
	global_load_dword v82, v74, s[2:3]
	v_readlane_b32 s2, v254, 19
	v_readlane_b32 s3, v254, 20
	s_waitcnt vmcnt(0)
	v_fmamk_f32 v82, v82, 0x3a800000, v247
	v_lshl_add_u64 v[74:75], s[2:3], 0, v[122:123]
	v_lshl_add_u64 v[78:79], v[202:203], 2, v[74:75]
	global_load_dwordx4 v[74:77], v[78:79], off
	s_nop 0
	global_load_dwordx4 v[78:81], v[78:79], off offset:16
	v_mul_f32_e32 v83, 0x4b800000, v82
	v_cmp_gt_f32_e64 s[2:3], s90, v82
	s_nop 1
	v_cndmask_b32_e64 v82, v82, v83, s[2:3]
	v_rsq_f32_e32 v82, v82
	s_nop 0
	v_mul_f32_e32 v83, 0x45800000, v82
	v_cndmask_b32_e64 v82, v82, v83, s[2:3]
	s_waitcnt vmcnt(1)
	v_pk_mul_f32 v[74:75], v[74:75], v[82:83] op_sel_hi:[1,0]
	v_pk_mul_f32 v[76:77], v[76:77], v[82:83] op_sel_hi:[1,0]
	s_waitcnt vmcnt(0)
	v_pk_mul_f32 v[78:79], v[78:79], v[82:83] op_sel_hi:[1,0]
	v_pk_mul_f32 v[80:81], v[82:83], v[80:81] op_sel_hi:[0,1]
	v_cvt_pk_bf16_f32 v114, v74, v75
	v_cvt_pk_bf16_f32 v115, v76, v77
	v_cvt_pk_bf16_f32 v116, v78, v79
	v_cvt_pk_bf16_f32 v117, v80, v81

.LBB0_1793:
	s_or_b64 exec, exec, s[2:3]
	global_load_dwordx4 v[94:97], v[204:205], off
	global_load_dwordx4 v[106:109], v[206:207], off
	global_load_dwordx4 v[102:105], v[210:211], off
	global_load_dwordx4 v[98:101], v[212:213], off
	global_load_dwordx4 v[74:77], v[204:205], off offset:16
	global_load_dwordx4 v[78:81], v[210:211], off offset:16
	global_load_dwordx4 v[82:85], v[212:213], off offset:16
	global_load_dwordx4 v[86:89], v[206:207], off offset:16
	v_mad_i64_i32 v[130:131], s[2:3], v118, s89, 0
	v_mad_i64_i32 v[128:129], s[2:3], v120, s89, 0
	v_mad_i64_i32 v[198:199], s[2:3], v132, s89, 0
	s_waitcnt lgkmcnt(2)
	v_pk_add_f32 v[118:119], v[134:135], v[138:139]
	v_mov_b64_e32 v[120:121], s[46:47]
	s_waitcnt lgkmcnt(0)
	v_pk_add_f32 v[132:133], v[136:137], v[140:141]
	v_mad_i64_i32 v[126:127], s[2:3], v126, s89, 0
	s_nop 0
	s_nop 0
	s_nop 0
	s_nop 0
	v_pk_fma_f32 v[118:119], v[118:119], s[44:45], v[120:121] op_sel_hi:[1,0,0]
	v_pk_fma_f32 v[120:121], v[132:133], s[44:45], v[120:121] op_sel_hi:[1,0,0]
	s_waitcnt vmcnt(8)
	v_mov_b32_dpp v139, v114 row_ror:1 row_mask:0xf bank_mask:0xf
	v_mov_b32_dpp v140, v114 row_ror:2 row_mask:0xf bank_mask:0xf
	v_mov_b32_dpp v141, v115 row_ror:1 row_mask:0xf bank_mask:0xf
	v_mov_b32_dpp v143, v115 row_ror:2 row_mask:0xf bank_mask:0xf
	v_mul_f32_e32 v114, 0x4b800000, v119
	v_mul_f32_e32 v115, 0x4b800000, v118
	v_mul_f32_e32 v133, 0x4b800000, v120
	v_cmp_gt_f32_e64 s[2:3], s90, v119
	v_cmp_gt_f32_e64 s[4:5], s90, v118
	v_cmp_gt_f32_e64 s[8:9], s90, v120
	v_mul_f32_e32 v132, 0x4b800000, v121
	v_cndmask_b32_e64 v114, v119, v114, s[2:3]
	v_cndmask_b32_e64 v115, v118, v115, s[4:5]
	v_cmp_gt_f32_e64 s[6:7], s90, v121
	v_cndmask_b32_e64 v119, v120, v133, s[8:9]
	v_mov_b32_dpp v139, v110 row_shr:1 row_mask:0xf bank_mask:0xf
	v_mov_b32_dpp v140, v110 row_shr:2 row_mask:0xf bank_mask:0xf
	v_cndmask_b32_e64 v118, v121, v132, s[6:7]
	v_rsq_f32_e32 v114, v114
	v_rsq_f32_e32 v115, v115
	v_rsq_f32_e32 v119, v119
	v_mov_b32_dpp v143, v111 row_shr:2 row_mask:0xf bank_mask:0xf
	v_lshlrev_b32_e32 v132, 16, v139
	v_lshlrev_b32_e32 v138, 16, v140
	v_and_b32_e32 v133, 0xffff0000, v139
	v_and_b32_e32 v139, 0xffff0000, v140
	v_rsq_f32_e32 v121, v118
	v_mov_b32_dpp v141, v111 row_shr:1 row_mask:0xf bank_mask:0xf
	v_lshlrev_b32_e32 v142, 16, v143
	v_and_b32_e32 v143, 0xffff0000, v143
	v_lshlrev_b32_e32 v134, 16, v110
	v_and_b32_e32 v135, 0xffff0000, v110
	v_lshlrev_b32_e32 v140, 16, v141
	v_and_b32_e32 v141, 0xffff0000, v141
	v_lshlrev_b32_e32 v136, 16, v111
	v_and_b32_e32 v137, 0xffff0000, v111
	v_mul_f32_e32 v118, 0x45800000, v114
	v_mul_f32_e32 v144, 0x45800000, v115
	v_mul_f32_e32 v146, 0x45800000, v119
	v_mul_f32_e32 v145, 0x45800000, v121
	v_cndmask_b32_e64 v120, v114, v118, s[2:3]
	v_cndmask_b32_e64 v118, v115, v144, s[4:5]
	v_cndmask_b32_e64 v200, v119, v146, s[8:9]
	v_cndmask_b32_e64 v114, v121, v145, s[6:7]
	v_pk_mul_f32 v[62:63], v[62:63], v[120:121] op_sel_hi:[1,0]
	v_pk_mul_f32 v[22:23], v[22:23], v[200:201] op_sel_hi:[1,0]
	v_pk_mul_f32 v[24:25], v[24:25], v[200:201] op_sel_hi:[1,0]
	v_pk_mul_f32 v[14:15], v[14:15], v[200:201] op_sel_hi:[1,0]
	v_pk_mul_f32 v[16:17], v[16:17], v[200:201] op_sel_hi:[1,0]
	s_waitcnt vmcnt(6)
	v_pk_fma_f32 v[138:139], v[94:95], v[138:139], v[106:107]
	v_pk_fma_f32 v[142:143], v[96:97], v[142:143], v[108:109]
	s_waitcnt vmcnt(5)
	v_pk_fma_f32 v[132:133], v[102:103], v[132:133], v[138:139]
	v_pk_fma_f32 v[138:139], v[104:105], v[140:141], v[142:143]
	s_waitcnt vmcnt(4)
	v_pk_fma_f32 v[132:133], v[98:99], v[134:135], v[132:133]
	v_pk_fma_f32 v[134:135], v[100:101], v[136:137], v[138:139]
	v_mul_f32_e32 v115, 0xbfb8aa3b, v132
	v_mul_f32_e32 v119, 0xbfb8aa3b, v133
	v_mul_f32_e32 v121, 0xbfb8aa3b, v134
	v_mul_f32_e32 v136, 0xbfb8aa3b, v135
	v_exp_f32_e32 v115, v115
	v_exp_f32_e32 v119, v119
	v_exp_f32_e32 v121, v121
	v_exp_f32_e32 v136, v136
	v_add_f32_e32 v115, 1.0, v115
	v_add_f32_e32 v119, 1.0, v119
	v_add_f32_e32 v121, 1.0, v121
	v_add_f32_e32 v139, 1.0, v136
	v_rcp_f32_e32 v136, v115
	v_rcp_f32_e32 v137, v119
	v_rcp_f32_e32 v138, v121
	v_rcp_f32_e32 v139, v139
	v_pk_mul_f32 v[64:65], v[64:65], v[120:121] op_sel_hi:[1,0]
	v_pk_mul_f32 v[132:133], v[132:133], v[136:137]
	s_nop 0
	v_pk_mul_f32 v[62:63], v[62:63], v[132:133]
	v_pk_mul_f32 v[132:133], v[134:135], v[138:139]
	v_cvt_pk_bf16_f32 v62, v62, v63
	v_pk_mul_f32 v[64:65], v[64:65], v[132:133]
	v_mov_b32_dpp v115, v116 row_ror:2 row_mask:0xf bank_mask:0xf
	v_cvt_pk_bf16_f32 v63, v64, v65
	s_nop 0
	v_mov_b32_dpp v115, v112 row_shr:2 row_mask:0xf bank_mask:0xf
	s_nop 0
	v_mov_b32_dpp v65, v116 row_ror:1 row_mask:0xf bank_mask:0xf
	s_nop 0
	v_mov_b32_dpp v119, v117 row_ror:1 row_mask:0xf bank_mask:0xf
	v_mov_b32_dpp v65, v112 row_shr:1 row_mask:0xf bank_mask:0xf
	v_mov_b32_dpp v121, v117 row_ror:2 row_mask:0xf bank_mask:0xf
	v_lshlrev_b32_e32 v116, 16, v115
	v_and_b32_e32 v117, 0xffff0000, v115
	v_lshlrev_b32_e32 v64, 16, v65
	v_and_b32_e32 v65, 0xffff0000, v65
	s_waitcnt vmcnt(0)
	v_pk_fma_f32 v[116:117], v[74:75], v[116:117], v[86:87]
	v_lshlrev_b32_e32 v132, 16, v112
	v_and_b32_e32 v133, 0xffff0000, v112
	v_pk_fma_f32 v[64:65], v[78:79], v[64:65], v[116:117]
	v_mov_b32_dpp v121, v113 row_shr:2 row_mask:0xf bank_mask:0xf
	v_pk_fma_f32 v[64:65], v[82:83], v[132:133], v[64:65]
	v_mov_b32_dpp v119, v113 row_shr:1 row_mask:0xf bank_mask:0xf
	v_mul_f32_e32 v115, 0xbfb8aa3b, v64
	v_exp_f32_e32 v115, v115
	v_mul_f32_e32 v116, 0xbfb8aa3b, v65
	v_exp_f32_e32 v117, v116
	v_lshlrev_b32_e32 v134, 16, v121
	v_and_b32_e32 v135, 0xffff0000, v121
	v_lshlrev_b32_e32 v132, 16, v119
	v_and_b32_e32 v133, 0xffff0000, v119
	v_pk_fma_f32 v[134:135], v[76:77], v[134:135], v[88:89]
	v_lshlrev_b32_e32 v136, 16, v113
	v_and_b32_e32 v137, 0xffff0000, v113
	v_pk_fma_f32 v[132:133], v[80:81], v[132:133], v[134:135]
	v_add_f32_e32 v115, 1.0, v115
	v_pk_fma_f32 v[132:133], v[84:85], v[136:137], v[132:133]
	v_rcp_f32_e32 v116, v115
	v_add_f32_e32 v115, 1.0, v117
	v_mul_f32_e32 v117, 0xbfb8aa3b, v132
	v_exp_f32_e32 v119, v117
	v_mul_f32_e32 v117, 0xbfb8aa3b, v133
	v_pk_mul_f32 v[58:59], v[58:59], v[120:121] op_sel_hi:[1,0]
	v_exp_f32_e32 v121, v117
	v_rcp_f32_e32 v117, v115
	v_add_f32_e32 v115, 1.0, v119
	v_rcp_f32_e32 v134, v115
	v_add_f32_e32 v115, 1.0, v121
	v_rcp_f32_e32 v135, v115
	v_pk_mul_f32 v[64:65], v[64:65], v[116:117]
	v_pk_mul_f32 v[60:61], v[60:61], v[120:121] op_sel_hi:[1,0]
	v_pk_mul_f32 v[58:59], v[58:59], v[64:65]
	v_pk_mul_f32 v[64:65], v[132:133], v[134:135]
	s_nop 0
	v_pk_mul_f32 v[60:61], v[60:61], v[64:65]
	v_cvt_pk_bf16_f32 v64, v58, v59
	v_lshl_add_u64 v[58:59], s[36:37], 0, v[130:131]
	v_cvt_pk_bf16_f32 v65, v60, v61
	v_lshl_add_u64 v[58:59], v[58:59], 0, v[178:179]
	global_store_dwordx4 v[58:59], v[62:65], off
	s_nop 0
	s_nop 0
	s_nop 0
	v_mov_b32_dpp v61, v110 row_ror:1 row_mask:0xf bank_mask:0xf
	v_mov_b32_dpp v116, v111 row_ror:2 row_mask:0xf bank_mask:0xf
	v_mov_b32_dpp v63, v110 row_ror:2 row_mask:0xf bank_mask:0xf
	v_mov_b32_dpp v61, v90 row_shr:1 row_mask:0xf bank_mask:0xf
	v_mov_b32_dpp v115, v111 row_ror:1 row_mask:0xf bank_mask:0xf
	v_mov_b32_dpp v63, v90 row_shr:2 row_mask:0xf bank_mask:0xf
	v_lshlrev_b32_e32 v62, 16, v63
	v_and_b32_e32 v63, 0xffff0000, v63
	v_lshlrev_b32_e32 v60, 16, v61
	v_and_b32_e32 v61, 0xffff0000, v61
	v_pk_fma_f32 v[62:63], v[94:95], v[62:63], v[106:107]
	v_mov_b32_dpp v116, v91 row_shr:2 row_mask:0xf bank_mask:0xf
	v_mov_b32_dpp v115, v91 row_shr:1 row_mask:0xf bank_mask:0xf
	v_lshlrev_b32_e32 v64, 16, v90
	v_and_b32_e32 v65, 0xffff0000, v90
	v_pk_fma_f32 v[60:61], v[102:103], v[60:61], v[62:63]
	v_lshlrev_b32_e32 v110, 16, v116
	v_and_b32_e32 v111, 0xffff0000, v116
	v_pk_fma_f32 v[60:61], v[98:99], v[64:65], v[60:61]
	v_lshlrev_b32_e32 v64, 16, v115
	v_and_b32_e32 v65, 0xffff0000, v115
	v_pk_fma_f32 v[110:111], v[96:97], v[110:111], v[108:109]
	v_lshlrev_b32_e32 v116, 16, v91
	v_and_b32_e32 v117, 0xffff0000, v91
	v_pk_fma_f32 v[64:65], v[104:105], v[64:65], v[110:111]
	v_mul_f32_e32 v62, 0xbfb8aa3b, v60
	v_mul_f32_e32 v63, 0xbfb8aa3b, v61
	v_pk_fma_f32 v[64:65], v[100:101], v[116:117], v[64:65]
	v_exp_f32_e32 v62, v62
	v_exp_f32_e32 v63, v63
	v_mul_f32_e32 v110, 0xbfb8aa3b, v64
	v_mul_f32_e32 v111, 0xbfb8aa3b, v65
	v_exp_f32_e32 v110, v110
	v_exp_f32_e32 v111, v111
	v_add_f32_e32 v62, 1.0, v62
	v_add_f32_e32 v63, 1.0, v63
	v_rcp_f32_e32 v62, v62
	v_rcp_f32_e32 v63, v63
	v_add_f32_e32 v110, 1.0, v110
	v_add_f32_e32 v111, 1.0, v111
	v_rcp_f32_e32 v110, v110
	v_rcp_f32_e32 v111, v111
	v_pk_mul_f32 v[54:55], v[54:55], v[118:119] op_sel_hi:[1,0]
	v_pk_mul_f32 v[60:61], v[60:61], v[62:63]
	v_pk_mul_f32 v[56:57], v[56:57], v[118:119] op_sel_hi:[1,0]
	v_pk_mul_f32 v[54:55], v[54:55], v[60:61]
	v_pk_mul_f32 v[60:61], v[64:65], v[110:111]
	v_cvt_pk_bf16_f32 v54, v54, v55
	v_pk_mul_f32 v[56:57], v[56:57], v[60:61]
	s_nop 0
	v_cvt_pk_bf16_f32 v55, v56, v57
	s_nop 0
	v_mov_b32_dpp v61, v112 row_ror:2 row_mask:0xf bank_mask:0xf
	s_nop 0
	v_mov_b32_dpp v57, v112 row_ror:1 row_mask:0xf bank_mask:0xf
	v_mov_b32_dpp v61, v92 row_shr:2 row_mask:0xf bank_mask:0xf
	s_nop 0
	v_mov_b32_dpp v57, v92 row_shr:1 row_mask:0xf bank_mask:0xf
	v_lshlrev_b32_e32 v60, 16, v61
	v_and_b32_e32 v61, 0xffff0000, v61
	v_mov_b32_dpp v65, v113 row_ror:1 row_mask:0xf bank_mask:0xf
	v_mov_b32_dpp v110, v113 row_ror:2 row_mask:0xf bank_mask:0xf
	v_lshlrev_b32_e32 v56, 16, v57
	v_and_b32_e32 v57, 0xffff0000, v57
	v_pk_fma_f32 v[60:61], v[74:75], v[60:61], v[86:87]
	v_mov_b32_dpp v65, v93 row_shr:1 row_mask:0xf bank_mask:0xf
	v_lshlrev_b32_e32 v62, 16, v92
	v_and_b32_e32 v63, 0xffff0000, v92
	v_pk_fma_f32 v[56:57], v[78:79], v[56:57], v[60:61]
	v_mov_b32_dpp v110, v93 row_shr:2 row_mask:0xf bank_mask:0xf
	v_pk_fma_f32 v[56:57], v[82:83], v[62:63], v[56:57]
	v_lshlrev_b32_e32 v62, 16, v65
	v_lshlrev_b32_e32 v64, 16, v110
	v_and_b32_e32 v63, 0xffff0000, v65
	v_and_b32_e32 v65, 0xffff0000, v110
	v_pk_fma_f32 v[64:65], v[76:77], v[64:65], v[88:89]
	v_lshlrev_b32_e32 v110, 16, v93
	v_and_b32_e32 v111, 0xffff0000, v93
	v_pk_fma_f32 v[62:63], v[80:81], v[62:63], v[64:65]
	v_mul_f32_e32 v60, 0xbfb8aa3b, v56
	v_mul_f32_e32 v61, 0xbfb8aa3b, v57
	v_pk_fma_f32 v[62:63], v[84:85], v[110:111], v[62:63]
	v_exp_f32_e32 v60, v60
	v_exp_f32_e32 v61, v61
	v_mul_f32_e32 v64, 0xbfb8aa3b, v62
	v_mul_f32_e32 v65, 0xbfb8aa3b, v63
	v_exp_f32_e32 v64, v64
	v_exp_f32_e32 v65, v65
	v_add_f32_e32 v60, 1.0, v60
	v_add_f32_e32 v61, 1.0, v61
	v_rcp_f32_e32 v60, v60
	v_rcp_f32_e32 v61, v61
	v_add_f32_e32 v64, 1.0, v64
	v_add_f32_e32 v65, 1.0, v65
	v_rcp_f32_e32 v64, v64
	v_rcp_f32_e32 v65, v65
	v_pk_mul_f32 v[50:51], v[50:51], v[118:119] op_sel_hi:[1,0]
	v_pk_mul_f32 v[56:57], v[56:57], v[60:61]
	v_pk_mul_f32 v[52:53], v[52:53], v[118:119] op_sel_hi:[1,0]
	v_pk_mul_f32 v[50:51], v[50:51], v[56:57]
	v_pk_mul_f32 v[56:57], v[62:63], v[64:65]
	s_nop 0
	v_pk_mul_f32 v[52:53], v[52:53], v[56:57]
	v_cvt_pk_bf16_f32 v56, v50, v51
	v_lshl_add_u64 v[50:51], s[36:37], 0, v[128:129]
	v_cvt_pk_bf16_f32 v57, v52, v53
	v_lshl_add_u64 v[52:53], v[50:51], 0, v[178:179]
	global_store_dwordx4 v[52:53], v[54:57], off
	s_nop 0
	s_nop 0
	s_nop 0
	v_mov_b32_dpp v51, v90 row_ror:1 row_mask:0xf bank_mask:0xf
	v_mov_b32_dpp v61, v91 row_ror:1 row_mask:0xf bank_mask:0xf
	v_mov_b32_dpp v55, v90 row_ror:2 row_mask:0xf bank_mask:0xf
	v_mov_b32_dpp v51, v70 row_shr:1 row_mask:0xf bank_mask:0xf
	v_mov_b32_dpp v62, v91 row_ror:2 row_mask:0xf bank_mask:0xf
	v_mov_b32_dpp v55, v70 row_shr:2 row_mask:0xf bank_mask:0xf
	v_lshlrev_b32_e32 v54, 16, v55
	v_and_b32_e32 v55, 0xffff0000, v55
	v_lshlrev_b32_e32 v50, 16, v51
	v_and_b32_e32 v51, 0xffff0000, v51
	v_pk_fma_f32 v[54:55], v[94:95], v[54:55], v[106:107]
	v_mov_b32_dpp v61, v71 row_shr:1 row_mask:0xf bank_mask:0xf
	v_lshlrev_b32_e32 v56, 16, v70
	v_and_b32_e32 v57, 0xffff0000, v70
	v_pk_fma_f32 v[50:51], v[102:103], v[50:51], v[54:55]
	v_mov_b32_dpp v62, v71 row_shr:2 row_mask:0xf bank_mask:0xf
	v_pk_fma_f32 v[50:51], v[98:99], v[56:57], v[50:51]
	v_lshlrev_b32_e32 v56, 16, v61
	v_lshlrev_b32_e32 v60, 16, v62
	v_and_b32_e32 v57, 0xffff0000, v61
	v_and_b32_e32 v61, 0xffff0000, v62
	v_pk_fma_f32 v[60:61], v[96:97], v[60:61], v[108:109]
	v_lshlrev_b32_e32 v62, 16, v71
	v_and_b32_e32 v63, 0xffff0000, v71
	v_pk_fma_f32 v[56:57], v[104:105], v[56:57], v[60:61]
	v_mul_f32_e32 v54, 0xbfb8aa3b, v50
	v_mul_f32_e32 v55, 0xbfb8aa3b, v51
	v_pk_fma_f32 v[56:57], v[100:101], v[62:63], v[56:57]
	v_exp_f32_e32 v54, v54
	v_exp_f32_e32 v55, v55
	v_mul_f32_e32 v60, 0xbfb8aa3b, v56
	v_mul_f32_e32 v61, 0xbfb8aa3b, v57
	v_exp_f32_e32 v60, v60
	v_exp_f32_e32 v61, v61
	v_add_f32_e32 v54, 1.0, v54
	v_add_f32_e32 v55, 1.0, v55
	v_rcp_f32_e32 v54, v54
	v_rcp_f32_e32 v55, v55
	v_add_f32_e32 v60, 1.0, v60
	v_add_f32_e32 v61, 1.0, v61
	v_rcp_f32_e32 v60, v60
	v_rcp_f32_e32 v61, v61
	v_pk_mul_f32 v[42:43], v[42:43], v[114:115] op_sel_hi:[1,0]
	v_pk_mul_f32 v[50:51], v[50:51], v[54:55]
	v_pk_mul_f32 v[44:45], v[44:45], v[114:115] op_sel_hi:[1,0]
	v_pk_mul_f32 v[42:43], v[42:43], v[50:51]
	v_pk_mul_f32 v[50:51], v[56:57], v[60:61]
	v_cvt_pk_bf16_f32 v42, v42, v43
	v_pk_mul_f32 v[44:45], v[44:45], v[50:51]
	s_nop 0
	v_cvt_pk_bf16_f32 v43, v44, v45
	s_nop 0
	v_mov_b32_dpp v51, v92 row_ror:2 row_mask:0xf bank_mask:0xf
	s_nop 0
	v_mov_b32_dpp v45, v92 row_ror:1 row_mask:0xf bank_mask:0xf
	v_mov_b32_dpp v51, v72 row_shr:2 row_mask:0xf bank_mask:0xf
	s_nop 0
	v_mov_b32_dpp v45, v72 row_shr:1 row_mask:0xf bank_mask:0xf
	v_lshlrev_b32_e32 v50, 16, v51
	v_and_b32_e32 v51, 0xffff0000, v51
	v_mov_b32_dpp v57, v93 row_ror:1 row_mask:0xf bank_mask:0xf
	v_mov_b32_dpp v60, v93 row_ror:2 row_mask:0xf bank_mask:0xf
	v_lshlrev_b32_e32 v44, 16, v45
	v_and_b32_e32 v45, 0xffff0000, v45
	v_pk_fma_f32 v[50:51], v[74:75], v[50:51], v[86:87]
	v_mov_b32_dpp v57, v73 row_shr:1 row_mask:0xf bank_mask:0xf
	v_lshlrev_b32_e32 v54, 16, v72
	v_and_b32_e32 v55, 0xffff0000, v72
	v_pk_fma_f32 v[44:45], v[78:79], v[44:45], v[50:51]
	v_mov_b32_dpp v60, v73 row_shr:2 row_mask:0xf bank_mask:0xf
	v_pk_fma_f32 v[44:45], v[82:83], v[54:55], v[44:45]
	v_lshlrev_b32_e32 v54, 16, v57
	v_lshlrev_b32_e32 v56, 16, v60
	v_and_b32_e32 v55, 0xffff0000, v57
	v_and_b32_e32 v57, 0xffff0000, v60
	v_pk_fma_f32 v[56:57], v[76:77], v[56:57], v[88:89]
	v_lshlrev_b32_e32 v60, 16, v73
	v_and_b32_e32 v61, 0xffff0000, v73
	v_pk_fma_f32 v[54:55], v[80:81], v[54:55], v[56:57]
	v_mul_f32_e32 v50, 0xbfb8aa3b, v44
	v_mul_f32_e32 v51, 0xbfb8aa3b, v45
	v_pk_fma_f32 v[54:55], v[84:85], v[60:61], v[54:55]
	v_exp_f32_e32 v50, v50
	v_exp_f32_e32 v51, v51
	v_mul_f32_e32 v56, 0xbfb8aa3b, v54
	v_mul_f32_e32 v57, 0xbfb8aa3b, v55
	v_exp_f32_e32 v56, v56
	v_exp_f32_e32 v57, v57
	v_add_f32_e32 v50, 1.0, v50
	v_add_f32_e32 v51, 1.0, v51
	v_rcp_f32_e32 v50, v50
	v_rcp_f32_e32 v51, v51
	v_add_f32_e32 v56, 1.0, v56
	v_add_f32_e32 v57, 1.0, v57
	v_rcp_f32_e32 v56, v56
	v_rcp_f32_e32 v57, v57
	v_pk_mul_f32 v[34:35], v[34:35], v[114:115] op_sel_hi:[1,0]
	v_pk_mul_f32 v[44:45], v[44:45], v[50:51]
	v_pk_mul_f32 v[36:37], v[36:37], v[114:115] op_sel_hi:[1,0]
	v_pk_mul_f32 v[34:35], v[34:35], v[44:45]
	v_pk_mul_f32 v[44:45], v[54:55], v[56:57]
	s_nop 0
	v_pk_mul_f32 v[36:37], v[36:37], v[44:45]
	v_cvt_pk_bf16_f32 v44, v34, v35
	v_lshl_add_u64 v[34:35], s[36:37], 0, v[126:127]
	v_lshl_add_u64 v[50:51], v[34:35], 0, v[178:179]
	s_nop 0
	v_cvt_pk_bf16_f32 v45, v36, v37
	s_nop 0
	v_mov_b32_dpp v35, v70 row_ror:2 row_mask:0xf bank_mask:0xf
	global_store_dwordx4 v[50:51], v[42:45], off
	v_mov_b32_dpp v37, v70 row_ror:1 row_mask:0xf bank_mask:0xf
	v_mov_b32_dpp v35, v66 row_shr:2 row_mask:0xf bank_mask:0xf
	v_lshlrev_b32_e32 v34, 16, v35
	v_mov_b32_dpp v37, v66 row_shr:1 row_mask:0xf bank_mask:0xf
	v_and_b32_e32 v35, 0xffff0000, v35
	v_lshlrev_b32_e32 v36, 16, v37
	v_and_b32_e32 v37, 0xffff0000, v37
	v_pk_fma_f32 v[34:35], v[94:95], v[34:35], v[106:107]
	s_nop 0
	v_pk_fma_f32 v[34:35], v[102:103], v[36:37], v[34:35]
	v_lshlrev_b32_e32 v36, 16, v66
	v_and_b32_e32 v37, 0xffff0000, v66
	v_pk_fma_f32 v[34:35], v[98:99], v[36:37], v[34:35]
	s_nop 0
	v_mul_f32_e32 v36, 0xbfb8aa3b, v34
	v_mul_f32_e32 v37, 0xbfb8aa3b, v35
	v_exp_f32_e32 v36, v36
	v_exp_f32_e32 v37, v37
	v_mov_b32_dpp v44, v71 row_ror:2 row_mask:0xf bank_mask:0xf
	v_mov_b32_dpp v42, v71 row_ror:1 row_mask:0xf bank_mask:0xf
	v_add_f32_e32 v36, 1.0, v36
	v_add_f32_e32 v37, 1.0, v37
	v_rcp_f32_e32 v36, v36
	v_rcp_f32_e32 v37, v37
	v_mov_b32_dpp v44, v67 row_shr:2 row_mask:0xf bank_mask:0xf
	v_mov_b32_dpp v42, v67 row_shr:1 row_mask:0xf bank_mask:0xf
	v_lshlrev_b32_e32 v54, 16, v42
	v_pk_mul_f32 v[34:35], v[34:35], v[36:37]
	v_lshlrev_b32_e32 v36, 16, v44
	v_and_b32_e32 v37, 0xffff0000, v44
	v_and_b32_e32 v55, 0xffff0000, v42
	v_pk_fma_f32 v[36:37], v[96:97], v[36:37], v[108:109]
	s_nop 0
	v_pk_fma_f32 v[36:37], v[104:105], v[54:55], v[36:37]
	v_lshlrev_b32_e32 v54, 16, v67
	v_and_b32_e32 v55, 0xffff0000, v67
	v_mov_b32_dpp v60, v72 row_ror:2 row_mask:0xf bank_mask:0xf
	v_pk_fma_f32 v[36:37], v[100:101], v[54:55], v[36:37]
	v_mov_b32_dpp v57, v72 row_ror:1 row_mask:0xf bank_mask:0xf
	v_mov_b32_dpp v60, v68 row_shr:2 row_mask:0xf bank_mask:0xf
	v_mul_f32_e32 v42, 0xbfb8aa3b, v36
	v_mov_b32_dpp v57, v68 row_shr:1 row_mask:0xf bank_mask:0xf
	v_exp_f32_e32 v42, v42
	v_lshlrev_b32_e32 v54, 16, v60
	v_and_b32_e32 v55, 0xffff0000, v60
	v_lshlrev_b32_e32 v56, 16, v57
	v_and_b32_e32 v57, 0xffff0000, v57
	v_pk_fma_f32 v[54:55], v[74:75], v[54:55], v[86:87]
	v_pk_mul_f32 v[22:23], v[22:23], v[34:35]
	v_pk_fma_f32 v[54:55], v[78:79], v[56:57], v[54:55]
	v_lshlrev_b32_e32 v56, 16, v68
	v_and_b32_e32 v57, 0xffff0000, v68
	v_mul_f32_e32 v34, 0xbfb8aa3b, v37
	v_pk_fma_f32 v[54:55], v[82:83], v[56:57], v[54:55]
	v_exp_f32_e32 v35, v34
	v_add_f32_e32 v34, 1.0, v42
	v_mul_f32_e32 v42, 0xbfb8aa3b, v54
	v_exp_f32_e32 v42, v42
	v_mul_f32_e32 v44, 0xbfb8aa3b, v55
	v_exp_f32_e32 v44, v44
	s_nop 0
	v_add_f32_e32 v35, 1.0, v35
	s_nop 0
	v_mov_b32_dpp v62, v73 row_ror:2 row_mask:0xf bank_mask:0xf
	v_rcp_f32_e32 v34, v34
	v_rcp_f32_e32 v35, v35
	v_add_f32_e32 v42, 1.0, v42
	v_mov_b32_dpp v61, v73 row_ror:1 row_mask:0xf bank_mask:0xf
	v_mov_b32_dpp v62, v69 row_shr:2 row_mask:0xf bank_mask:0xf
	v_rcp_f32_e32 v56, v42
	v_add_f32_e32 v42, 1.0, v44
	v_mov_b32_dpp v61, v69 row_shr:1 row_mask:0xf bank_mask:0xf
	v_and_b32_e32 v43, 0xffff0000, v62
	v_rcp_f32_e32 v57, v42
	v_lshlrev_b32_e32 v42, 16, v62
	v_and_b32_e32 v45, 0xffff0000, v61
	v_lshlrev_b32_e32 v44, 16, v61
	v_pk_fma_f32 v[42:43], v[76:77], v[42:43], v[88:89]
	v_pk_mul_f32 v[34:35], v[36:37], v[34:35]
	v_lshlrev_b32_e32 v36, 16, v69
	v_and_b32_e32 v37, 0xffff0000, v69
	v_pk_fma_f32 v[42:43], v[80:81], v[44:45], v[42:43]
	v_pk_mul_f32 v[24:25], v[24:25], v[34:35]
	v_pk_fma_f32 v[36:37], v[84:85], v[36:37], v[42:43]
	v_pk_mul_f32 v[34:35], v[54:55], v[56:57]
	v_mul_f32_e32 v42, 0xbfb8aa3b, v36
	v_exp_f32_e32 v42, v42
	v_mul_f32_e32 v43, 0xbfb8aa3b, v37
	v_exp_f32_e32 v43, v43
	v_pk_mul_f32 v[34:35], v[14:15], v[34:35]
	v_add_f32_e32 v14, 1.0, v42
	v_rcp_f32_e32 v42, v14
	v_add_f32_e32 v14, 1.0, v43
	v_rcp_f32_e32 v43, v14
	v_cvt_pk_bf16_f32 v14, v22, v23
	v_cvt_pk_bf16_f32 v15, v24, v25
	v_pk_mul_f32 v[22:23], v[36:37], v[42:43]
	s_nop 0
	v_pk_mul_f32 v[22:23], v[16:17], v[22:23]
	v_cvt_pk_bf16_f32 v16, v34, v35
	v_cvt_pk_bf16_f32 v17, v22, v23
	v_lshl_add_u64 v[22:23], s[36:37], 0, v[198:199]
	v_lshl_add_u64 v[22:23], v[22:23], 0, v[178:179]
	global_store_dwordx4 v[22:23], v[14:17], off
	s_nop 1
	v_lshl_add_u64 v[14:15], s[24:25], 0, v[130:131]
	v_lshl_add_u64 v[14:15], v[14:15], 0, v[150:151]
	v_lshl_add_u64 v[16:17], s[24:25], 0, v[128:129]
	v_lshl_add_u64 v[16:17], v[16:17], 0, v[150:151]
	global_load_dwordx4 v[34:37], v[14:15], off
	global_load_dwordx4 v[22:25], v[16:17], off
	v_lshl_add_u64 v[14:15], s[24:25], 0, v[126:127]
	v_lshl_add_u64 v[14:15], v[14:15], 0, v[150:151]
	v_lshl_add_u64 v[16:17], s[24:25], 0, v[198:199]
	v_lshl_add_u64 v[42:43], v[16:17], 0, v[150:151]
	global_load_dwordx4 v[14:17], v[14:15], off
	s_nop 0
	global_load_dwordx4 v[130:133], v[42:43], off
	s_and_saveexec_b64 s[2:3], vcc
	s_xor_b64 s[2:3], exec, s[2:3]
	s_cbranch_execz .LBB0_1797
	v_mov_b32_e32 v45, 0
	v_mov_b32_e32 v44, 0
	v_mov_b32_e32 v43, 0
	v_mov_b32_e32 v42, 0
	s_and_saveexec_b64 s[4:5], s[0:1]
	s_cbranch_execz .LBB0_1796
	v_readlane_b32 s6, v254, 11
	v_lshlrev_b32_e32 v1, 2, v1
	v_readlane_b32 s7, v254, 12
	s_nop 4
	global_load_dword v1, v1, s[6:7]
	v_readlane_b32 s6, v254, 19
	v_readlane_b32 s7, v254, 20
	s_waitcnt vmcnt(0)
	v_fmamk_f32 v1, v1, 0x3a800000, v247
	v_lshl_add_u64 v[42:43], s[6:7], 0, v[122:123]
	v_lshl_add_u64 v[54:55], v[202:203], 2, v[42:43]
	global_load_dwordx4 v[42:45], v[54:55], off offset:512
	s_nop 0
	global_load_dwordx4 v[54:57], v[54:55], off offset:528
	v_mul_f32_e32 v60, 0x4b800000, v1
	v_cmp_gt_f32_e32 vcc, s90, v1
	s_nop 1
	v_cndmask_b32_e32 v1, v1, v60, vcc
	v_rsq_f32_e32 v1, v1
	s_nop 0
	v_mul_f32_e32 v60, 0x45800000, v1
	v_cndmask_b32_e32 v60, v1, v60, vcc
	s_waitcnt vmcnt(1)
	v_pk_mul_f32 v[42:43], v[42:43], v[60:61] op_sel_hi:[1,0]
	v_pk_mul_f32 v[44:45], v[44:45], v[60:61] op_sel_hi:[1,0]
	s_waitcnt vmcnt(0)
	v_pk_mul_f32 v[54:55], v[54:55], v[60:61] op_sel_hi:[1,0]
	v_pk_mul_f32 v[56:57], v[60:61], v[56:57] op_sel_hi:[0,1]
	v_cvt_pk_bf16_f32 v42, v42, v43
	v_cvt_pk_bf16_f32 v43, v44, v45
	v_cvt_pk_bf16_f32 v44, v54, v55
	v_cvt_pk_bf16_f32 v45, v56, v57

.LBB0_1799:
	s_or_b64 exec, exec, s[2:3]
	global_load_dwordx4 v[158:161], v[156:157], off
	global_load_dwordx4 v[150:153], v[154:155], off
	global_load_dwordx4 v[134:137], v[154:155], off offset:16
	global_load_dwordx4 v[146:149], v[156:157], off offset:16
	global_load_dwordx4 v[162:165], v[166:167], off
	global_load_dwordx4 v[138:141], v[166:167], off offset:16
	s_nop 0
	global_load_dwordx4 v[154:157], v[168:169], off
	global_load_dwordx4 v[142:145], v[168:169], off offset:16
	s_nop 0
	s_nop 0
	s_nop 0
	s_nop 0
	s_nop 0
	s_waitcnt vmcnt(8)
	v_mov_b32_dpp v62, v42 row_ror:2 row_mask:0xf bank_mask:0xf
	v_mov_b32_dpp v65, v43 row_ror:2 row_mask:0xf bank_mask:0xf
	v_mov_b32_e32 v121, v120
	s_nop 0
	v_mov_b32_dpp v1, v42 row_ror:1 row_mask:0xf bank_mask:0xf
	v_mov_b32_dpp v63, v43 row_ror:1 row_mask:0xf bank_mask:0xf
	v_mov_b32_dpp v69, v44 row_ror:2 row_mask:0xf bank_mask:0xf
	v_mov_b32_dpp v62, v34 row_shr:2 row_mask:0xf bank_mask:0xf
	v_mov_b32_dpp v65, v35 row_shr:2 row_mask:0xf bank_mask:0xf
	s_nop 0
	s_nop 0
	v_pk_mul_f32 v[42:43], v[46:47], v[120:121]
	v_pk_mul_f32 v[46:47], v[48:49], v[120:121]
	v_mov_b32_dpp v67, v44 row_ror:1 row_mask:0xf bank_mask:0xf
	v_mov_b32_dpp v1, v34 row_shr:1 row_mask:0xf bank_mask:0xf
	v_mov_b32_dpp v63, v35 row_shr:1 row_mask:0xf bank_mask:0xf
	v_mov_b32_dpp v69, v36 row_shr:2 row_mask:0xf bank_mask:0xf
	v_lshlrev_b32_e32 v48, 16, v62
	v_and_b32_e32 v49, 0xffff0000, v62
	v_lshlrev_b32_e32 v64, 16, v65
	v_and_b32_e32 v65, 0xffff0000, v65
	v_mov_b32_dpp v71, v45 row_ror:1 row_mask:0xf bank_mask:0xf
	v_mov_b32_dpp v73, v45 row_ror:2 row_mask:0xf bank_mask:0xf
	v_pk_mul_f32 v[44:45], v[38:39], v[120:121]
	v_mov_b32_dpp v67, v36 row_shr:1 row_mask:0xf bank_mask:0xf
	v_lshlrev_b32_e32 v38, 16, v1
	v_and_b32_e32 v39, 0xffff0000, v1
	v_lshlrev_b32_e32 v62, 16, v63
	v_and_b32_e32 v63, 0xffff0000, v63
	v_lshlrev_b32_e32 v68, 16, v69
	v_and_b32_e32 v69, 0xffff0000, v69
	v_lshlrev_b32_e32 v54, 16, v34
	v_and_b32_e32 v55, 0xffff0000, v34
	v_lshlrev_b32_e32 v56, 16, v35
	v_and_b32_e32 v57, 0xffff0000, v35
	v_lshlrev_b32_e32 v66, 16, v67
	v_and_b32_e32 v67, 0xffff0000, v67
	v_lshlrev_b32_e32 v60, 16, v36
	v_and_b32_e32 v61, 0xffff0000, v36
	v_mov_b32_dpp v73, v37 row_shr:2 row_mask:0xf bank_mask:0xf
	v_mov_b32_dpp v71, v37 row_shr:1 row_mask:0xf bank_mask:0xf
	v_lshlrev_b32_e32 v72, 16, v73
	v_and_b32_e32 v73, 0xffff0000, v73
	v_lshlrev_b32_e32 v70, 16, v71
	v_and_b32_e32 v71, 0xffff0000, v71
	v_pk_mul_f32 v[40:41], v[40:41], v[120:121]
	v_mov_b32_e32 v119, v118
	v_pk_mul_f32 v[30:31], v[30:31], v[118:119]
	v_pk_mul_f32 v[32:33], v[32:33], v[118:119]
	v_pk_mul_f32 v[26:27], v[26:27], v[118:119]
	v_pk_mul_f32 v[28:29], v[28:29], v[118:119]
	v_mov_b32_e32 v115, v114
	v_pk_mul_f32 v[18:19], v[18:19], v[114:115]
	v_pk_mul_f32 v[20:21], v[20:21], v[114:115]
	v_pk_mul_f32 v[10:11], v[10:11], v[114:115]
	v_pk_mul_f32 v[12:13], v[12:13], v[114:115]
	s_nop 0
	s_nop 0
	s_nop 0
	s_nop 0
	s_nop 0
	v_mov_b32_e32 v170, 0
	v_mov_b32_e32 v167, 0
	v_mov_b32_dpp v173, v14 row_ror:1 row_mask:0xf bank_mask:0xf
	v_mov_b32_dpp v174, v14 row_ror:2 row_mask:0xf bank_mask:0xf
	v_mov_b32_dpp v171, v15 row_ror:1 row_mask:0xf bank_mask:0xf
	v_mov_b32_dpp v172, v15 row_ror:2 row_mask:0xf bank_mask:0xf
	v_mov_b32_dpp v166, v16 row_ror:1 row_mask:0xf bank_mask:0xf
	s_waitcnt vmcnt(6)
	v_pk_fma_f32 v[48:49], v[150:151], v[48:49], v[158:159]
	v_pk_fma_f32 v[64:65], v[152:153], v[64:65], v[160:161]
	s_waitcnt vmcnt(4)
	v_pk_fma_f32 v[68:69], v[134:135], v[68:69], v[146:147]
	s_waitcnt vmcnt(3)
	v_pk_fma_f32 v[38:39], v[162:163], v[38:39], v[48:49]
	v_pk_fma_f32 v[48:49], v[164:165], v[62:63], v[64:65]
	s_waitcnt vmcnt(2)
	v_pk_fma_f32 v[62:63], v[138:139], v[66:67], v[68:69]
	s_waitcnt vmcnt(1)
	v_pk_fma_f32 v[38:39], v[154:155], v[54:55], v[38:39]
	v_pk_fma_f32 v[48:49], v[156:157], v[56:57], v[48:49]
	s_waitcnt vmcnt(0)
	v_pk_fma_f32 v[54:55], v[142:143], v[60:61], v[62:63]
	v_mul_f32_e32 v1, 0xbfb8aa3b, v38
	v_mul_f32_e32 v56, 0xbfb8aa3b, v39
	v_mul_f32_e32 v57, 0xbfb8aa3b, v48
	v_mul_f32_e32 v60, 0xbfb8aa3b, v49
	v_mul_f32_e32 v61, 0xbfb8aa3b, v54
	v_exp_f32_e32 v1, v1
	v_exp_f32_e32 v56, v56
	v_exp_f32_e32 v57, v57
	v_exp_f32_e32 v60, v60
	v_exp_f32_e32 v61, v61
	v_add_f32_e32 v1, 1.0, v1
	v_add_f32_e32 v63, 1.0, v56
	v_add_f32_e32 v64, 1.0, v57
	v_add_f32_e32 v65, 1.0, v60
	v_add_f32_e32 v66, 1.0, v61
	v_rcp_f32_e32 v56, v1
	v_rcp_f32_e32 v57, v63
	v_rcp_f32_e32 v60, v64
	v_rcp_f32_e32 v61, v65
	v_mul_f32_e32 v62, 0xbfb8aa3b, v55
	v_pk_mul_f32 v[38:39], v[38:39], v[56:57]
	v_exp_f32_e32 v62, v62
	v_pk_mul_f32 v[48:49], v[48:49], v[60:61]
	v_pk_mul_f32 v[38:39], v[42:43], v[38:39]
	v_pk_mul_f32 v[42:43], v[46:47], v[48:49]
	v_pk_fma_f32 v[46:47], v[136:137], v[72:73], v[148:149]
	v_cvt_pk_bf16_f32 v38, v38, v39
	v_cvt_pk_bf16_f32 v39, v42, v43
	v_lshlrev_b32_e32 v42, 16, v37
	v_and_b32_e32 v43, 0xffff0000, v37
	v_pk_fma_f32 v[46:47], v[140:141], v[70:71], v[46:47]
	v_add_f32_e32 v1, 1.0, v62
	v_pk_fma_f32 v[42:43], v[144:145], v[42:43], v[46:47]
	v_rcp_f32_e32 v63, v1
	v_mul_f32_e32 v46, 0xbfb8aa3b, v42
	v_exp_f32_e32 v46, v46
	v_mul_f32_e32 v47, 0xbfb8aa3b, v43
	v_exp_f32_e32 v47, v47
	v_rcp_f32_e32 v62, v66
	v_add_f32_e32 v1, 1.0, v46
	v_rcp_f32_e32 v46, v1
	v_add_f32_e32 v1, 1.0, v47
	v_rcp_f32_e32 v47, v1
	v_pk_mul_f32 v[48:49], v[54:55], v[62:63]
	s_nop 0
	v_pk_mul_f32 v[44:45], v[44:45], v[48:49]
	v_pk_mul_f32 v[42:43], v[42:43], v[46:47]
	v_mov_b32_dpp v1, v34 row_ror:1 row_mask:0xf bank_mask:0xf
	v_pk_mul_f32 v[42:43], v[40:41], v[42:43]
	v_cvt_pk_bf16_f32 v40, v44, v45
	v_cvt_pk_bf16_f32 v41, v42, v43
	global_store_dwordx4 v[58:59], v[38:41], off offset:256
	v_mov_b32_dpp v1, v22 row_shr:1 row_mask:0xf bank_mask:0xf
	s_nop 0
	s_nop 0
	s_nop 0
	v_mov_b32_dpp v43, v35 row_ror:1 row_mask:0xf bank_mask:0xf
	v_mov_b32_dpp v39, v34 row_ror:2 row_mask:0xf bank_mask:0xf
	v_mov_b32_dpp v44, v35 row_ror:2 row_mask:0xf bank_mask:0xf
	v_lshlrev_b32_e32 v34, 16, v1
	v_mov_b32_dpp v39, v22 row_shr:2 row_mask:0xf bank_mask:0xf
	v_lshlrev_b32_e32 v38, 16, v39
	v_and_b32_e32 v39, 0xffff0000, v39
	v_and_b32_e32 v35, 0xffff0000, v1
	v_pk_fma_f32 v[38:39], v[150:151], v[38:39], v[158:159]
	v_lshlrev_b32_e32 v40, 16, v22
	v_and_b32_e32 v41, 0xffff0000, v22
	v_pk_fma_f32 v[34:35], v[162:163], v[34:35], v[38:39]
	v_mov_b32_dpp v43, v23 row_shr:1 row_mask:0xf bank_mask:0xf
	v_pk_fma_f32 v[34:35], v[154:155], v[40:41], v[34:35]
	v_mov_b32_dpp v44, v23 row_shr:2 row_mask:0xf bank_mask:0xf
	v_mul_f32_e32 v1, 0xbfb8aa3b, v34
	v_exp_f32_e32 v1, v1
	v_mul_f32_e32 v38, 0xbfb8aa3b, v35
	v_exp_f32_e32 v39, v38
	v_lshlrev_b32_e32 v40, 16, v43
	v_lshlrev_b32_e32 v42, 16, v44
	v_and_b32_e32 v41, 0xffff0000, v43
	v_and_b32_e32 v43, 0xffff0000, v44
	v_pk_fma_f32 v[42:43], v[152:153], v[42:43], v[160:161]
	v_lshlrev_b32_e32 v44, 16, v23
	v_and_b32_e32 v45, 0xffff0000, v23
	v_pk_fma_f32 v[40:41], v[164:165], v[40:41], v[42:43]
	v_add_f32_e32 v1, 1.0, v1
	v_pk_fma_f32 v[40:41], v[156:157], v[44:45], v[40:41]
	v_rcp_f32_e32 v38, v1
	v_add_f32_e32 v1, 1.0, v39
	v_mul_f32_e32 v39, 0xbfb8aa3b, v40
	v_exp_f32_e32 v42, v39
	v_mul_f32_e32 v39, 0xbfb8aa3b, v41
	v_exp_f32_e32 v43, v39
	v_rcp_f32_e32 v39, v1
	v_add_f32_e32 v1, 1.0, v42
	v_rcp_f32_e32 v42, v1
	v_add_f32_e32 v1, 1.0, v43
	v_rcp_f32_e32 v43, v1
	v_pk_mul_f32 v[34:35], v[34:35], v[38:39]
	s_nop 0
	v_pk_mul_f32 v[30:31], v[30:31], v[34:35]
	v_pk_mul_f32 v[34:35], v[40:41], v[42:43]
	v_mov_b32_dpp v1, v36 row_ror:1 row_mask:0xf bank_mask:0xf
	v_pk_mul_f32 v[32:33], v[32:33], v[34:35]
	s_nop 0
	v_mov_b32_dpp v1, v24 row_shr:1 row_mask:0xf bank_mask:0xf
	v_cvt_pk_bf16_f32 v30, v30, v31
	v_mov_b32_dpp v35, v36 row_ror:2 row_mask:0xf bank_mask:0xf
	v_cvt_pk_bf16_f32 v31, v32, v33
	s_nop 0
	v_mov_b32_dpp v35, v24 row_shr:2 row_mask:0xf bank_mask:0xf
	v_lshlrev_b32_e32 v34, 16, v35
	v_and_b32_e32 v35, 0xffff0000, v35
	s_nop 0
	v_lshlrev_b32_e32 v32, 16, v1
	v_and_b32_e32 v33, 0xffff0000, v1
	v_pk_fma_f32 v[34:35], v[134:135], v[34:35], v[146:147]
	v_mov_b32_dpp v39, v37 row_ror:1 row_mask:0xf bank_mask:0xf
	v_mov_b32_dpp v40, v37 row_ror:2 row_mask:0xf bank_mask:0xf
	v_lshlrev_b32_e32 v36, 16, v24
	v_and_b32_e32 v37, 0xffff0000, v24
	v_pk_fma_f32 v[32:33], v[138:139], v[32:33], v[34:35]
	v_mov_b32_dpp v39, v25 row_shr:1 row_mask:0xf bank_mask:0xf
	v_pk_fma_f32 v[32:33], v[142:143], v[36:37], v[32:33]
	v_mov_b32_dpp v40, v25 row_shr:2 row_mask:0xf bank_mask:0xf
	v_mul_f32_e32 v1, 0xbfb8aa3b, v32
	v_exp_f32_e32 v1, v1
	v_mul_f32_e32 v34, 0xbfb8aa3b, v33
	v_exp_f32_e32 v35, v34
	v_lshlrev_b32_e32 v36, 16, v39
	v_lshlrev_b32_e32 v38, 16, v40
	v_and_b32_e32 v37, 0xffff0000, v39
	v_and_b32_e32 v39, 0xffff0000, v40
	v_pk_fma_f32 v[38:39], v[136:137], v[38:39], v[148:149]
	v_lshlrev_b32_e32 v40, 16, v25
	v_and_b32_e32 v41, 0xffff0000, v25
	v_pk_fma_f32 v[36:37], v[140:141], v[36:37], v[38:39]
	v_add_f32_e32 v1, 1.0, v1
	v_pk_fma_f32 v[36:37], v[144:145], v[40:41], v[36:37]
	v_rcp_f32_e32 v34, v1
	v_add_f32_e32 v1, 1.0, v35
	v_mul_f32_e32 v35, 0xbfb8aa3b, v36
	v_exp_f32_e32 v38, v35
	v_mul_f32_e32 v35, 0xbfb8aa3b, v37
	v_exp_f32_e32 v39, v35
	v_rcp_f32_e32 v35, v1
	v_add_f32_e32 v1, 1.0, v38
	v_rcp_f32_e32 v38, v1
	v_add_f32_e32 v1, 1.0, v39
	v_rcp_f32_e32 v39, v1
	v_pk_mul_f32 v[32:33], v[32:33], v[34:35]
	s_nop 0
	v_pk_mul_f32 v[26:27], v[26:27], v[32:33]
	v_pk_mul_f32 v[32:33], v[36:37], v[38:39]
	v_mov_b32_dpp v1, v22 row_ror:1 row_mask:0xf bank_mask:0xf
	v_pk_mul_f32 v[28:29], v[28:29], v[32:33]
	v_cvt_pk_bf16_f32 v32, v26, v27
	s_nop 0
	v_cvt_pk_bf16_f32 v33, v28, v29
	global_store_dwordx4 v[52:53], v[30:33], off offset:256
	v_mov_b32_dpp v27, v22 row_ror:2 row_mask:0xf bank_mask:0xf
	v_mov_b32_dpp v1, v14 row_shr:1 row_mask:0xf bank_mask:0xf
	s_nop 0
	v_mov_b32_dpp v27, v14 row_shr:2 row_mask:0xf bank_mask:0xf
	s_nop 0
	v_lshlrev_b32_e32 v26, 16, v27
	v_and_b32_e32 v27, 0xffff0000, v27
	v_mov_b32_dpp v31, v23 row_ror:1 row_mask:0xf bank_mask:0xf
	v_mov_b32_dpp v32, v23 row_ror:2 row_mask:0xf bank_mask:0xf
	v_lshlrev_b32_e32 v22, 16, v1
	v_and_b32_e32 v23, 0xffff0000, v1
	v_pk_fma_f32 v[26:27], v[150:151], v[26:27], v[158:159]
	v_lshlrev_b32_e32 v28, 16, v14
	v_and_b32_e32 v29, 0xffff0000, v14
	v_pk_fma_f32 v[22:23], v[162:163], v[22:23], v[26:27]
	v_mov_b32_dpp v31, v15 row_shr:1 row_mask:0xf bank_mask:0xf
	v_pk_fma_f32 v[22:23], v[154:155], v[28:29], v[22:23]
	v_mov_b32_dpp v32, v15 row_shr:2 row_mask:0xf bank_mask:0xf
	v_mul_f32_e32 v1, 0xbfb8aa3b, v22
	v_exp_f32_e32 v1, v1
	v_mul_f32_e32 v26, 0xbfb8aa3b, v23
	v_exp_f32_e32 v27, v26
	v_lshlrev_b32_e32 v28, 16, v31
	v_lshlrev_b32_e32 v30, 16, v32
	v_and_b32_e32 v29, 0xffff0000, v31
	v_and_b32_e32 v31, 0xffff0000, v32
	v_pk_fma_f32 v[30:31], v[152:153], v[30:31], v[160:161]
	v_lshlrev_b32_e32 v32, 16, v15
	v_and_b32_e32 v33, 0xffff0000, v15
	v_pk_fma_f32 v[28:29], v[164:165], v[28:29], v[30:31]
	v_add_f32_e32 v1, 1.0, v1
	v_pk_fma_f32 v[28:29], v[156:157], v[32:33], v[28:29]
	v_rcp_f32_e32 v26, v1
	v_add_f32_e32 v1, 1.0, v27
	v_mul_f32_e32 v27, 0xbfb8aa3b, v28
	v_exp_f32_e32 v30, v27
	v_mul_f32_e32 v27, 0xbfb8aa3b, v29
	v_exp_f32_e32 v31, v27
	v_rcp_f32_e32 v27, v1
	v_add_f32_e32 v1, 1.0, v30
	v_rcp_f32_e32 v30, v1
	v_add_f32_e32 v1, 1.0, v31
	v_rcp_f32_e32 v31, v1
	v_pk_mul_f32 v[22:23], v[22:23], v[26:27]
	s_nop 0
	v_pk_mul_f32 v[18:19], v[18:19], v[22:23]
	v_pk_mul_f32 v[22:23], v[28:29], v[30:31]
	v_mov_b32_dpp v1, v24 row_ror:1 row_mask:0xf bank_mask:0xf
	v_pk_mul_f32 v[20:21], v[20:21], v[22:23]
	s_nop 0
	v_mov_b32_dpp v1, v16 row_shr:1 row_mask:0xf bank_mask:0xf
	v_cvt_pk_bf16_f32 v18, v18, v19
	v_mov_b32_dpp v23, v24 row_ror:2 row_mask:0xf bank_mask:0xf
	v_cvt_pk_bf16_f32 v19, v20, v21
	s_nop 0
	v_mov_b32_dpp v23, v16 row_shr:2 row_mask:0xf bank_mask:0xf
	v_lshlrev_b32_e32 v22, 16, v23
	v_and_b32_e32 v23, 0xffff0000, v23
	s_nop 0
	v_lshlrev_b32_e32 v20, 16, v1
	v_and_b32_e32 v21, 0xffff0000, v1
	v_pk_fma_f32 v[22:23], v[134:135], v[22:23], v[146:147]
	v_mov_b32_dpp v27, v25 row_ror:1 row_mask:0xf bank_mask:0xf
	v_mov_b32_dpp v28, v25 row_ror:2 row_mask:0xf bank_mask:0xf
	v_lshlrev_b32_e32 v24, 16, v16
	v_and_b32_e32 v25, 0xffff0000, v16
	v_pk_fma_f32 v[20:21], v[138:139], v[20:21], v[22:23]
	v_mov_b32_dpp v27, v17 row_shr:1 row_mask:0xf bank_mask:0xf
	v_pk_fma_f32 v[20:21], v[142:143], v[24:25], v[20:21]
	v_mov_b32_dpp v28, v17 row_shr:2 row_mask:0xf bank_mask:0xf
	v_mul_f32_e32 v1, 0xbfb8aa3b, v20
	v_exp_f32_e32 v1, v1
	v_mul_f32_e32 v22, 0xbfb8aa3b, v21
	v_exp_f32_e32 v23, v22
	v_lshlrev_b32_e32 v24, 16, v27
	v_lshlrev_b32_e32 v26, 16, v28
	v_and_b32_e32 v25, 0xffff0000, v27
	v_and_b32_e32 v27, 0xffff0000, v28
	v_pk_fma_f32 v[26:27], v[136:137], v[26:27], v[148:149]
	v_lshlrev_b32_e32 v28, 16, v17
	v_and_b32_e32 v29, 0xffff0000, v17
	v_pk_fma_f32 v[24:25], v[140:141], v[24:25], v[26:27]
	v_add_f32_e32 v1, 1.0, v1
	v_pk_fma_f32 v[24:25], v[144:145], v[28:29], v[24:25]
	v_rcp_f32_e32 v22, v1
	v_add_f32_e32 v1, 1.0, v23
	v_mul_f32_e32 v23, 0xbfb8aa3b, v24
	v_exp_f32_e32 v26, v23
	v_mul_f32_e32 v23, 0xbfb8aa3b, v25
	v_exp_f32_e32 v27, v23
	v_rcp_f32_e32 v23, v1
	v_add_f32_e32 v1, 1.0, v26
	v_rcp_f32_e32 v26, v1
	v_add_f32_e32 v1, 1.0, v27
	v_rcp_f32_e32 v27, v1
	v_pk_mul_f32 v[20:21], v[20:21], v[22:23]
	s_nop 0
	v_pk_mul_f32 v[10:11], v[10:11], v[20:21]
	v_pk_mul_f32 v[20:21], v[24:25], v[26:27]
	v_mov_b32_dpp v170, v16 row_ror:2 row_mask:0xf bank_mask:0xf
	v_pk_mul_f32 v[12:13], v[12:13], v[20:21]
	v_mov_b32_dpp v1, v17 row_ror:1 row_mask:0xf bank_mask:0xf
	v_mov_b32_dpp v167, v17 row_ror:2 row_mask:0xf bank_mask:0xf
	v_cvt_pk_bf16_f32 v20, v10, v11
	v_cvt_pk_bf16_f32 v21, v12, v13
	v_mov_b32_dpp v173, v130 row_shr:1 row_mask:0xf bank_mask:0xf
	v_mov_b32_dpp v174, v130 row_shr:2 row_mask:0xf bank_mask:0xf
	v_mov_b32_dpp v171, v131 row_shr:1 row_mask:0xf bank_mask:0xf
	v_mov_b32_dpp v172, v131 row_shr:2 row_mask:0xf bank_mask:0xf
	v_mov_b32_dpp v166, v132 row_shr:1 row_mask:0xf bank_mask:0xf
	v_mov_b32_dpp v170, v132 row_shr:2 row_mask:0xf bank_mask:0xf
	v_mov_b32_dpp v1, v133 row_shr:1 row_mask:0xf bank_mask:0xf
	v_mov_b32_dpp v167, v133 row_shr:2 row_mask:0xf bank_mask:0xf
	global_store_dwordx4 v[50:51], v[18:21], off offset:256
	s_branch .LBB0_1804
